# P1 pair block on the 8-phase ping-pong k-loop (two wave groups one barrier apart, 16-KB half tiles by LDS-DMA, v_mfma_f32_16x16x32_bf16)
# baseline (speedup 1.0000x reference)
; #define MFMA32(a, b, c) __builtin_amdgcn_mfma_f32_32x32x16_bf16((a), (b), (c), 0, 0, 0)
; template <bool SWAP, class Epi>
; DI void gemm_tile(const u16* __restrict__ A, int lda, const u16* __restrict__ Bw, int ldb, int K, char* lds, Epi epi) {
;     ...
;   const int lrow = tid >> 3, lkc = tid & 7;
;   u32x4 ra0[4], rb0[2], ra1[4], rb1[2];
;   const u16* ap = A + (size_t)lrow * lda + lkc * 8;
;   const u16* bp = Bw + (size_t)lrow * ldb + lkc * 8;
;   const int nk = K >> 6;
;   auto gload = [&](int kt, u32x4* ra, u32x4* rb) {
; #pragma unroll
;     for (int j = 0; j < 4; ++j) ra[j] = *(const u32x4*)(ap + (size_t)(64 * j) * lda + kt * 64);
; #pragma unroll
;     for (int j = 0; j < 2; ++j) rb[j] = *(const u32x4*)(bp + (size_t)(64 * j) * ldb + kt * 64);
;   };
;   auto lstore = [&](int st, const u32x4* ra, const u32x4* rb) {
;     char* base = lds + st * GEMM_STAGE;
; #pragma unroll
;     for (int j = 0; j < 4; ++j) *(u32x4*)(base + ((lrow + 64 * j) * 72 + lkc * 8) * 2) = ra[j];
; #pragma unroll
;     for (int j = 0; j < 2; ++j) *(u32x4*)(base + 36864 + ((lrow + 64 * j) * 72 + lkc * 8) * 2) = rb[j];
;   };
;   auto compute = [&](int st) {
;     const char* as = lds + st * GEMM_STAGE;
;     const char* bs = as + 36864;
; #pragma unroll
;     for (int ks = 0; ks < 4; ++ks) {
;       bf16x8 af[2], bfr[2];
; #pragma unroll
;       for (int mi = 0; mi < 2; ++mi) af[mi] = *(const bf16x8*)(as + ((wm * 64 + mi * 32 + r) * 72 + ks * 16 + 8 * h) * 2);
; #pragma unroll
;       for (int ni = 0; ni < 2; ++ni) bfr[ni] = *(const bf16x8*)(bs + ((wn * 64 + ni * 32 + r) * 72 + ks * 16 + 8 * h) * 2);
; #pragma unroll
;       for (int mi = 0; mi < 2; ++mi)
; #pragma unroll
;         for (int ni = 0; ni < 2; ++ni) {
;           if (SWAP) acc[mi][ni] = MFMA32(bfr[ni], af[mi], acc[mi][ni]);
;           else acc[mi][ni] = MFMA32(af[mi], bfr[ni], acc[mi][ni]);
;         }
;     }
;   };
;   gload(0, ra0, rb0);
;   lstore(0, ra0, rb0);
;   gload(1, ra1, rb1);
;   __syncthreads();
;   for (int kt = 0; kt < nk; kt += 2) {
;     if (kt + 2 < nk) gload(kt + 2, ra0, rb0);
;     compute(0);
;     lstore(1, ra1, rb1);
;     __syncthreads();
;     if (kt + 3 < nk) gload(kt + 3, ra1, rb1);
;     compute(1);
;     if (kt + 2 < nk) lstore(0, ra0, rb0);
.Lpp_body:
	s_waitcnt lgkmcnt(0)
	s_barrier
	s_lshl_b32 s1, s0, 1
	s_cmp_gt_u32 s0, 1
	s_cselect_b32 s2, 4, 0
	s_add_i32 s2, s1, s2
	v_readlane_b32 s4, v241, 26
	v_readlane_b32 s5, v241, 27
	v_readlane_b32 s8, v241, 24
	v_readlane_b32 s9, v241, 25
	v_lshrrev_b32_e32 v0, 6, v152
	v_and_b32_e32 v1, 63, v152
	s_lshl_b32 s0, s26, 19
	s_add_u32 s4, s4, s0
	s_addc_u32 s5, s5, 0
	s_lshl_b32 s0, s2, 18
	s_add_u32 s6, s18, s0
	s_addc_u32 s7, s19, 0
	v_readfirstlane_b32 s3, v0
	s_lshl_b32 s0, s3, 15
	s_add_u32 s68, s4, s0
	s_addc_u32 s69, s5, 0
	s_add_u32 s70, s68, 0x3c00
	s_addc_u32 s71, s69, 0
	s_add_u32 s72, s68, 0x40000
	s_addc_u32 s73, s69, 0
	s_add_u32 s74, s70, 0x40000
	s_addc_u32 s75, s71, 0
	s_add_u32 s76, s6, s0
	s_addc_u32 s77, s7, 0
	s_add_u32 s78, s76, 0x3c00
	s_addc_u32 s79, s77, 0
	s_add_u32 s80, s76, 0x40000
	s_addc_u32 s81, s77, 0
	s_add_u32 s82, s78, 0x40000
	s_addc_u32 s83, s79, 0
	s_lshl_b32 s40, s3, 11
	v_lshrrev_b32_e32 v2, 4, v1
	v_and_b32_e32 v0, 7, v1
	v_xor_b32_e32 v2, v2, v0
	v_lshlrev_b32_e32 v2, 4, v2
	v_lshrrev_b32_e32 v0, 3, v1
	v_lshlrev_b32_e32 v0, 11, v0
	v_add_u32_e32 v208, v2, v0
	v_xor_b32_e32 v209, 64, v208
	v_and_b32_e32 v0, 15, v1
	v_lshrrev_b32_e32 v2, 1, v0
	v_lshrrev_b32_e32 v1, 4, v1
	v_xor_b32_e32 v2, v2, v1
	v_lshlrev_b32_e32 v0, 7, v0
	s_lshr_b32 s0, s3, 2
	s_and_b32 s1, s3, 3
	s_lshl_b32 s10, s0, 13
	s_lshl_b32 s11, s1, 12
	s_add_i32 s11, s11, 0x10000
	v_xor_b32_e32 v212, 0, v2
	v_lshl_add_u32 v212, v212, 4, v0
	v_add_u32_e32 v210, s10, v212
	v_add_u32_e32 v212, s11, v212
	v_xor_b32_e32 v213, 4, v2
	v_lshl_add_u32 v213, v213, 4, v0
	v_add_u32_e32 v211, s10, v213
	v_add_u32_e32 v213, s11, v213
	s_lshl_b32 s12, s26, 8
	s_lshl_b32 s0, s0, 6
	s_add_i32 s12, s12, s0
	v_lshrrev_b32_e32 v0, 7, v0
	v_add_u32_e32 v0, s12, v0
	v_mul_u32_u24_e32 v0, 0x2a00, v0
	s_lshl_b32 s12, s2, 8
	s_lshl_b32 s1, s1, 6
	s_add_i32 s12, s12, s1
	v_lshlrev_b32_e32 v1, 3, v1
	v_add3_u32 v214, v0, v1, s12
	s_add_i32 m0, s40, 0x10000
	s_nop 0
	global_load_lds_dwordx4 v208, s[76:77]
	global_load_lds_dwordx4 v209, s[78:79] offset:1024
	s_add_i32 m0, s40, 0x0
	s_nop 0
	global_load_lds_dwordx4 v208, s[68:69]
	global_load_lds_dwordx4 v209, s[70:71] offset:1024
	s_add_i32 m0, s40, 0x14000
	s_nop 0
	global_load_lds_dwordx4 v208, s[80:81]
	global_load_lds_dwordx4 v209, s[82:83] offset:1024
	s_add_i32 m0, s40, 0x4000
	s_nop 0
	global_load_lds_dwordx4 v208, s[72:73]
	global_load_lds_dwordx4 v209, s[74:75] offset:1024
	v_add_u32_e32 v208, 0x80, v208
	v_add_u32_e32 v209, 0x80, v209
	s_cmp_lt_u32 s3, 4
	s_cbranch_scc1 .Lpp_g0a
	s_barrier
.Lpp_g0a:
	s_waitcnt vmcnt(4)
	s_barrier
	s_add_i32 m0, s40, 0x18000
	s_nop 0
	global_load_lds_dwordx4 v208, s[76:77]
	global_load_lds_dwordx4 v209, s[78:79] offset:1024
	s_add_i32 m0, s40, 0x8000
	s_nop 0
	global_load_lds_dwordx4 v208, s[68:69]
	global_load_lds_dwordx4 v209, s[70:71] offset:1024
	s_add_i32 m0, s40, 0x1c000
	s_nop 0
	global_load_lds_dwordx4 v208, s[80:81]
	global_load_lds_dwordx4 v209, s[82:83] offset:1024
	s_waitcnt vmcnt(6)
	s_barrier
	ds_read_b128 v[172:175], v212 offset:0
	ds_read_b128 v[176:179], v213 offset:0
	ds_read_b128 v[180:183], v212 offset:2048
	ds_read_b128 v[184:187], v213 offset:2048
	ds_read_b128 v[132:135], v210 offset:0
	ds_read_b128 v[136:139], v211 offset:0
	ds_read_b128 v[140:143], v210 offset:2048
	ds_read_b128 v[144:147], v211 offset:2048
	ds_read_b128 v[148:151], v210 offset:4096
	ds_read_b128 v[158:161], v211 offset:4096
	ds_read_b128 v[162:165], v210 offset:6144
	ds_read_b128 v[168:171], v211 offset:6144
	s_add_i32 m0, s40, 0xc000
	s_nop 0
	global_load_lds_dwordx4 v208, s[72:73]
	global_load_lds_dwordx4 v209, s[74:75] offset:1024
	s_waitcnt lgkmcnt(8)
	s_barrier
	s_waitcnt lgkmcnt(0)
	s_setprio 1
	v_mfma_f32_16x16x32_bf16 v[4:7], v[172:175], v[132:135], 0
	v_mfma_f32_16x16x32_bf16 v[8:11], v[180:183], v[132:135], 0
	v_mfma_f32_16x16x32_bf16 v[12:15], v[172:175], v[140:143], 0
	v_mfma_f32_16x16x32_bf16 v[16:19], v[180:183], v[140:143], 0
	v_mfma_f32_16x16x32_bf16 v[20:23], v[172:175], v[148:151], 0
	v_mfma_f32_16x16x32_bf16 v[24:27], v[180:183], v[148:151], 0
	v_mfma_f32_16x16x32_bf16 v[28:31], v[172:175], v[162:165], 0
	v_mfma_f32_16x16x32_bf16 v[32:35], v[180:183], v[162:165], 0
	v_mfma_f32_16x16x32_bf16 v[4:7], v[176:179], v[136:139], v[4:7]
	v_mfma_f32_16x16x32_bf16 v[8:11], v[184:187], v[136:139], v[8:11]
	v_mfma_f32_16x16x32_bf16 v[12:15], v[176:179], v[144:147], v[12:15]
	v_mfma_f32_16x16x32_bf16 v[16:19], v[184:187], v[144:147], v[16:19]
	v_mfma_f32_16x16x32_bf16 v[20:23], v[176:179], v[158:161], v[20:23]
	v_mfma_f32_16x16x32_bf16 v[24:27], v[184:187], v[158:161], v[24:27]
	v_mfma_f32_16x16x32_bf16 v[28:31], v[176:179], v[168:171], v[28:31]
	v_mfma_f32_16x16x32_bf16 v[32:35], v[184:187], v[168:171], v[32:35]
	s_setprio 0
	s_barrier
	ds_read_b128 v[216:219], v212 offset:16384
	ds_read_b128 v[220:223], v213 offset:16384
	ds_read_b128 v[224:227], v212 offset:18432
	ds_read_b128 v[228:231], v213 offset:18432
	v_add_u32_e32 v208, 0x80, v208
	v_add_u32_e32 v209, 0x80, v209
	s_add_i32 m0, s40, 0x10000
	s_nop 0
	global_load_lds_dwordx4 v208, s[76:77]
	global_load_lds_dwordx4 v209, s[78:79] offset:1024
	s_barrier
; #define MFMA32(a, b, c) __builtin_amdgcn_mfma_f32_32x32x16_bf16((a), (b), (c), 0, 0, 0)
; template <bool SWAP, class Epi>
; DI void gemm_tile(const u16* __restrict__ A, int lda, const u16* __restrict__ Bw, int ldb, int K, char* lds, Epi epi) {
;     ...
;   auto compute = [&](int st) {
;     const char* as = lds + st * GEMM_STAGE;
;     const char* bs = as + 36864;
; #pragma unroll
;     for (int ks = 0; ks < 4; ++ks) {
;       bf16x8 af[2], bfr[2];
; #pragma unroll
;       for (int mi = 0; mi < 2; ++mi) af[mi] = *(const bf16x8*)(as + ((wm * 64 + mi * 32 + r) * 72 + ks * 16 + 8 * h) * 2);
; #pragma unroll
;       for (int ni = 0; ni < 2; ++ni) bfr[ni] = *(const bf16x8*)(bs + ((wn * 64 + ni * 32 + r) * 72 + ks * 16 + 8 * h) * 2);
; #pragma unroll
;       for (int mi = 0; mi < 2; ++mi)
; #pragma unroll
;         for (int ni = 0; ni < 2; ++ni) {
;           if (SWAP) acc[mi][ni] = MFMA32(bfr[ni], af[mi], acc[mi][ni]);
;           else acc[mi][ni] = MFMA32(af[mi], bfr[ni], acc[mi][ni]);
;         }
;     }
;   };
;   gload(0, ra0, rb0);
;   lstore(0, ra0, rb0);
;   gload(1, ra1, rb1);
;   __syncthreads();
;   for (int kt = 0; kt < nk; kt += 2) {
;     if (kt + 2 < nk) gload(kt + 2, ra0, rb0);
;     compute(0);
;     lstore(1, ra1, rb1);
;     __syncthreads();
;     if (kt + 3 < nk) gload(kt + 3, ra1, rb1);
;     compute(1);
;     if (kt + 2 < nk) lstore(0, ra0, rb0);
;     __syncthreads();
	s_waitcnt lgkmcnt(0)
	s_setprio 1
	v_mfma_f32_16x16x32_bf16 v[36:39], v[216:219], v[132:135], 0
	v_mfma_f32_16x16x32_bf16 v[40:43], v[224:227], v[132:135], 0
	v_mfma_f32_16x16x32_bf16 v[44:47], v[216:219], v[140:143], 0
	v_mfma_f32_16x16x32_bf16 v[48:51], v[224:227], v[140:143], 0
	v_mfma_f32_16x16x32_bf16 v[52:55], v[216:219], v[148:151], 0
	v_mfma_f32_16x16x32_bf16 v[56:59], v[224:227], v[148:151], 0
	v_mfma_f32_16x16x32_bf16 v[60:63], v[216:219], v[162:165], 0
	v_mfma_f32_16x16x32_bf16 v[64:67], v[224:227], v[162:165], 0
	v_mfma_f32_16x16x32_bf16 v[36:39], v[220:223], v[136:139], v[36:39]
	v_mfma_f32_16x16x32_bf16 v[40:43], v[228:231], v[136:139], v[40:43]
	v_mfma_f32_16x16x32_bf16 v[44:47], v[220:223], v[144:147], v[44:47]
	v_mfma_f32_16x16x32_bf16 v[48:51], v[228:231], v[144:147], v[48:51]
	v_mfma_f32_16x16x32_bf16 v[52:55], v[220:223], v[158:161], v[52:55]
	v_mfma_f32_16x16x32_bf16 v[56:59], v[228:231], v[158:161], v[56:59]
	v_mfma_f32_16x16x32_bf16 v[60:63], v[220:223], v[168:171], v[60:63]
	v_mfma_f32_16x16x32_bf16 v[64:67], v[228:231], v[168:171], v[64:67]
	s_setprio 0
	s_barrier
	ds_read_b128 v[132:135], v210 offset:16384
	ds_read_b128 v[136:139], v211 offset:16384
	ds_read_b128 v[140:143], v210 offset:18432
	ds_read_b128 v[144:147], v211 offset:18432
	ds_read_b128 v[148:151], v210 offset:20480
	ds_read_b128 v[158:161], v211 offset:20480
	ds_read_b128 v[162:165], v210 offset:22528
	ds_read_b128 v[168:171], v211 offset:22528
	s_add_i32 m0, s40, 0x0
	s_nop 0
	global_load_lds_dwordx4 v208, s[68:69]
	global_load_lds_dwordx4 v209, s[70:71] offset:1024
	s_barrier
	s_waitcnt lgkmcnt(0)
	s_setprio 1
	v_mfma_f32_16x16x32_bf16 v[68:71], v[172:175], v[132:135], 0
	v_mfma_f32_16x16x32_bf16 v[72:75], v[180:183], v[132:135], 0
	v_mfma_f32_16x16x32_bf16 v[76:79], v[172:175], v[140:143], 0
	v_mfma_f32_16x16x32_bf16 v[80:83], v[180:183], v[140:143], 0
	v_mfma_f32_16x16x32_bf16 v[84:87], v[172:175], v[148:151], 0
	v_mfma_f32_16x16x32_bf16 v[88:91], v[180:183], v[148:151], 0
	v_mfma_f32_16x16x32_bf16 v[92:95], v[172:175], v[162:165], 0
	v_mfma_f32_16x16x32_bf16 v[96:99], v[180:183], v[162:165], 0
	v_mfma_f32_16x16x32_bf16 v[68:71], v[176:179], v[136:139], v[68:71]
	v_mfma_f32_16x16x32_bf16 v[72:75], v[184:187], v[136:139], v[72:75]
	v_mfma_f32_16x16x32_bf16 v[76:79], v[176:179], v[144:147], v[76:79]
	v_mfma_f32_16x16x32_bf16 v[80:83], v[184:187], v[144:147], v[80:83]
	v_mfma_f32_16x16x32_bf16 v[84:87], v[176:179], v[158:161], v[84:87]
	v_mfma_f32_16x16x32_bf16 v[88:91], v[184:187], v[158:161], v[88:91]
	v_mfma_f32_16x16x32_bf16 v[92:95], v[176:179], v[168:171], v[92:95]
	v_mfma_f32_16x16x32_bf16 v[96:99], v[184:187], v[168:171], v[96:99]
	s_setprio 0
	s_barrier
	s_add_i32 m0, s40, 0x14000
	s_nop 0
	global_load_lds_dwordx4 v208, s[80:81]
	global_load_lds_dwordx4 v209, s[82:83] offset:1024
	s_waitcnt vmcnt(6)
	s_barrier
	s_setprio 1
	v_mfma_f32_16x16x32_bf16 v[100:103], v[216:219], v[132:135], 0
	v_mfma_f32_16x16x32_bf16 v[104:107], v[224:227], v[132:135], 0
	v_mfma_f32_16x16x32_bf16 v[108:111], v[216:219], v[140:143], 0
	v_mfma_f32_16x16x32_bf16 v[112:115], v[224:227], v[140:143], 0
	v_mfma_f32_16x16x32_bf16 v[116:119], v[216:219], v[148:151], 0
	v_mfma_f32_16x16x32_bf16 v[120:123], v[224:227], v[148:151], 0
	v_mfma_f32_16x16x32_bf16 v[124:127], v[216:219], v[162:165], 0
	v_mfma_f32_16x16x32_bf16 v[128:131], v[224:227], v[162:165], 0
	v_mfma_f32_16x16x32_bf16 v[100:103], v[220:223], v[136:139], v[100:103]
	v_mfma_f32_16x16x32_bf16 v[104:107], v[228:231], v[136:139], v[104:107]
	v_mfma_f32_16x16x32_bf16 v[108:111], v[220:223], v[144:147], v[108:111]
	v_mfma_f32_16x16x32_bf16 v[112:115], v[228:231], v[144:147], v[112:115]
	v_mfma_f32_16x16x32_bf16 v[116:119], v[220:223], v[158:161], v[116:119]
	v_mfma_f32_16x16x32_bf16 v[120:123], v[228:231], v[158:161], v[120:123]
	v_mfma_f32_16x16x32_bf16 v[124:127], v[220:223], v[168:171], v[124:127]
	v_mfma_f32_16x16x32_bf16 v[128:131], v[228:231], v[168:171], v[128:131]
	s_setprio 0
	s_barrier
	ds_read_b128 v[172:175], v212 offset:32768
	ds_read_b128 v[176:179], v213 offset:32768
	ds_read_b128 v[180:183], v212 offset:34816
	ds_read_b128 v[184:187], v213 offset:34816
	ds_read_b128 v[132:135], v210 offset:32768
	ds_read_b128 v[136:139], v211 offset:32768
	ds_read_b128 v[140:143], v210 offset:34816
	ds_read_b128 v[144:147], v211 offset:34816
	ds_read_b128 v[148:151], v210 offset:36864
	ds_read_b128 v[158:161], v211 offset:36864
	ds_read_b128 v[162:165], v210 offset:38912
	ds_read_b128 v[168:171], v211 offset:38912
	s_add_i32 m0, s40, 0x4000
	s_nop 0
	global_load_lds_dwordx4 v208, s[72:73]
	global_load_lds_dwordx4 v209, s[74:75] offset:1024
	s_waitcnt lgkmcnt(8)
	s_barrier
	s_waitcnt lgkmcnt(0)
	s_setprio 1
	v_mfma_f32_16x16x32_bf16 v[4:7], v[172:175], v[132:135], v[4:7]
	v_mfma_f32_16x16x32_bf16 v[8:11], v[180:183], v[132:135], v[8:11]
	v_mfma_f32_16x16x32_bf16 v[12:15], v[172:175], v[140:143], v[12:15]
	v_mfma_f32_16x16x32_bf16 v[16:19], v[180:183], v[140:143], v[16:19]
	v_mfma_f32_16x16x32_bf16 v[20:23], v[172:175], v[148:151], v[20:23]
	v_mfma_f32_16x16x32_bf16 v[24:27], v[180:183], v[148:151], v[24:27]
	v_mfma_f32_16x16x32_bf16 v[28:31], v[172:175], v[162:165], v[28:31]
	v_mfma_f32_16x16x32_bf16 v[32:35], v[180:183], v[162:165], v[32:35]
	v_mfma_f32_16x16x32_bf16 v[4:7], v[176:179], v[136:139], v[4:7]
	v_mfma_f32_16x16x32_bf16 v[8:11], v[184:187], v[136:139], v[8:11]
	v_mfma_f32_16x16x32_bf16 v[12:15], v[176:179], v[144:147], v[12:15]
	v_mfma_f32_16x16x32_bf16 v[16:19], v[184:187], v[144:147], v[16:19]
	v_mfma_f32_16x16x32_bf16 v[20:23], v[176:179], v[158:161], v[20:23]
	v_mfma_f32_16x16x32_bf16 v[24:27], v[184:187], v[158:161], v[24:27]
	v_mfma_f32_16x16x32_bf16 v[28:31], v[176:179], v[168:171], v[28:31]
	v_mfma_f32_16x16x32_bf16 v[32:35], v[184:187], v[168:171], v[32:35]
	s_setprio 0
	s_barrier
; #define MFMA32(a, b, c) __builtin_amdgcn_mfma_f32_32x32x16_bf16((a), (b), (c), 0, 0, 0)
; template <bool SWAP, class Epi>
; DI void gemm_tile(const u16* __restrict__ A, int lda, const u16* __restrict__ Bw, int ldb, int K, char* lds, Epi epi) {
;     ...
;   auto compute = [&](int st) {
;     const char* as = lds + st * GEMM_STAGE;
;     const char* bs = as + 36864;
; #pragma unroll
;     for (int ks = 0; ks < 4; ++ks) {
;       bf16x8 af[2], bfr[2];
; #pragma unroll
;       for (int mi = 0; mi < 2; ++mi) af[mi] = *(const bf16x8*)(as + ((wm * 64 + mi * 32 + r) * 72 + ks * 16 + 8 * h) * 2);
; #pragma unroll
;       for (int ni = 0; ni < 2; ++ni) bfr[ni] = *(const bf16x8*)(bs + ((wn * 64 + ni * 32 + r) * 72 + ks * 16 + 8 * h) * 2);
; #pragma unroll
;       for (int mi = 0; mi < 2; ++mi)
; #pragma unroll
;         for (int ni = 0; ni < 2; ++ni) {
;           if (SWAP) acc[mi][ni] = MFMA32(bfr[ni], af[mi], acc[mi][ni]);
;           else acc[mi][ni] = MFMA32(af[mi], bfr[ni], acc[mi][ni]);
;         }
;     }
;   };
;   gload(0, ra0, rb0);
;   lstore(0, ra0, rb0);
;   gload(1, ra1, rb1);
;   __syncthreads();
;   for (int kt = 0; kt < nk; kt += 2) {
;     if (kt + 2 < nk) gload(kt + 2, ra0, rb0);
;     compute(0);
;     lstore(1, ra1, rb1);
;     __syncthreads();
;     if (kt + 3 < nk) gload(kt + 3, ra1, rb1);
;     compute(1);
;     if (kt + 2 < nk) lstore(0, ra0, rb0);
;     __syncthreads();
	ds_read_b128 v[216:219], v212 offset:49152
	ds_read_b128 v[220:223], v213 offset:49152
	ds_read_b128 v[224:227], v212 offset:51200
	ds_read_b128 v[228:231], v213 offset:51200
	v_add_u32_e32 v208, 0x80, v208
	v_add_u32_e32 v209, 0x80, v209
	s_add_i32 m0, s40, 0x18000
	s_nop 0
	global_load_lds_dwordx4 v208, s[76:77]
	global_load_lds_dwordx4 v209, s[78:79] offset:1024
	s_barrier
	s_waitcnt lgkmcnt(0)
	s_setprio 1
	v_mfma_f32_16x16x32_bf16 v[36:39], v[216:219], v[132:135], v[36:39]
	v_mfma_f32_16x16x32_bf16 v[40:43], v[224:227], v[132:135], v[40:43]
	v_mfma_f32_16x16x32_bf16 v[44:47], v[216:219], v[140:143], v[44:47]
	v_mfma_f32_16x16x32_bf16 v[48:51], v[224:227], v[140:143], v[48:51]
	v_mfma_f32_16x16x32_bf16 v[52:55], v[216:219], v[148:151], v[52:55]
	v_mfma_f32_16x16x32_bf16 v[56:59], v[224:227], v[148:151], v[56:59]
	v_mfma_f32_16x16x32_bf16 v[60:63], v[216:219], v[162:165], v[60:63]
	v_mfma_f32_16x16x32_bf16 v[64:67], v[224:227], v[162:165], v[64:67]
	v_mfma_f32_16x16x32_bf16 v[36:39], v[220:223], v[136:139], v[36:39]
	v_mfma_f32_16x16x32_bf16 v[40:43], v[228:231], v[136:139], v[40:43]
	v_mfma_f32_16x16x32_bf16 v[44:47], v[220:223], v[144:147], v[44:47]
	v_mfma_f32_16x16x32_bf16 v[48:51], v[228:231], v[144:147], v[48:51]
	v_mfma_f32_16x16x32_bf16 v[52:55], v[220:223], v[158:161], v[52:55]
	v_mfma_f32_16x16x32_bf16 v[56:59], v[228:231], v[158:161], v[56:59]
	v_mfma_f32_16x16x32_bf16 v[60:63], v[220:223], v[168:171], v[60:63]
	v_mfma_f32_16x16x32_bf16 v[64:67], v[228:231], v[168:171], v[64:67]
	s_setprio 0
	s_barrier
	ds_read_b128 v[132:135], v210 offset:49152
	ds_read_b128 v[136:139], v211 offset:49152
	ds_read_b128 v[140:143], v210 offset:51200
	ds_read_b128 v[144:147], v211 offset:51200
	ds_read_b128 v[148:151], v210 offset:53248
	ds_read_b128 v[158:161], v211 offset:53248
	ds_read_b128 v[162:165], v210 offset:55296
	ds_read_b128 v[168:171], v211 offset:55296
	s_add_i32 m0, s40, 0x8000
	s_nop 0
	global_load_lds_dwordx4 v208, s[68:69]
	global_load_lds_dwordx4 v209, s[70:71] offset:1024
	s_barrier
	s_waitcnt lgkmcnt(0)
	s_setprio 1
	v_mfma_f32_16x16x32_bf16 v[68:71], v[172:175], v[132:135], v[68:71]
	v_mfma_f32_16x16x32_bf16 v[72:75], v[180:183], v[132:135], v[72:75]
	v_mfma_f32_16x16x32_bf16 v[76:79], v[172:175], v[140:143], v[76:79]
	v_mfma_f32_16x16x32_bf16 v[80:83], v[180:183], v[140:143], v[80:83]
	v_mfma_f32_16x16x32_bf16 v[84:87], v[172:175], v[148:151], v[84:87]
	v_mfma_f32_16x16x32_bf16 v[88:91], v[180:183], v[148:151], v[88:91]
	v_mfma_f32_16x16x32_bf16 v[92:95], v[172:175], v[162:165], v[92:95]
	v_mfma_f32_16x16x32_bf16 v[96:99], v[180:183], v[162:165], v[96:99]
	v_mfma_f32_16x16x32_bf16 v[68:71], v[176:179], v[136:139], v[68:71]
	v_mfma_f32_16x16x32_bf16 v[72:75], v[184:187], v[136:139], v[72:75]
	v_mfma_f32_16x16x32_bf16 v[76:79], v[176:179], v[144:147], v[76:79]
	v_mfma_f32_16x16x32_bf16 v[80:83], v[184:187], v[144:147], v[80:83]
	v_mfma_f32_16x16x32_bf16 v[84:87], v[176:179], v[158:161], v[84:87]
	v_mfma_f32_16x16x32_bf16 v[88:91], v[184:187], v[158:161], v[88:91]
	v_mfma_f32_16x16x32_bf16 v[92:95], v[176:179], v[168:171], v[92:95]
	v_mfma_f32_16x16x32_bf16 v[96:99], v[184:187], v[168:171], v[96:99]
	s_setprio 0
	s_barrier
	s_add_i32 m0, s40, 0x1c000
	s_nop 0
	global_load_lds_dwordx4 v208, s[80:81]
	global_load_lds_dwordx4 v209, s[82:83] offset:1024
	s_waitcnt vmcnt(6)
	s_barrier
	s_setprio 1
	v_mfma_f32_16x16x32_bf16 v[100:103], v[216:219], v[132:135], v[100:103]
	v_mfma_f32_16x16x32_bf16 v[104:107], v[224:227], v[132:135], v[104:107]
	v_mfma_f32_16x16x32_bf16 v[108:111], v[216:219], v[140:143], v[108:111]
	v_mfma_f32_16x16x32_bf16 v[112:115], v[224:227], v[140:143], v[112:115]
	v_mfma_f32_16x16x32_bf16 v[116:119], v[216:219], v[148:151], v[116:119]
	v_mfma_f32_16x16x32_bf16 v[120:123], v[224:227], v[148:151], v[120:123]
	v_mfma_f32_16x16x32_bf16 v[124:127], v[216:219], v[162:165], v[124:127]
	v_mfma_f32_16x16x32_bf16 v[128:131], v[224:227], v[162:165], v[128:131]
	v_mfma_f32_16x16x32_bf16 v[100:103], v[220:223], v[136:139], v[100:103]
	v_mfma_f32_16x16x32_bf16 v[104:107], v[228:231], v[136:139], v[104:107]
	v_mfma_f32_16x16x32_bf16 v[108:111], v[220:223], v[144:147], v[108:111]
	v_mfma_f32_16x16x32_bf16 v[112:115], v[228:231], v[144:147], v[112:115]
	v_mfma_f32_16x16x32_bf16 v[116:119], v[220:223], v[158:161], v[116:119]
	v_mfma_f32_16x16x32_bf16 v[120:123], v[228:231], v[158:161], v[120:123]
	v_mfma_f32_16x16x32_bf16 v[124:127], v[220:223], v[168:171], v[124:127]
	v_mfma_f32_16x16x32_bf16 v[128:131], v[228:231], v[168:171], v[128:131]
	s_setprio 0
	s_barrier
	ds_read_b128 v[172:175], v212 offset:0
	ds_read_b128 v[176:179], v213 offset:0
	ds_read_b128 v[180:183], v212 offset:2048
	ds_read_b128 v[184:187], v213 offset:2048
	ds_read_b128 v[132:135], v210 offset:0
	ds_read_b128 v[136:139], v211 offset:0
	ds_read_b128 v[140:143], v210 offset:2048
	ds_read_b128 v[144:147], v211 offset:2048
	ds_read_b128 v[148:151], v210 offset:4096
	ds_read_b128 v[158:161], v211 offset:4096
	ds_read_b128 v[162:165], v210 offset:6144
	ds_read_b128 v[168:171], v211 offset:6144
	s_add_i32 m0, s40, 0xc000
	s_nop 0
	global_load_lds_dwordx4 v208, s[72:73]
	global_load_lds_dwordx4 v209, s[74:75] offset:1024
	s_waitcnt lgkmcnt(8)
	s_barrier
; #define MFMA32(a, b, c) __builtin_amdgcn_mfma_f32_32x32x16_bf16((a), (b), (c), 0, 0, 0)
; template <bool SWAP, class Epi>
; DI void gemm_tile(const u16* __restrict__ A, int lda, const u16* __restrict__ Bw, int ldb, int K, char* lds, Epi epi) {
;     ...
;   auto compute = [&](int st) {
;     const char* as = lds + st * GEMM_STAGE;
;     const char* bs = as + 36864;
; #pragma unroll
;     for (int ks = 0; ks < 4; ++ks) {
;       bf16x8 af[2], bfr[2];
; #pragma unroll
;       for (int mi = 0; mi < 2; ++mi) af[mi] = *(const bf16x8*)(as + ((wm * 64 + mi * 32 + r) * 72 + ks * 16 + 8 * h) * 2);
; #pragma unroll
;       for (int ni = 0; ni < 2; ++ni) bfr[ni] = *(const bf16x8*)(bs + ((wn * 64 + ni * 32 + r) * 72 + ks * 16 + 8 * h) * 2);
; #pragma unroll
;       for (int mi = 0; mi < 2; ++mi)
; #pragma unroll
;         for (int ni = 0; ni < 2; ++ni) {
;           if (SWAP) acc[mi][ni] = MFMA32(bfr[ni], af[mi], acc[mi][ni]);
;           else acc[mi][ni] = MFMA32(af[mi], bfr[ni], acc[mi][ni]);
;         }
;     }
;   };
;   gload(0, ra0, rb0);
;   lstore(0, ra0, rb0);
;   gload(1, ra1, rb1);
;   __syncthreads();
;   for (int kt = 0; kt < nk; kt += 2) {
;     if (kt + 2 < nk) gload(kt + 2, ra0, rb0);
;     compute(0);
;     lstore(1, ra1, rb1);
;     __syncthreads();
;     if (kt + 3 < nk) gload(kt + 3, ra1, rb1);
;     compute(1);
;     if (kt + 2 < nk) lstore(0, ra0, rb0);
;     __syncthreads();
	s_waitcnt lgkmcnt(0)
	s_setprio 1
	v_mfma_f32_16x16x32_bf16 v[4:7], v[172:175], v[132:135], v[4:7]
	v_mfma_f32_16x16x32_bf16 v[8:11], v[180:183], v[132:135], v[8:11]
	v_mfma_f32_16x16x32_bf16 v[12:15], v[172:175], v[140:143], v[12:15]
	v_mfma_f32_16x16x32_bf16 v[16:19], v[180:183], v[140:143], v[16:19]
	v_mfma_f32_16x16x32_bf16 v[20:23], v[172:175], v[148:151], v[20:23]
	v_mfma_f32_16x16x32_bf16 v[24:27], v[180:183], v[148:151], v[24:27]
	v_mfma_f32_16x16x32_bf16 v[28:31], v[172:175], v[162:165], v[28:31]
	v_mfma_f32_16x16x32_bf16 v[32:35], v[180:183], v[162:165], v[32:35]
	v_mfma_f32_16x16x32_bf16 v[4:7], v[176:179], v[136:139], v[4:7]
	v_mfma_f32_16x16x32_bf16 v[8:11], v[184:187], v[136:139], v[8:11]
	v_mfma_f32_16x16x32_bf16 v[12:15], v[176:179], v[144:147], v[12:15]
	v_mfma_f32_16x16x32_bf16 v[16:19], v[184:187], v[144:147], v[16:19]
	v_mfma_f32_16x16x32_bf16 v[20:23], v[176:179], v[158:161], v[20:23]
	v_mfma_f32_16x16x32_bf16 v[24:27], v[184:187], v[158:161], v[24:27]
	v_mfma_f32_16x16x32_bf16 v[28:31], v[176:179], v[168:171], v[28:31]
	v_mfma_f32_16x16x32_bf16 v[32:35], v[184:187], v[168:171], v[32:35]
	s_setprio 0
	s_barrier
	ds_read_b128 v[216:219], v212 offset:16384
	ds_read_b128 v[220:223], v213 offset:16384
	ds_read_b128 v[224:227], v212 offset:18432
	ds_read_b128 v[228:231], v213 offset:18432
	v_add_u32_e32 v208, 0x80, v208
	v_add_u32_e32 v209, 0x80, v209
	s_add_i32 m0, s40, 0x10000
	s_nop 0
	global_load_lds_dwordx4 v208, s[76:77]
	global_load_lds_dwordx4 v209, s[78:79] offset:1024
	s_barrier
	s_waitcnt lgkmcnt(0)
	s_setprio 1
	v_mfma_f32_16x16x32_bf16 v[36:39], v[216:219], v[132:135], v[36:39]
	v_mfma_f32_16x16x32_bf16 v[40:43], v[224:227], v[132:135], v[40:43]
	v_mfma_f32_16x16x32_bf16 v[44:47], v[216:219], v[140:143], v[44:47]
	v_mfma_f32_16x16x32_bf16 v[48:51], v[224:227], v[140:143], v[48:51]
	v_mfma_f32_16x16x32_bf16 v[52:55], v[216:219], v[148:151], v[52:55]
	v_mfma_f32_16x16x32_bf16 v[56:59], v[224:227], v[148:151], v[56:59]
	v_mfma_f32_16x16x32_bf16 v[60:63], v[216:219], v[162:165], v[60:63]
	v_mfma_f32_16x16x32_bf16 v[64:67], v[224:227], v[162:165], v[64:67]
	v_mfma_f32_16x16x32_bf16 v[36:39], v[220:223], v[136:139], v[36:39]
	v_mfma_f32_16x16x32_bf16 v[40:43], v[228:231], v[136:139], v[40:43]
	v_mfma_f32_16x16x32_bf16 v[44:47], v[220:223], v[144:147], v[44:47]
	v_mfma_f32_16x16x32_bf16 v[48:51], v[228:231], v[144:147], v[48:51]
	v_mfma_f32_16x16x32_bf16 v[52:55], v[220:223], v[158:161], v[52:55]
	v_mfma_f32_16x16x32_bf16 v[56:59], v[228:231], v[158:161], v[56:59]
	v_mfma_f32_16x16x32_bf16 v[60:63], v[220:223], v[168:171], v[60:63]
	v_mfma_f32_16x16x32_bf16 v[64:67], v[228:231], v[168:171], v[64:67]
	s_setprio 0
	s_barrier
	ds_read_b128 v[132:135], v210 offset:16384
	ds_read_b128 v[136:139], v211 offset:16384
	ds_read_b128 v[140:143], v210 offset:18432
	ds_read_b128 v[144:147], v211 offset:18432
	ds_read_b128 v[148:151], v210 offset:20480
	ds_read_b128 v[158:161], v211 offset:20480
	ds_read_b128 v[162:165], v210 offset:22528
	ds_read_b128 v[168:171], v211 offset:22528
	s_add_i32 m0, s40, 0x0
	s_nop 0
	global_load_lds_dwordx4 v208, s[68:69]
	global_load_lds_dwordx4 v209, s[70:71] offset:1024
	s_barrier
	s_waitcnt lgkmcnt(0)
	s_setprio 1
	v_mfma_f32_16x16x32_bf16 v[68:71], v[172:175], v[132:135], v[68:71]
	v_mfma_f32_16x16x32_bf16 v[72:75], v[180:183], v[132:135], v[72:75]
	v_mfma_f32_16x16x32_bf16 v[76:79], v[172:175], v[140:143], v[76:79]
	v_mfma_f32_16x16x32_bf16 v[80:83], v[180:183], v[140:143], v[80:83]
	v_mfma_f32_16x16x32_bf16 v[84:87], v[172:175], v[148:151], v[84:87]
	v_mfma_f32_16x16x32_bf16 v[88:91], v[180:183], v[148:151], v[88:91]
	v_mfma_f32_16x16x32_bf16 v[92:95], v[172:175], v[162:165], v[92:95]
	v_mfma_f32_16x16x32_bf16 v[96:99], v[180:183], v[162:165], v[96:99]
	v_mfma_f32_16x16x32_bf16 v[68:71], v[176:179], v[136:139], v[68:71]
	v_mfma_f32_16x16x32_bf16 v[72:75], v[184:187], v[136:139], v[72:75]
	v_mfma_f32_16x16x32_bf16 v[76:79], v[176:179], v[144:147], v[76:79]
	v_mfma_f32_16x16x32_bf16 v[80:83], v[184:187], v[144:147], v[80:83]
	v_mfma_f32_16x16x32_bf16 v[84:87], v[176:179], v[158:161], v[84:87]
	v_mfma_f32_16x16x32_bf16 v[88:91], v[184:187], v[158:161], v[88:91]
	v_mfma_f32_16x16x32_bf16 v[92:95], v[176:179], v[168:171], v[92:95]
	v_mfma_f32_16x16x32_bf16 v[96:99], v[184:187], v[168:171], v[96:99]
	s_setprio 0
	s_barrier
	s_add_i32 m0, s40, 0x14000
	s_nop 0
	global_load_lds_dwordx4 v208, s[80:81]
	global_load_lds_dwordx4 v209, s[82:83] offset:1024
	s_waitcnt vmcnt(6)
	s_barrier
	s_setprio 1
	v_mfma_f32_16x16x32_bf16 v[100:103], v[216:219], v[132:135], v[100:103]
	v_mfma_f32_16x16x32_bf16 v[104:107], v[224:227], v[132:135], v[104:107]
	v_mfma_f32_16x16x32_bf16 v[108:111], v[216:219], v[140:143], v[108:111]
	v_mfma_f32_16x16x32_bf16 v[112:115], v[224:227], v[140:143], v[112:115]
	v_mfma_f32_16x16x32_bf16 v[116:119], v[216:219], v[148:151], v[116:119]
	v_mfma_f32_16x16x32_bf16 v[120:123], v[224:227], v[148:151], v[120:123]
	v_mfma_f32_16x16x32_bf16 v[124:127], v[216:219], v[162:165], v[124:127]
	v_mfma_f32_16x16x32_bf16 v[128:131], v[224:227], v[162:165], v[128:131]
	v_mfma_f32_16x16x32_bf16 v[100:103], v[220:223], v[136:139], v[100:103]
	v_mfma_f32_16x16x32_bf16 v[104:107], v[228:231], v[136:139], v[104:107]
	v_mfma_f32_16x16x32_bf16 v[108:111], v[220:223], v[144:147], v[108:111]
	v_mfma_f32_16x16x32_bf16 v[112:115], v[228:231], v[144:147], v[112:115]
	v_mfma_f32_16x16x32_bf16 v[116:119], v[220:223], v[158:161], v[116:119]
	v_mfma_f32_16x16x32_bf16 v[120:123], v[228:231], v[158:161], v[120:123]
	v_mfma_f32_16x16x32_bf16 v[124:127], v[220:223], v[168:171], v[124:127]
	v_mfma_f32_16x16x32_bf16 v[128:131], v[228:231], v[168:171], v[128:131]
	s_setprio 0
	s_barrier
; #define MFMA32(a, b, c) __builtin_amdgcn_mfma_f32_32x32x16_bf16((a), (b), (c), 0, 0, 0)
; template <bool SWAP, class Epi>
; DI void gemm_tile(const u16* __restrict__ A, int lda, const u16* __restrict__ Bw, int ldb, int K, char* lds, Epi epi) {
;     ...
;   auto compute = [&](int st) {
;     const char* as = lds + st * GEMM_STAGE;
;     const char* bs = as + 36864;
; #pragma unroll
;     for (int ks = 0; ks < 4; ++ks) {
;       bf16x8 af[2], bfr[2];
; #pragma unroll
;       for (int mi = 0; mi < 2; ++mi) af[mi] = *(const bf16x8*)(as + ((wm * 64 + mi * 32 + r) * 72 + ks * 16 + 8 * h) * 2);
; #pragma unroll
;       for (int ni = 0; ni < 2; ++ni) bfr[ni] = *(const bf16x8*)(bs + ((wn * 64 + ni * 32 + r) * 72 + ks * 16 + 8 * h) * 2);
; #pragma unroll
;       for (int mi = 0; mi < 2; ++mi)
; #pragma unroll
;         for (int ni = 0; ni < 2; ++ni) {
;           if (SWAP) acc[mi][ni] = MFMA32(bfr[ni], af[mi], acc[mi][ni]);
;           else acc[mi][ni] = MFMA32(af[mi], bfr[ni], acc[mi][ni]);
;         }
;     }
;   };
;   gload(0, ra0, rb0);
;   lstore(0, ra0, rb0);
;   gload(1, ra1, rb1);
;   __syncthreads();
;   for (int kt = 0; kt < nk; kt += 2) {
;     if (kt + 2 < nk) gload(kt + 2, ra0, rb0);
;     compute(0);
;     lstore(1, ra1, rb1);
;     __syncthreads();
;     if (kt + 3 < nk) gload(kt + 3, ra1, rb1);
;     compute(1);
;     if (kt + 2 < nk) lstore(0, ra0, rb0);
;     __syncthreads();
	ds_read_b128 v[172:175], v212 offset:32768
	ds_read_b128 v[176:179], v213 offset:32768
	ds_read_b128 v[180:183], v212 offset:34816
	ds_read_b128 v[184:187], v213 offset:34816
	ds_read_b128 v[132:135], v210 offset:32768
	ds_read_b128 v[136:139], v211 offset:32768
	ds_read_b128 v[140:143], v210 offset:34816
	ds_read_b128 v[144:147], v211 offset:34816
	ds_read_b128 v[148:151], v210 offset:36864
	ds_read_b128 v[158:161], v211 offset:36864
	ds_read_b128 v[162:165], v210 offset:38912
	ds_read_b128 v[168:171], v211 offset:38912
	s_add_i32 m0, s40, 0x4000
	s_nop 0
	global_load_lds_dwordx4 v208, s[72:73]
	global_load_lds_dwordx4 v209, s[74:75] offset:1024
	s_waitcnt lgkmcnt(8)
	s_barrier
	s_waitcnt lgkmcnt(0)
	s_setprio 1
	v_mfma_f32_16x16x32_bf16 v[4:7], v[172:175], v[132:135], v[4:7]
	v_mfma_f32_16x16x32_bf16 v[8:11], v[180:183], v[132:135], v[8:11]
	v_mfma_f32_16x16x32_bf16 v[12:15], v[172:175], v[140:143], v[12:15]
	v_mfma_f32_16x16x32_bf16 v[16:19], v[180:183], v[140:143], v[16:19]
	v_mfma_f32_16x16x32_bf16 v[20:23], v[172:175], v[148:151], v[20:23]
	v_mfma_f32_16x16x32_bf16 v[24:27], v[180:183], v[148:151], v[24:27]
	v_mfma_f32_16x16x32_bf16 v[28:31], v[172:175], v[162:165], v[28:31]
	v_mfma_f32_16x16x32_bf16 v[32:35], v[180:183], v[162:165], v[32:35]
	v_mfma_f32_16x16x32_bf16 v[4:7], v[176:179], v[136:139], v[4:7]
	v_mfma_f32_16x16x32_bf16 v[8:11], v[184:187], v[136:139], v[8:11]
	v_mfma_f32_16x16x32_bf16 v[12:15], v[176:179], v[144:147], v[12:15]
	v_mfma_f32_16x16x32_bf16 v[16:19], v[184:187], v[144:147], v[16:19]
	v_mfma_f32_16x16x32_bf16 v[20:23], v[176:179], v[158:161], v[20:23]
	v_mfma_f32_16x16x32_bf16 v[24:27], v[184:187], v[158:161], v[24:27]
	v_mfma_f32_16x16x32_bf16 v[28:31], v[176:179], v[168:171], v[28:31]
	v_mfma_f32_16x16x32_bf16 v[32:35], v[184:187], v[168:171], v[32:35]
	s_setprio 0
	s_barrier
	ds_read_b128 v[216:219], v212 offset:49152
	ds_read_b128 v[220:223], v213 offset:49152
	ds_read_b128 v[224:227], v212 offset:51200
	ds_read_b128 v[228:231], v213 offset:51200
	v_add_u32_e32 v208, 0x80, v208
	v_add_u32_e32 v209, 0x80, v209
	s_add_i32 m0, s40, 0x18000
	s_nop 0
	global_load_lds_dwordx4 v208, s[76:77]
	global_load_lds_dwordx4 v209, s[78:79] offset:1024
	s_barrier
	s_waitcnt lgkmcnt(0)
	s_setprio 1
	v_mfma_f32_16x16x32_bf16 v[36:39], v[216:219], v[132:135], v[36:39]
	v_mfma_f32_16x16x32_bf16 v[40:43], v[224:227], v[132:135], v[40:43]
	v_mfma_f32_16x16x32_bf16 v[44:47], v[216:219], v[140:143], v[44:47]
	v_mfma_f32_16x16x32_bf16 v[48:51], v[224:227], v[140:143], v[48:51]
	v_mfma_f32_16x16x32_bf16 v[52:55], v[216:219], v[148:151], v[52:55]
	v_mfma_f32_16x16x32_bf16 v[56:59], v[224:227], v[148:151], v[56:59]
	v_mfma_f32_16x16x32_bf16 v[60:63], v[216:219], v[162:165], v[60:63]
	v_mfma_f32_16x16x32_bf16 v[64:67], v[224:227], v[162:165], v[64:67]
	v_mfma_f32_16x16x32_bf16 v[36:39], v[220:223], v[136:139], v[36:39]
	v_mfma_f32_16x16x32_bf16 v[40:43], v[228:231], v[136:139], v[40:43]
	v_mfma_f32_16x16x32_bf16 v[44:47], v[220:223], v[144:147], v[44:47]
	v_mfma_f32_16x16x32_bf16 v[48:51], v[228:231], v[144:147], v[48:51]
	v_mfma_f32_16x16x32_bf16 v[52:55], v[220:223], v[158:161], v[52:55]
	v_mfma_f32_16x16x32_bf16 v[56:59], v[228:231], v[158:161], v[56:59]
	v_mfma_f32_16x16x32_bf16 v[60:63], v[220:223], v[168:171], v[60:63]
	v_mfma_f32_16x16x32_bf16 v[64:67], v[228:231], v[168:171], v[64:67]
	s_setprio 0
	s_barrier
	ds_read_b128 v[132:135], v210 offset:49152
	ds_read_b128 v[136:139], v211 offset:49152
	ds_read_b128 v[140:143], v210 offset:51200
	ds_read_b128 v[144:147], v211 offset:51200
	ds_read_b128 v[148:151], v210 offset:53248
	ds_read_b128 v[158:161], v211 offset:53248
	ds_read_b128 v[162:165], v210 offset:55296
	ds_read_b128 v[168:171], v211 offset:55296
	s_add_i32 m0, s40, 0x8000
	s_nop 0
	global_load_lds_dwordx4 v208, s[68:69]
	global_load_lds_dwordx4 v209, s[70:71] offset:1024
	s_barrier
	s_waitcnt lgkmcnt(0)
	s_setprio 1
	v_mfma_f32_16x16x32_bf16 v[68:71], v[172:175], v[132:135], v[68:71]
	v_mfma_f32_16x16x32_bf16 v[72:75], v[180:183], v[132:135], v[72:75]
	v_mfma_f32_16x16x32_bf16 v[76:79], v[172:175], v[140:143], v[76:79]
	v_mfma_f32_16x16x32_bf16 v[80:83], v[180:183], v[140:143], v[80:83]
	v_mfma_f32_16x16x32_bf16 v[84:87], v[172:175], v[148:151], v[84:87]
	v_mfma_f32_16x16x32_bf16 v[88:91], v[180:183], v[148:151], v[88:91]
	v_mfma_f32_16x16x32_bf16 v[92:95], v[172:175], v[162:165], v[92:95]
	v_mfma_f32_16x16x32_bf16 v[96:99], v[180:183], v[162:165], v[96:99]
	v_mfma_f32_16x16x32_bf16 v[68:71], v[176:179], v[136:139], v[68:71]
	v_mfma_f32_16x16x32_bf16 v[72:75], v[184:187], v[136:139], v[72:75]
	v_mfma_f32_16x16x32_bf16 v[76:79], v[176:179], v[144:147], v[76:79]
	v_mfma_f32_16x16x32_bf16 v[80:83], v[184:187], v[144:147], v[80:83]
	v_mfma_f32_16x16x32_bf16 v[84:87], v[176:179], v[158:161], v[84:87]
	v_mfma_f32_16x16x32_bf16 v[88:91], v[184:187], v[158:161], v[88:91]
	v_mfma_f32_16x16x32_bf16 v[92:95], v[176:179], v[168:171], v[92:95]
	v_mfma_f32_16x16x32_bf16 v[96:99], v[184:187], v[168:171], v[96:99]
	s_setprio 0
	s_barrier
	s_add_i32 m0, s40, 0x1c000
	s_nop 0
	global_load_lds_dwordx4 v208, s[80:81]
	global_load_lds_dwordx4 v209, s[82:83] offset:1024
	s_waitcnt vmcnt(6)
	s_barrier
; #define MFMA32(a, b, c) __builtin_amdgcn_mfma_f32_32x32x16_bf16((a), (b), (c), 0, 0, 0)
; template <bool SWAP, class Epi>
; DI void gemm_tile(const u16* __restrict__ A, int lda, const u16* __restrict__ Bw, int ldb, int K, char* lds, Epi epi) {
;     ...
;   auto compute = [&](int st) {
;     const char* as = lds + st * GEMM_STAGE;
;     const char* bs = as + 36864;
; #pragma unroll
;     for (int ks = 0; ks < 4; ++ks) {
;       bf16x8 af[2], bfr[2];
; #pragma unroll
;       for (int mi = 0; mi < 2; ++mi) af[mi] = *(const bf16x8*)(as + ((wm * 64 + mi * 32 + r) * 72 + ks * 16 + 8 * h) * 2);
; #pragma unroll
;       for (int ni = 0; ni < 2; ++ni) bfr[ni] = *(const bf16x8*)(bs + ((wn * 64 + ni * 32 + r) * 72 + ks * 16 + 8 * h) * 2);
; #pragma unroll
;       for (int mi = 0; mi < 2; ++mi)
; #pragma unroll
;         for (int ni = 0; ni < 2; ++ni) {
;           if (SWAP) acc[mi][ni] = MFMA32(bfr[ni], af[mi], acc[mi][ni]);
;           else acc[mi][ni] = MFMA32(af[mi], bfr[ni], acc[mi][ni]);
;         }
;     }
;   };
;   gload(0, ra0, rb0);
;   lstore(0, ra0, rb0);
;   gload(1, ra1, rb1);
;   __syncthreads();
;   for (int kt = 0; kt < nk; kt += 2) {
;     if (kt + 2 < nk) gload(kt + 2, ra0, rb0);
;     compute(0);
;     lstore(1, ra1, rb1);
;     __syncthreads();
;     if (kt + 3 < nk) gload(kt + 3, ra1, rb1);
;     compute(1);
;     if (kt + 2 < nk) lstore(0, ra0, rb0);
;     __syncthreads();
	s_setprio 1
	v_mfma_f32_16x16x32_bf16 v[100:103], v[216:219], v[132:135], v[100:103]
	v_mfma_f32_16x16x32_bf16 v[104:107], v[224:227], v[132:135], v[104:107]
	v_mfma_f32_16x16x32_bf16 v[108:111], v[216:219], v[140:143], v[108:111]
	v_mfma_f32_16x16x32_bf16 v[112:115], v[224:227], v[140:143], v[112:115]
	v_mfma_f32_16x16x32_bf16 v[116:119], v[216:219], v[148:151], v[116:119]
	v_mfma_f32_16x16x32_bf16 v[120:123], v[224:227], v[148:151], v[120:123]
	v_mfma_f32_16x16x32_bf16 v[124:127], v[216:219], v[162:165], v[124:127]
	v_mfma_f32_16x16x32_bf16 v[128:131], v[224:227], v[162:165], v[128:131]
	v_mfma_f32_16x16x32_bf16 v[100:103], v[220:223], v[136:139], v[100:103]
	v_mfma_f32_16x16x32_bf16 v[104:107], v[228:231], v[136:139], v[104:107]
	v_mfma_f32_16x16x32_bf16 v[108:111], v[220:223], v[144:147], v[108:111]
	v_mfma_f32_16x16x32_bf16 v[112:115], v[228:231], v[144:147], v[112:115]
	v_mfma_f32_16x16x32_bf16 v[116:119], v[220:223], v[158:161], v[116:119]
	v_mfma_f32_16x16x32_bf16 v[120:123], v[228:231], v[158:161], v[120:123]
	v_mfma_f32_16x16x32_bf16 v[124:127], v[220:223], v[168:171], v[124:127]
	v_mfma_f32_16x16x32_bf16 v[128:131], v[228:231], v[168:171], v[128:131]
	s_setprio 0
	s_barrier
	ds_read_b128 v[172:175], v212 offset:0
	ds_read_b128 v[176:179], v213 offset:0
	ds_read_b128 v[180:183], v212 offset:2048
	ds_read_b128 v[184:187], v213 offset:2048
	ds_read_b128 v[132:135], v210 offset:0
	ds_read_b128 v[136:139], v211 offset:0
	ds_read_b128 v[140:143], v210 offset:2048
	ds_read_b128 v[144:147], v211 offset:2048
	ds_read_b128 v[148:151], v210 offset:4096
	ds_read_b128 v[158:161], v211 offset:4096
	ds_read_b128 v[162:165], v210 offset:6144
	ds_read_b128 v[168:171], v211 offset:6144
	s_add_i32 m0, s40, 0xc000
	s_nop 0
	global_load_lds_dwordx4 v208, s[72:73]
	global_load_lds_dwordx4 v209, s[74:75] offset:1024
	s_waitcnt lgkmcnt(8)
	s_barrier
	s_waitcnt lgkmcnt(0)
	s_setprio 1
	v_mfma_f32_16x16x32_bf16 v[4:7], v[172:175], v[132:135], v[4:7]
	v_mfma_f32_16x16x32_bf16 v[8:11], v[180:183], v[132:135], v[8:11]
	v_mfma_f32_16x16x32_bf16 v[12:15], v[172:175], v[140:143], v[12:15]
	v_mfma_f32_16x16x32_bf16 v[16:19], v[180:183], v[140:143], v[16:19]
	v_mfma_f32_16x16x32_bf16 v[20:23], v[172:175], v[148:151], v[20:23]
	v_mfma_f32_16x16x32_bf16 v[24:27], v[180:183], v[148:151], v[24:27]
	v_mfma_f32_16x16x32_bf16 v[28:31], v[172:175], v[162:165], v[28:31]
	v_mfma_f32_16x16x32_bf16 v[32:35], v[180:183], v[162:165], v[32:35]
	v_mfma_f32_16x16x32_bf16 v[4:7], v[176:179], v[136:139], v[4:7]
	v_mfma_f32_16x16x32_bf16 v[8:11], v[184:187], v[136:139], v[8:11]
	v_mfma_f32_16x16x32_bf16 v[12:15], v[176:179], v[144:147], v[12:15]
	v_mfma_f32_16x16x32_bf16 v[16:19], v[184:187], v[144:147], v[16:19]
	v_mfma_f32_16x16x32_bf16 v[20:23], v[176:179], v[158:161], v[20:23]
	v_mfma_f32_16x16x32_bf16 v[24:27], v[184:187], v[158:161], v[24:27]
	v_mfma_f32_16x16x32_bf16 v[28:31], v[176:179], v[168:171], v[28:31]
	v_mfma_f32_16x16x32_bf16 v[32:35], v[184:187], v[168:171], v[32:35]
	s_setprio 0
	s_barrier
	ds_read_b128 v[216:219], v212 offset:16384
	ds_read_b128 v[220:223], v213 offset:16384
	ds_read_b128 v[224:227], v212 offset:18432
	ds_read_b128 v[228:231], v213 offset:18432
	v_add_u32_e32 v208, 0x80, v208
	v_add_u32_e32 v209, 0x80, v209
	s_add_i32 m0, s40, 0x10000
	s_nop 0
	global_load_lds_dwordx4 v208, s[76:77]
	global_load_lds_dwordx4 v209, s[78:79] offset:1024
	s_barrier
	s_waitcnt lgkmcnt(0)
	s_setprio 1
	v_mfma_f32_16x16x32_bf16 v[36:39], v[216:219], v[132:135], v[36:39]
	v_mfma_f32_16x16x32_bf16 v[40:43], v[224:227], v[132:135], v[40:43]
	v_mfma_f32_16x16x32_bf16 v[44:47], v[216:219], v[140:143], v[44:47]
	v_mfma_f32_16x16x32_bf16 v[48:51], v[224:227], v[140:143], v[48:51]
	v_mfma_f32_16x16x32_bf16 v[52:55], v[216:219], v[148:151], v[52:55]
	v_mfma_f32_16x16x32_bf16 v[56:59], v[224:227], v[148:151], v[56:59]
	v_mfma_f32_16x16x32_bf16 v[60:63], v[216:219], v[162:165], v[60:63]
	v_mfma_f32_16x16x32_bf16 v[64:67], v[224:227], v[162:165], v[64:67]
	v_mfma_f32_16x16x32_bf16 v[36:39], v[220:223], v[136:139], v[36:39]
	v_mfma_f32_16x16x32_bf16 v[40:43], v[228:231], v[136:139], v[40:43]
	v_mfma_f32_16x16x32_bf16 v[44:47], v[220:223], v[144:147], v[44:47]
	v_mfma_f32_16x16x32_bf16 v[48:51], v[228:231], v[144:147], v[48:51]
	v_mfma_f32_16x16x32_bf16 v[52:55], v[220:223], v[158:161], v[52:55]
	v_mfma_f32_16x16x32_bf16 v[56:59], v[228:231], v[158:161], v[56:59]
	v_mfma_f32_16x16x32_bf16 v[60:63], v[220:223], v[168:171], v[60:63]
	v_mfma_f32_16x16x32_bf16 v[64:67], v[228:231], v[168:171], v[64:67]
	s_setprio 0
	s_barrier
	ds_read_b128 v[132:135], v210 offset:16384
	ds_read_b128 v[136:139], v211 offset:16384
	ds_read_b128 v[140:143], v210 offset:18432
	ds_read_b128 v[144:147], v211 offset:18432
	ds_read_b128 v[148:151], v210 offset:20480
	ds_read_b128 v[158:161], v211 offset:20480
	ds_read_b128 v[162:165], v210 offset:22528
	ds_read_b128 v[168:171], v211 offset:22528
	s_add_i32 m0, s40, 0x0
	s_nop 0
	global_load_lds_dwordx4 v208, s[68:69]
	global_load_lds_dwordx4 v209, s[70:71] offset:1024
	s_barrier
	s_waitcnt lgkmcnt(0)
	s_setprio 1
	v_mfma_f32_16x16x32_bf16 v[68:71], v[172:175], v[132:135], v[68:71]
	v_mfma_f32_16x16x32_bf16 v[72:75], v[180:183], v[132:135], v[72:75]
	v_mfma_f32_16x16x32_bf16 v[76:79], v[172:175], v[140:143], v[76:79]
	v_mfma_f32_16x16x32_bf16 v[80:83], v[180:183], v[140:143], v[80:83]
	v_mfma_f32_16x16x32_bf16 v[84:87], v[172:175], v[148:151], v[84:87]
	v_mfma_f32_16x16x32_bf16 v[88:91], v[180:183], v[148:151], v[88:91]
	v_mfma_f32_16x16x32_bf16 v[92:95], v[172:175], v[162:165], v[92:95]
	v_mfma_f32_16x16x32_bf16 v[96:99], v[180:183], v[162:165], v[96:99]
	v_mfma_f32_16x16x32_bf16 v[68:71], v[176:179], v[136:139], v[68:71]
	v_mfma_f32_16x16x32_bf16 v[72:75], v[184:187], v[136:139], v[72:75]
	v_mfma_f32_16x16x32_bf16 v[76:79], v[176:179], v[144:147], v[76:79]
	v_mfma_f32_16x16x32_bf16 v[80:83], v[184:187], v[144:147], v[80:83]
	v_mfma_f32_16x16x32_bf16 v[84:87], v[176:179], v[158:161], v[84:87]
	v_mfma_f32_16x16x32_bf16 v[88:91], v[184:187], v[158:161], v[88:91]
	v_mfma_f32_16x16x32_bf16 v[92:95], v[176:179], v[168:171], v[92:95]
	v_mfma_f32_16x16x32_bf16 v[96:99], v[184:187], v[168:171], v[96:99]
	s_setprio 0
	s_barrier
; #define MFMA32(a, b, c) __builtin_amdgcn_mfma_f32_32x32x16_bf16((a), (b), (c), 0, 0, 0)
; template <bool SWAP, class Epi>
; DI void gemm_tile(const u16* __restrict__ A, int lda, const u16* __restrict__ Bw, int ldb, int K, char* lds, Epi epi) {
;     ...
;   auto compute = [&](int st) {
;     const char* as = lds + st * GEMM_STAGE;
;     const char* bs = as + 36864;
; #pragma unroll
;     for (int ks = 0; ks < 4; ++ks) {
;       bf16x8 af[2], bfr[2];
; #pragma unroll
;       for (int mi = 0; mi < 2; ++mi) af[mi] = *(const bf16x8*)(as + ((wm * 64 + mi * 32 + r) * 72 + ks * 16 + 8 * h) * 2);
; #pragma unroll
;       for (int ni = 0; ni < 2; ++ni) bfr[ni] = *(const bf16x8*)(bs + ((wn * 64 + ni * 32 + r) * 72 + ks * 16 + 8 * h) * 2);
; #pragma unroll
;       for (int mi = 0; mi < 2; ++mi)
; #pragma unroll
;         for (int ni = 0; ni < 2; ++ni) {
;           if (SWAP) acc[mi][ni] = MFMA32(bfr[ni], af[mi], acc[mi][ni]);
;           else acc[mi][ni] = MFMA32(af[mi], bfr[ni], acc[mi][ni]);
;         }
;     }
;   };
;   gload(0, ra0, rb0);
;   lstore(0, ra0, rb0);
;   gload(1, ra1, rb1);
;   __syncthreads();
;   for (int kt = 0; kt < nk; kt += 2) {
;     if (kt + 2 < nk) gload(kt + 2, ra0, rb0);
;     compute(0);
;     lstore(1, ra1, rb1);
;     __syncthreads();
;     if (kt + 3 < nk) gload(kt + 3, ra1, rb1);
;     compute(1);
;     if (kt + 2 < nk) lstore(0, ra0, rb0);
;     __syncthreads();
	s_add_i32 m0, s40, 0x14000
	s_nop 0
	global_load_lds_dwordx4 v208, s[80:81]
	global_load_lds_dwordx4 v209, s[82:83] offset:1024
	s_waitcnt vmcnt(6)
	s_barrier
	s_setprio 1
	v_mfma_f32_16x16x32_bf16 v[100:103], v[216:219], v[132:135], v[100:103]
	v_mfma_f32_16x16x32_bf16 v[104:107], v[224:227], v[132:135], v[104:107]
	v_mfma_f32_16x16x32_bf16 v[108:111], v[216:219], v[140:143], v[108:111]
	v_mfma_f32_16x16x32_bf16 v[112:115], v[224:227], v[140:143], v[112:115]
	v_mfma_f32_16x16x32_bf16 v[116:119], v[216:219], v[148:151], v[116:119]
	v_mfma_f32_16x16x32_bf16 v[120:123], v[224:227], v[148:151], v[120:123]
	v_mfma_f32_16x16x32_bf16 v[124:127], v[216:219], v[162:165], v[124:127]
	v_mfma_f32_16x16x32_bf16 v[128:131], v[224:227], v[162:165], v[128:131]
	v_mfma_f32_16x16x32_bf16 v[100:103], v[220:223], v[136:139], v[100:103]
	v_mfma_f32_16x16x32_bf16 v[104:107], v[228:231], v[136:139], v[104:107]
	v_mfma_f32_16x16x32_bf16 v[108:111], v[220:223], v[144:147], v[108:111]
	v_mfma_f32_16x16x32_bf16 v[112:115], v[228:231], v[144:147], v[112:115]
	v_mfma_f32_16x16x32_bf16 v[116:119], v[220:223], v[158:161], v[116:119]
	v_mfma_f32_16x16x32_bf16 v[120:123], v[228:231], v[158:161], v[120:123]
	v_mfma_f32_16x16x32_bf16 v[124:127], v[220:223], v[168:171], v[124:127]
	v_mfma_f32_16x16x32_bf16 v[128:131], v[228:231], v[168:171], v[128:131]
	s_setprio 0
	s_barrier
	ds_read_b128 v[172:175], v212 offset:32768
	ds_read_b128 v[176:179], v213 offset:32768
	ds_read_b128 v[180:183], v212 offset:34816
	ds_read_b128 v[184:187], v213 offset:34816
	ds_read_b128 v[132:135], v210 offset:32768
	ds_read_b128 v[136:139], v211 offset:32768
	ds_read_b128 v[140:143], v210 offset:34816
	ds_read_b128 v[144:147], v211 offset:34816
	ds_read_b128 v[148:151], v210 offset:36864
	ds_read_b128 v[158:161], v211 offset:36864
	ds_read_b128 v[162:165], v210 offset:38912
	ds_read_b128 v[168:171], v211 offset:38912
	s_add_i32 m0, s40, 0x4000
	s_nop 0
	global_load_lds_dwordx4 v208, s[72:73]
	global_load_lds_dwordx4 v209, s[74:75] offset:1024
	s_waitcnt lgkmcnt(8)
	s_barrier
	s_waitcnt lgkmcnt(0)
	s_setprio 1
	v_mfma_f32_16x16x32_bf16 v[4:7], v[172:175], v[132:135], v[4:7]
	v_mfma_f32_16x16x32_bf16 v[8:11], v[180:183], v[132:135], v[8:11]
	v_mfma_f32_16x16x32_bf16 v[12:15], v[172:175], v[140:143], v[12:15]
	v_mfma_f32_16x16x32_bf16 v[16:19], v[180:183], v[140:143], v[16:19]
	v_mfma_f32_16x16x32_bf16 v[20:23], v[172:175], v[148:151], v[20:23]
	v_mfma_f32_16x16x32_bf16 v[24:27], v[180:183], v[148:151], v[24:27]
	v_mfma_f32_16x16x32_bf16 v[28:31], v[172:175], v[162:165], v[28:31]
	v_mfma_f32_16x16x32_bf16 v[32:35], v[180:183], v[162:165], v[32:35]
	v_mfma_f32_16x16x32_bf16 v[4:7], v[176:179], v[136:139], v[4:7]
	v_mfma_f32_16x16x32_bf16 v[8:11], v[184:187], v[136:139], v[8:11]
	v_mfma_f32_16x16x32_bf16 v[12:15], v[176:179], v[144:147], v[12:15]
	v_mfma_f32_16x16x32_bf16 v[16:19], v[184:187], v[144:147], v[16:19]
	v_mfma_f32_16x16x32_bf16 v[20:23], v[176:179], v[158:161], v[20:23]
	v_mfma_f32_16x16x32_bf16 v[24:27], v[184:187], v[158:161], v[24:27]
	v_mfma_f32_16x16x32_bf16 v[28:31], v[176:179], v[168:171], v[28:31]
	v_mfma_f32_16x16x32_bf16 v[32:35], v[184:187], v[168:171], v[32:35]
	s_setprio 0
	s_barrier
	ds_read_b128 v[216:219], v212 offset:49152
	ds_read_b128 v[220:223], v213 offset:49152
	ds_read_b128 v[224:227], v212 offset:51200
	ds_read_b128 v[228:231], v213 offset:51200
	v_add_u32_e32 v208, 0x80, v208
	v_add_u32_e32 v209, 0x80, v209
	s_add_i32 m0, s40, 0x18000
	s_nop 0
	global_load_lds_dwordx4 v208, s[76:77]
	global_load_lds_dwordx4 v209, s[78:79] offset:1024
	s_barrier
	s_waitcnt lgkmcnt(0)
	s_setprio 1
	v_mfma_f32_16x16x32_bf16 v[36:39], v[216:219], v[132:135], v[36:39]
	v_mfma_f32_16x16x32_bf16 v[40:43], v[224:227], v[132:135], v[40:43]
	v_mfma_f32_16x16x32_bf16 v[44:47], v[216:219], v[140:143], v[44:47]
	v_mfma_f32_16x16x32_bf16 v[48:51], v[224:227], v[140:143], v[48:51]
	v_mfma_f32_16x16x32_bf16 v[52:55], v[216:219], v[148:151], v[52:55]
	v_mfma_f32_16x16x32_bf16 v[56:59], v[224:227], v[148:151], v[56:59]
	v_mfma_f32_16x16x32_bf16 v[60:63], v[216:219], v[162:165], v[60:63]
	v_mfma_f32_16x16x32_bf16 v[64:67], v[224:227], v[162:165], v[64:67]
	v_mfma_f32_16x16x32_bf16 v[36:39], v[220:223], v[136:139], v[36:39]
	v_mfma_f32_16x16x32_bf16 v[40:43], v[228:231], v[136:139], v[40:43]
	v_mfma_f32_16x16x32_bf16 v[44:47], v[220:223], v[144:147], v[44:47]
	v_mfma_f32_16x16x32_bf16 v[48:51], v[228:231], v[144:147], v[48:51]
	v_mfma_f32_16x16x32_bf16 v[52:55], v[220:223], v[158:161], v[52:55]
	v_mfma_f32_16x16x32_bf16 v[56:59], v[228:231], v[158:161], v[56:59]
	v_mfma_f32_16x16x32_bf16 v[60:63], v[220:223], v[168:171], v[60:63]
	v_mfma_f32_16x16x32_bf16 v[64:67], v[228:231], v[168:171], v[64:67]
	s_setprio 0
	s_barrier
	ds_read_b128 v[132:135], v210 offset:49152
	ds_read_b128 v[136:139], v211 offset:49152
	ds_read_b128 v[140:143], v210 offset:51200
	ds_read_b128 v[144:147], v211 offset:51200
	ds_read_b128 v[148:151], v210 offset:53248
	ds_read_b128 v[158:161], v211 offset:53248
	ds_read_b128 v[162:165], v210 offset:55296
	ds_read_b128 v[168:171], v211 offset:55296
	s_add_i32 m0, s40, 0x8000
	s_nop 0
	global_load_lds_dwordx4 v208, s[68:69]
	global_load_lds_dwordx4 v209, s[70:71] offset:1024
	s_barrier
; #define MFMA32(a, b, c) __builtin_amdgcn_mfma_f32_32x32x16_bf16((a), (b), (c), 0, 0, 0)
; template <bool SWAP, class Epi>
; DI void gemm_tile(const u16* __restrict__ A, int lda, const u16* __restrict__ Bw, int ldb, int K, char* lds, Epi epi) {
;     ...
;   auto compute = [&](int st) {
;     const char* as = lds + st * GEMM_STAGE;
;     const char* bs = as + 36864;
; #pragma unroll
;     for (int ks = 0; ks < 4; ++ks) {
;       bf16x8 af[2], bfr[2];
; #pragma unroll
;       for (int mi = 0; mi < 2; ++mi) af[mi] = *(const bf16x8*)(as + ((wm * 64 + mi * 32 + r) * 72 + ks * 16 + 8 * h) * 2);
; #pragma unroll
;       for (int ni = 0; ni < 2; ++ni) bfr[ni] = *(const bf16x8*)(bs + ((wn * 64 + ni * 32 + r) * 72 + ks * 16 + 8 * h) * 2);
; #pragma unroll
;       for (int mi = 0; mi < 2; ++mi)
; #pragma unroll
;         for (int ni = 0; ni < 2; ++ni) {
;           if (SWAP) acc[mi][ni] = MFMA32(bfr[ni], af[mi], acc[mi][ni]);
;           else acc[mi][ni] = MFMA32(af[mi], bfr[ni], acc[mi][ni]);
;         }
;     }
;   };
;   gload(0, ra0, rb0);
;   lstore(0, ra0, rb0);
;   gload(1, ra1, rb1);
;   __syncthreads();
;   for (int kt = 0; kt < nk; kt += 2) {
;     if (kt + 2 < nk) gload(kt + 2, ra0, rb0);
;     compute(0);
;     lstore(1, ra1, rb1);
;     __syncthreads();
;     if (kt + 3 < nk) gload(kt + 3, ra1, rb1);
;     compute(1);
;     if (kt + 2 < nk) lstore(0, ra0, rb0);
;     __syncthreads();
	s_waitcnt lgkmcnt(0)
	s_setprio 1
	v_mfma_f32_16x16x32_bf16 v[68:71], v[172:175], v[132:135], v[68:71]
	v_mfma_f32_16x16x32_bf16 v[72:75], v[180:183], v[132:135], v[72:75]
	v_mfma_f32_16x16x32_bf16 v[76:79], v[172:175], v[140:143], v[76:79]
	v_mfma_f32_16x16x32_bf16 v[80:83], v[180:183], v[140:143], v[80:83]
	v_mfma_f32_16x16x32_bf16 v[84:87], v[172:175], v[148:151], v[84:87]
	v_mfma_f32_16x16x32_bf16 v[88:91], v[180:183], v[148:151], v[88:91]
	v_mfma_f32_16x16x32_bf16 v[92:95], v[172:175], v[162:165], v[92:95]
	v_mfma_f32_16x16x32_bf16 v[96:99], v[180:183], v[162:165], v[96:99]
	v_mfma_f32_16x16x32_bf16 v[68:71], v[176:179], v[136:139], v[68:71]
	v_mfma_f32_16x16x32_bf16 v[72:75], v[184:187], v[136:139], v[72:75]
	v_mfma_f32_16x16x32_bf16 v[76:79], v[176:179], v[144:147], v[76:79]
	v_mfma_f32_16x16x32_bf16 v[80:83], v[184:187], v[144:147], v[80:83]
	v_mfma_f32_16x16x32_bf16 v[84:87], v[176:179], v[158:161], v[84:87]
	v_mfma_f32_16x16x32_bf16 v[88:91], v[184:187], v[158:161], v[88:91]
	v_mfma_f32_16x16x32_bf16 v[92:95], v[176:179], v[168:171], v[92:95]
	v_mfma_f32_16x16x32_bf16 v[96:99], v[184:187], v[168:171], v[96:99]
	s_setprio 0
	s_barrier
	s_add_i32 m0, s40, 0x1c000
	s_nop 0
	global_load_lds_dwordx4 v208, s[80:81]
	global_load_lds_dwordx4 v209, s[82:83] offset:1024
	s_waitcnt vmcnt(6)
	s_barrier
	s_setprio 1
	v_mfma_f32_16x16x32_bf16 v[100:103], v[216:219], v[132:135], v[100:103]
	v_mfma_f32_16x16x32_bf16 v[104:107], v[224:227], v[132:135], v[104:107]
	v_mfma_f32_16x16x32_bf16 v[108:111], v[216:219], v[140:143], v[108:111]
	v_mfma_f32_16x16x32_bf16 v[112:115], v[224:227], v[140:143], v[112:115]
	v_mfma_f32_16x16x32_bf16 v[116:119], v[216:219], v[148:151], v[116:119]
	v_mfma_f32_16x16x32_bf16 v[120:123], v[224:227], v[148:151], v[120:123]
	v_mfma_f32_16x16x32_bf16 v[124:127], v[216:219], v[162:165], v[124:127]
	v_mfma_f32_16x16x32_bf16 v[128:131], v[224:227], v[162:165], v[128:131]
	v_mfma_f32_16x16x32_bf16 v[100:103], v[220:223], v[136:139], v[100:103]
	v_mfma_f32_16x16x32_bf16 v[104:107], v[228:231], v[136:139], v[104:107]
	v_mfma_f32_16x16x32_bf16 v[108:111], v[220:223], v[144:147], v[108:111]
	v_mfma_f32_16x16x32_bf16 v[112:115], v[228:231], v[144:147], v[112:115]
	v_mfma_f32_16x16x32_bf16 v[116:119], v[220:223], v[158:161], v[116:119]
	v_mfma_f32_16x16x32_bf16 v[120:123], v[228:231], v[158:161], v[120:123]
	v_mfma_f32_16x16x32_bf16 v[124:127], v[220:223], v[168:171], v[124:127]
	v_mfma_f32_16x16x32_bf16 v[128:131], v[228:231], v[168:171], v[128:131]
	s_setprio 0
	s_barrier
	ds_read_b128 v[172:175], v212 offset:0
	ds_read_b128 v[176:179], v213 offset:0
	ds_read_b128 v[180:183], v212 offset:2048
	ds_read_b128 v[184:187], v213 offset:2048
	ds_read_b128 v[132:135], v210 offset:0
	ds_read_b128 v[136:139], v211 offset:0
	ds_read_b128 v[140:143], v210 offset:2048
	ds_read_b128 v[144:147], v211 offset:2048
	ds_read_b128 v[148:151], v210 offset:4096
	ds_read_b128 v[158:161], v211 offset:4096
	ds_read_b128 v[162:165], v210 offset:6144
	ds_read_b128 v[168:171], v211 offset:6144
	s_add_i32 m0, s40, 0xc000
	s_nop 0
	global_load_lds_dwordx4 v208, s[72:73]
	global_load_lds_dwordx4 v209, s[74:75] offset:1024
	s_waitcnt lgkmcnt(8)
	s_barrier
	s_waitcnt lgkmcnt(0)
	s_setprio 1
	v_mfma_f32_16x16x32_bf16 v[4:7], v[172:175], v[132:135], v[4:7]
	v_mfma_f32_16x16x32_bf16 v[8:11], v[180:183], v[132:135], v[8:11]
	v_mfma_f32_16x16x32_bf16 v[12:15], v[172:175], v[140:143], v[12:15]
	v_mfma_f32_16x16x32_bf16 v[16:19], v[180:183], v[140:143], v[16:19]
	v_mfma_f32_16x16x32_bf16 v[20:23], v[172:175], v[148:151], v[20:23]
	v_mfma_f32_16x16x32_bf16 v[24:27], v[180:183], v[148:151], v[24:27]
	v_mfma_f32_16x16x32_bf16 v[28:31], v[172:175], v[162:165], v[28:31]
	v_mfma_f32_16x16x32_bf16 v[32:35], v[180:183], v[162:165], v[32:35]
	v_mfma_f32_16x16x32_bf16 v[4:7], v[176:179], v[136:139], v[4:7]
	v_mfma_f32_16x16x32_bf16 v[8:11], v[184:187], v[136:139], v[8:11]
	v_mfma_f32_16x16x32_bf16 v[12:15], v[176:179], v[144:147], v[12:15]
	v_mfma_f32_16x16x32_bf16 v[16:19], v[184:187], v[144:147], v[16:19]
	v_mfma_f32_16x16x32_bf16 v[20:23], v[176:179], v[158:161], v[20:23]
	v_mfma_f32_16x16x32_bf16 v[24:27], v[184:187], v[158:161], v[24:27]
	v_mfma_f32_16x16x32_bf16 v[28:31], v[176:179], v[168:171], v[28:31]
	v_mfma_f32_16x16x32_bf16 v[32:35], v[184:187], v[168:171], v[32:35]
	s_setprio 0
	s_barrier
	ds_read_b128 v[216:219], v212 offset:16384
	ds_read_b128 v[220:223], v213 offset:16384
	ds_read_b128 v[224:227], v212 offset:18432
	ds_read_b128 v[228:231], v213 offset:18432
	v_add_u32_e32 v208, 0x80, v208
	v_add_u32_e32 v209, 0x80, v209
	s_add_i32 m0, s40, 0x10000
	s_nop 0
	global_load_lds_dwordx4 v208, s[76:77]
	global_load_lds_dwordx4 v209, s[78:79] offset:1024
	s_barrier
	s_waitcnt lgkmcnt(0)
	s_setprio 1
	v_mfma_f32_16x16x32_bf16 v[36:39], v[216:219], v[132:135], v[36:39]
	v_mfma_f32_16x16x32_bf16 v[40:43], v[224:227], v[132:135], v[40:43]
	v_mfma_f32_16x16x32_bf16 v[44:47], v[216:219], v[140:143], v[44:47]
	v_mfma_f32_16x16x32_bf16 v[48:51], v[224:227], v[140:143], v[48:51]
	v_mfma_f32_16x16x32_bf16 v[52:55], v[216:219], v[148:151], v[52:55]
	v_mfma_f32_16x16x32_bf16 v[56:59], v[224:227], v[148:151], v[56:59]
	v_mfma_f32_16x16x32_bf16 v[60:63], v[216:219], v[162:165], v[60:63]
	v_mfma_f32_16x16x32_bf16 v[64:67], v[224:227], v[162:165], v[64:67]
	v_mfma_f32_16x16x32_bf16 v[36:39], v[220:223], v[136:139], v[36:39]
	v_mfma_f32_16x16x32_bf16 v[40:43], v[228:231], v[136:139], v[40:43]
	v_mfma_f32_16x16x32_bf16 v[44:47], v[220:223], v[144:147], v[44:47]
	v_mfma_f32_16x16x32_bf16 v[48:51], v[228:231], v[144:147], v[48:51]
	v_mfma_f32_16x16x32_bf16 v[52:55], v[220:223], v[158:161], v[52:55]
	v_mfma_f32_16x16x32_bf16 v[56:59], v[228:231], v[158:161], v[56:59]
	v_mfma_f32_16x16x32_bf16 v[60:63], v[220:223], v[168:171], v[60:63]
	v_mfma_f32_16x16x32_bf16 v[64:67], v[228:231], v[168:171], v[64:67]
	s_setprio 0
	s_barrier
; #define MFMA32(a, b, c) __builtin_amdgcn_mfma_f32_32x32x16_bf16((a), (b), (c), 0, 0, 0)
; template <bool SWAP, class Epi>
; DI void gemm_tile(const u16* __restrict__ A, int lda, const u16* __restrict__ Bw, int ldb, int K, char* lds, Epi epi) {
;     ...
;   auto compute = [&](int st) {
;     const char* as = lds + st * GEMM_STAGE;
;     const char* bs = as + 36864;
; #pragma unroll
;     for (int ks = 0; ks < 4; ++ks) {
;       bf16x8 af[2], bfr[2];
; #pragma unroll
;       for (int mi = 0; mi < 2; ++mi) af[mi] = *(const bf16x8*)(as + ((wm * 64 + mi * 32 + r) * 72 + ks * 16 + 8 * h) * 2);
; #pragma unroll
;       for (int ni = 0; ni < 2; ++ni) bfr[ni] = *(const bf16x8*)(bs + ((wn * 64 + ni * 32 + r) * 72 + ks * 16 + 8 * h) * 2);
; #pragma unroll
;       for (int mi = 0; mi < 2; ++mi)
; #pragma unroll
;         for (int ni = 0; ni < 2; ++ni) {
;           if (SWAP) acc[mi][ni] = MFMA32(bfr[ni], af[mi], acc[mi][ni]);
;           else acc[mi][ni] = MFMA32(af[mi], bfr[ni], acc[mi][ni]);
;         }
;     }
;   };
;   gload(0, ra0, rb0);
;   lstore(0, ra0, rb0);
;   gload(1, ra1, rb1);
;   __syncthreads();
;   for (int kt = 0; kt < nk; kt += 2) {
;     if (kt + 2 < nk) gload(kt + 2, ra0, rb0);
;     compute(0);
;     lstore(1, ra1, rb1);
;     __syncthreads();
;     if (kt + 3 < nk) gload(kt + 3, ra1, rb1);
;     compute(1);
;     if (kt + 2 < nk) lstore(0, ra0, rb0);
;     __syncthreads();
	ds_read_b128 v[132:135], v210 offset:16384
	ds_read_b128 v[136:139], v211 offset:16384
	ds_read_b128 v[140:143], v210 offset:18432
	ds_read_b128 v[144:147], v211 offset:18432
	ds_read_b128 v[148:151], v210 offset:20480
	ds_read_b128 v[158:161], v211 offset:20480
	ds_read_b128 v[162:165], v210 offset:22528
	ds_read_b128 v[168:171], v211 offset:22528
	s_add_i32 m0, s40, 0x0
	s_nop 0
	global_load_lds_dwordx4 v208, s[68:69]
	global_load_lds_dwordx4 v209, s[70:71] offset:1024
	s_barrier
	s_waitcnt lgkmcnt(0)
	s_setprio 1
	v_mfma_f32_16x16x32_bf16 v[68:71], v[172:175], v[132:135], v[68:71]
	v_mfma_f32_16x16x32_bf16 v[72:75], v[180:183], v[132:135], v[72:75]
	v_mfma_f32_16x16x32_bf16 v[76:79], v[172:175], v[140:143], v[76:79]
	v_mfma_f32_16x16x32_bf16 v[80:83], v[180:183], v[140:143], v[80:83]
	v_mfma_f32_16x16x32_bf16 v[84:87], v[172:175], v[148:151], v[84:87]
	v_mfma_f32_16x16x32_bf16 v[88:91], v[180:183], v[148:151], v[88:91]
	v_mfma_f32_16x16x32_bf16 v[92:95], v[172:175], v[162:165], v[92:95]
	v_mfma_f32_16x16x32_bf16 v[96:99], v[180:183], v[162:165], v[96:99]
	v_mfma_f32_16x16x32_bf16 v[68:71], v[176:179], v[136:139], v[68:71]
	v_mfma_f32_16x16x32_bf16 v[72:75], v[184:187], v[136:139], v[72:75]
	v_mfma_f32_16x16x32_bf16 v[76:79], v[176:179], v[144:147], v[76:79]
	v_mfma_f32_16x16x32_bf16 v[80:83], v[184:187], v[144:147], v[80:83]
	v_mfma_f32_16x16x32_bf16 v[84:87], v[176:179], v[158:161], v[84:87]
	v_mfma_f32_16x16x32_bf16 v[88:91], v[184:187], v[158:161], v[88:91]
	v_mfma_f32_16x16x32_bf16 v[92:95], v[176:179], v[168:171], v[92:95]
	v_mfma_f32_16x16x32_bf16 v[96:99], v[184:187], v[168:171], v[96:99]
	s_setprio 0
	s_barrier
	s_add_i32 m0, s40, 0x14000
	s_nop 0
	global_load_lds_dwordx4 v208, s[80:81]
	global_load_lds_dwordx4 v209, s[82:83] offset:1024
	s_waitcnt vmcnt(6)
	s_barrier
	s_setprio 1
	v_mfma_f32_16x16x32_bf16 v[100:103], v[216:219], v[132:135], v[100:103]
	v_mfma_f32_16x16x32_bf16 v[104:107], v[224:227], v[132:135], v[104:107]
	v_mfma_f32_16x16x32_bf16 v[108:111], v[216:219], v[140:143], v[108:111]
	v_mfma_f32_16x16x32_bf16 v[112:115], v[224:227], v[140:143], v[112:115]
	v_mfma_f32_16x16x32_bf16 v[116:119], v[216:219], v[148:151], v[116:119]
	v_mfma_f32_16x16x32_bf16 v[120:123], v[224:227], v[148:151], v[120:123]
	v_mfma_f32_16x16x32_bf16 v[124:127], v[216:219], v[162:165], v[124:127]
	v_mfma_f32_16x16x32_bf16 v[128:131], v[224:227], v[162:165], v[128:131]
	v_mfma_f32_16x16x32_bf16 v[100:103], v[220:223], v[136:139], v[100:103]
	v_mfma_f32_16x16x32_bf16 v[104:107], v[228:231], v[136:139], v[104:107]
	v_mfma_f32_16x16x32_bf16 v[108:111], v[220:223], v[144:147], v[108:111]
	v_mfma_f32_16x16x32_bf16 v[112:115], v[228:231], v[144:147], v[112:115]
	v_mfma_f32_16x16x32_bf16 v[116:119], v[220:223], v[158:161], v[116:119]
	v_mfma_f32_16x16x32_bf16 v[120:123], v[228:231], v[158:161], v[120:123]
	v_mfma_f32_16x16x32_bf16 v[124:127], v[220:223], v[168:171], v[124:127]
	v_mfma_f32_16x16x32_bf16 v[128:131], v[228:231], v[168:171], v[128:131]
	s_setprio 0
	s_barrier
	ds_read_b128 v[172:175], v212 offset:32768
	ds_read_b128 v[176:179], v213 offset:32768
	ds_read_b128 v[180:183], v212 offset:34816
	ds_read_b128 v[184:187], v213 offset:34816
	ds_read_b128 v[132:135], v210 offset:32768
	ds_read_b128 v[136:139], v211 offset:32768
	ds_read_b128 v[140:143], v210 offset:34816
	ds_read_b128 v[144:147], v211 offset:34816
	ds_read_b128 v[148:151], v210 offset:36864
	ds_read_b128 v[158:161], v211 offset:36864
	ds_read_b128 v[162:165], v210 offset:38912
	ds_read_b128 v[168:171], v211 offset:38912
	s_add_i32 m0, s40, 0x4000
	s_nop 0
	global_load_lds_dwordx4 v208, s[72:73]
	global_load_lds_dwordx4 v209, s[74:75] offset:1024
	s_waitcnt lgkmcnt(8)
	s_barrier
	s_waitcnt lgkmcnt(0)
	s_setprio 1
	v_mfma_f32_16x16x32_bf16 v[4:7], v[172:175], v[132:135], v[4:7]
	v_mfma_f32_16x16x32_bf16 v[8:11], v[180:183], v[132:135], v[8:11]
	v_mfma_f32_16x16x32_bf16 v[12:15], v[172:175], v[140:143], v[12:15]
	v_mfma_f32_16x16x32_bf16 v[16:19], v[180:183], v[140:143], v[16:19]
	v_mfma_f32_16x16x32_bf16 v[20:23], v[172:175], v[148:151], v[20:23]
	v_mfma_f32_16x16x32_bf16 v[24:27], v[180:183], v[148:151], v[24:27]
	v_mfma_f32_16x16x32_bf16 v[28:31], v[172:175], v[162:165], v[28:31]
	v_mfma_f32_16x16x32_bf16 v[32:35], v[180:183], v[162:165], v[32:35]
	v_mfma_f32_16x16x32_bf16 v[4:7], v[176:179], v[136:139], v[4:7]
	v_mfma_f32_16x16x32_bf16 v[8:11], v[184:187], v[136:139], v[8:11]
	v_mfma_f32_16x16x32_bf16 v[12:15], v[176:179], v[144:147], v[12:15]
	v_mfma_f32_16x16x32_bf16 v[16:19], v[184:187], v[144:147], v[16:19]
	v_mfma_f32_16x16x32_bf16 v[20:23], v[176:179], v[158:161], v[20:23]
	v_mfma_f32_16x16x32_bf16 v[24:27], v[184:187], v[158:161], v[24:27]
	v_mfma_f32_16x16x32_bf16 v[28:31], v[176:179], v[168:171], v[28:31]
	v_mfma_f32_16x16x32_bf16 v[32:35], v[184:187], v[168:171], v[32:35]
	s_setprio 0
	s_barrier
	ds_read_b128 v[216:219], v212 offset:49152
	ds_read_b128 v[220:223], v213 offset:49152
	ds_read_b128 v[224:227], v212 offset:51200
	ds_read_b128 v[228:231], v213 offset:51200
	v_add_u32_e32 v208, 0x80, v208
	v_add_u32_e32 v209, 0x80, v209
	s_add_i32 m0, s40, 0x18000
	s_nop 0
	global_load_lds_dwordx4 v208, s[76:77]
	global_load_lds_dwordx4 v209, s[78:79] offset:1024
	s_barrier
; #define MFMA32(a, b, c) __builtin_amdgcn_mfma_f32_32x32x16_bf16((a), (b), (c), 0, 0, 0)
; template <bool SWAP, class Epi>
; DI void gemm_tile(const u16* __restrict__ A, int lda, const u16* __restrict__ Bw, int ldb, int K, char* lds, Epi epi) {
;     ...
;   auto compute = [&](int st) {
;     const char* as = lds + st * GEMM_STAGE;
;     const char* bs = as + 36864;
; #pragma unroll
;     for (int ks = 0; ks < 4; ++ks) {
;       bf16x8 af[2], bfr[2];
; #pragma unroll
;       for (int mi = 0; mi < 2; ++mi) af[mi] = *(const bf16x8*)(as + ((wm * 64 + mi * 32 + r) * 72 + ks * 16 + 8 * h) * 2);
; #pragma unroll
;       for (int ni = 0; ni < 2; ++ni) bfr[ni] = *(const bf16x8*)(bs + ((wn * 64 + ni * 32 + r) * 72 + ks * 16 + 8 * h) * 2);
; #pragma unroll
;       for (int mi = 0; mi < 2; ++mi)
; #pragma unroll
;         for (int ni = 0; ni < 2; ++ni) {
;           if (SWAP) acc[mi][ni] = MFMA32(bfr[ni], af[mi], acc[mi][ni]);
;           else acc[mi][ni] = MFMA32(af[mi], bfr[ni], acc[mi][ni]);
;         }
;     }
;   };
;   gload(0, ra0, rb0);
;   lstore(0, ra0, rb0);
;   gload(1, ra1, rb1);
;   __syncthreads();
;   for (int kt = 0; kt < nk; kt += 2) {
;     if (kt + 2 < nk) gload(kt + 2, ra0, rb0);
;     compute(0);
;     lstore(1, ra1, rb1);
;     __syncthreads();
;     if (kt + 3 < nk) gload(kt + 3, ra1, rb1);
;     compute(1);
;     if (kt + 2 < nk) lstore(0, ra0, rb0);
;     __syncthreads();
	s_waitcnt lgkmcnt(0)
	s_setprio 1
	v_mfma_f32_16x16x32_bf16 v[36:39], v[216:219], v[132:135], v[36:39]
	v_mfma_f32_16x16x32_bf16 v[40:43], v[224:227], v[132:135], v[40:43]
	v_mfma_f32_16x16x32_bf16 v[44:47], v[216:219], v[140:143], v[44:47]
	v_mfma_f32_16x16x32_bf16 v[48:51], v[224:227], v[140:143], v[48:51]
	v_mfma_f32_16x16x32_bf16 v[52:55], v[216:219], v[148:151], v[52:55]
	v_mfma_f32_16x16x32_bf16 v[56:59], v[224:227], v[148:151], v[56:59]
	v_mfma_f32_16x16x32_bf16 v[60:63], v[216:219], v[162:165], v[60:63]
	v_mfma_f32_16x16x32_bf16 v[64:67], v[224:227], v[162:165], v[64:67]
	v_mfma_f32_16x16x32_bf16 v[36:39], v[220:223], v[136:139], v[36:39]
	v_mfma_f32_16x16x32_bf16 v[40:43], v[228:231], v[136:139], v[40:43]
	v_mfma_f32_16x16x32_bf16 v[44:47], v[220:223], v[144:147], v[44:47]
	v_mfma_f32_16x16x32_bf16 v[48:51], v[228:231], v[144:147], v[48:51]
	v_mfma_f32_16x16x32_bf16 v[52:55], v[220:223], v[158:161], v[52:55]
	v_mfma_f32_16x16x32_bf16 v[56:59], v[228:231], v[158:161], v[56:59]
	v_mfma_f32_16x16x32_bf16 v[60:63], v[220:223], v[168:171], v[60:63]
	v_mfma_f32_16x16x32_bf16 v[64:67], v[228:231], v[168:171], v[64:67]
	s_setprio 0
	s_barrier
	ds_read_b128 v[132:135], v210 offset:49152
	ds_read_b128 v[136:139], v211 offset:49152
	ds_read_b128 v[140:143], v210 offset:51200
	ds_read_b128 v[144:147], v211 offset:51200
	ds_read_b128 v[148:151], v210 offset:53248
	ds_read_b128 v[158:161], v211 offset:53248
	ds_read_b128 v[162:165], v210 offset:55296
	ds_read_b128 v[168:171], v211 offset:55296
	s_add_i32 m0, s40, 0x8000
	s_nop 0
	global_load_lds_dwordx4 v208, s[68:69]
	global_load_lds_dwordx4 v209, s[70:71] offset:1024
	s_barrier
	s_waitcnt lgkmcnt(0)
	s_setprio 1
	v_mfma_f32_16x16x32_bf16 v[68:71], v[172:175], v[132:135], v[68:71]
	v_mfma_f32_16x16x32_bf16 v[72:75], v[180:183], v[132:135], v[72:75]
	v_mfma_f32_16x16x32_bf16 v[76:79], v[172:175], v[140:143], v[76:79]
	v_mfma_f32_16x16x32_bf16 v[80:83], v[180:183], v[140:143], v[80:83]
	v_mfma_f32_16x16x32_bf16 v[84:87], v[172:175], v[148:151], v[84:87]
	v_mfma_f32_16x16x32_bf16 v[88:91], v[180:183], v[148:151], v[88:91]
	v_mfma_f32_16x16x32_bf16 v[92:95], v[172:175], v[162:165], v[92:95]
	v_mfma_f32_16x16x32_bf16 v[96:99], v[180:183], v[162:165], v[96:99]
	v_mfma_f32_16x16x32_bf16 v[68:71], v[176:179], v[136:139], v[68:71]
	v_mfma_f32_16x16x32_bf16 v[72:75], v[184:187], v[136:139], v[72:75]
	v_mfma_f32_16x16x32_bf16 v[76:79], v[176:179], v[144:147], v[76:79]
	v_mfma_f32_16x16x32_bf16 v[80:83], v[184:187], v[144:147], v[80:83]
	v_mfma_f32_16x16x32_bf16 v[84:87], v[176:179], v[158:161], v[84:87]
	v_mfma_f32_16x16x32_bf16 v[88:91], v[184:187], v[158:161], v[88:91]
	v_mfma_f32_16x16x32_bf16 v[92:95], v[176:179], v[168:171], v[92:95]
	v_mfma_f32_16x16x32_bf16 v[96:99], v[184:187], v[168:171], v[96:99]
	s_setprio 0
	s_barrier
	s_add_i32 m0, s40, 0x1c000
	s_nop 0
	global_load_lds_dwordx4 v208, s[80:81]
	global_load_lds_dwordx4 v209, s[82:83] offset:1024
	s_waitcnt vmcnt(6)
	s_barrier
	s_setprio 1
	v_mfma_f32_16x16x32_bf16 v[100:103], v[216:219], v[132:135], v[100:103]
	v_mfma_f32_16x16x32_bf16 v[104:107], v[224:227], v[132:135], v[104:107]
	v_mfma_f32_16x16x32_bf16 v[108:111], v[216:219], v[140:143], v[108:111]
	v_mfma_f32_16x16x32_bf16 v[112:115], v[224:227], v[140:143], v[112:115]
	v_mfma_f32_16x16x32_bf16 v[116:119], v[216:219], v[148:151], v[116:119]
	v_mfma_f32_16x16x32_bf16 v[120:123], v[224:227], v[148:151], v[120:123]
	v_mfma_f32_16x16x32_bf16 v[124:127], v[216:219], v[162:165], v[124:127]
	v_mfma_f32_16x16x32_bf16 v[128:131], v[224:227], v[162:165], v[128:131]
	v_mfma_f32_16x16x32_bf16 v[100:103], v[220:223], v[136:139], v[100:103]
	v_mfma_f32_16x16x32_bf16 v[104:107], v[228:231], v[136:139], v[104:107]
	v_mfma_f32_16x16x32_bf16 v[108:111], v[220:223], v[144:147], v[108:111]
	v_mfma_f32_16x16x32_bf16 v[112:115], v[228:231], v[144:147], v[112:115]
	v_mfma_f32_16x16x32_bf16 v[116:119], v[220:223], v[158:161], v[116:119]
	v_mfma_f32_16x16x32_bf16 v[120:123], v[228:231], v[158:161], v[120:123]
	v_mfma_f32_16x16x32_bf16 v[124:127], v[220:223], v[168:171], v[124:127]
	v_mfma_f32_16x16x32_bf16 v[128:131], v[228:231], v[168:171], v[128:131]
	s_setprio 0
	s_barrier
	ds_read_b128 v[172:175], v212 offset:0
	ds_read_b128 v[176:179], v213 offset:0
	ds_read_b128 v[180:183], v212 offset:2048
	ds_read_b128 v[184:187], v213 offset:2048
	ds_read_b128 v[132:135], v210 offset:0
	ds_read_b128 v[136:139], v211 offset:0
	ds_read_b128 v[140:143], v210 offset:2048
	ds_read_b128 v[144:147], v211 offset:2048
	ds_read_b128 v[148:151], v210 offset:4096
	ds_read_b128 v[158:161], v211 offset:4096
	ds_read_b128 v[162:165], v210 offset:6144
	ds_read_b128 v[168:171], v211 offset:6144
	s_add_i32 m0, s40, 0xc000
	s_nop 0
	global_load_lds_dwordx4 v208, s[72:73]
	global_load_lds_dwordx4 v209, s[74:75] offset:1024
	s_waitcnt lgkmcnt(8)
	s_barrier
	s_waitcnt lgkmcnt(0)
	s_setprio 1
	v_mfma_f32_16x16x32_bf16 v[4:7], v[172:175], v[132:135], v[4:7]
	v_mfma_f32_16x16x32_bf16 v[8:11], v[180:183], v[132:135], v[8:11]
	v_mfma_f32_16x16x32_bf16 v[12:15], v[172:175], v[140:143], v[12:15]
	v_mfma_f32_16x16x32_bf16 v[16:19], v[180:183], v[140:143], v[16:19]
	v_mfma_f32_16x16x32_bf16 v[20:23], v[172:175], v[148:151], v[20:23]
	v_mfma_f32_16x16x32_bf16 v[24:27], v[180:183], v[148:151], v[24:27]
	v_mfma_f32_16x16x32_bf16 v[28:31], v[172:175], v[162:165], v[28:31]
	v_mfma_f32_16x16x32_bf16 v[32:35], v[180:183], v[162:165], v[32:35]
	v_mfma_f32_16x16x32_bf16 v[4:7], v[176:179], v[136:139], v[4:7]
	v_mfma_f32_16x16x32_bf16 v[8:11], v[184:187], v[136:139], v[8:11]
	v_mfma_f32_16x16x32_bf16 v[12:15], v[176:179], v[144:147], v[12:15]
	v_mfma_f32_16x16x32_bf16 v[16:19], v[184:187], v[144:147], v[16:19]
	v_mfma_f32_16x16x32_bf16 v[20:23], v[176:179], v[158:161], v[20:23]
	v_mfma_f32_16x16x32_bf16 v[24:27], v[184:187], v[158:161], v[24:27]
	v_mfma_f32_16x16x32_bf16 v[28:31], v[176:179], v[168:171], v[28:31]
	v_mfma_f32_16x16x32_bf16 v[32:35], v[184:187], v[168:171], v[32:35]
	s_setprio 0
	s_barrier
; #define MFMA32(a, b, c) __builtin_amdgcn_mfma_f32_32x32x16_bf16((a), (b), (c), 0, 0, 0)
; template <bool SWAP, class Epi>
; DI void gemm_tile(const u16* __restrict__ A, int lda, const u16* __restrict__ Bw, int ldb, int K, char* lds, Epi epi) {
;     ...
;   auto compute = [&](int st) {
;     const char* as = lds + st * GEMM_STAGE;
;     const char* bs = as + 36864;
; #pragma unroll
;     for (int ks = 0; ks < 4; ++ks) {
;       bf16x8 af[2], bfr[2];
; #pragma unroll
;       for (int mi = 0; mi < 2; ++mi) af[mi] = *(const bf16x8*)(as + ((wm * 64 + mi * 32 + r) * 72 + ks * 16 + 8 * h) * 2);
; #pragma unroll
;       for (int ni = 0; ni < 2; ++ni) bfr[ni] = *(const bf16x8*)(bs + ((wn * 64 + ni * 32 + r) * 72 + ks * 16 + 8 * h) * 2);
; #pragma unroll
;       for (int mi = 0; mi < 2; ++mi)
; #pragma unroll
;         for (int ni = 0; ni < 2; ++ni) {
;           if (SWAP) acc[mi][ni] = MFMA32(bfr[ni], af[mi], acc[mi][ni]);
;           else acc[mi][ni] = MFMA32(af[mi], bfr[ni], acc[mi][ni]);
;         }
;     }
;   };
;   gload(0, ra0, rb0);
;   lstore(0, ra0, rb0);
;   gload(1, ra1, rb1);
;   __syncthreads();
;   for (int kt = 0; kt < nk; kt += 2) {
;     if (kt + 2 < nk) gload(kt + 2, ra0, rb0);
;     compute(0);
;     lstore(1, ra1, rb1);
;     __syncthreads();
;     if (kt + 3 < nk) gload(kt + 3, ra1, rb1);
;     compute(1);
;     if (kt + 2 < nk) lstore(0, ra0, rb0);
;     __syncthreads();
	ds_read_b128 v[216:219], v212 offset:16384
	ds_read_b128 v[220:223], v213 offset:16384
	ds_read_b128 v[224:227], v212 offset:18432
	ds_read_b128 v[228:231], v213 offset:18432
	v_add_u32_e32 v208, 0x80, v208
	v_add_u32_e32 v209, 0x80, v209
	s_add_i32 m0, s40, 0x10000
	s_nop 0
	global_load_lds_dwordx4 v208, s[76:77]
	global_load_lds_dwordx4 v209, s[78:79] offset:1024
	s_barrier
	s_waitcnt lgkmcnt(0)
	s_setprio 1
	v_mfma_f32_16x16x32_bf16 v[36:39], v[216:219], v[132:135], v[36:39]
	v_mfma_f32_16x16x32_bf16 v[40:43], v[224:227], v[132:135], v[40:43]
	v_mfma_f32_16x16x32_bf16 v[44:47], v[216:219], v[140:143], v[44:47]
	v_mfma_f32_16x16x32_bf16 v[48:51], v[224:227], v[140:143], v[48:51]
	v_mfma_f32_16x16x32_bf16 v[52:55], v[216:219], v[148:151], v[52:55]
	v_mfma_f32_16x16x32_bf16 v[56:59], v[224:227], v[148:151], v[56:59]
	v_mfma_f32_16x16x32_bf16 v[60:63], v[216:219], v[162:165], v[60:63]
	v_mfma_f32_16x16x32_bf16 v[64:67], v[224:227], v[162:165], v[64:67]
	v_mfma_f32_16x16x32_bf16 v[36:39], v[220:223], v[136:139], v[36:39]
	v_mfma_f32_16x16x32_bf16 v[40:43], v[228:231], v[136:139], v[40:43]
	v_mfma_f32_16x16x32_bf16 v[44:47], v[220:223], v[144:147], v[44:47]
	v_mfma_f32_16x16x32_bf16 v[48:51], v[228:231], v[144:147], v[48:51]
	v_mfma_f32_16x16x32_bf16 v[52:55], v[220:223], v[158:161], v[52:55]
	v_mfma_f32_16x16x32_bf16 v[56:59], v[228:231], v[158:161], v[56:59]
	v_mfma_f32_16x16x32_bf16 v[60:63], v[220:223], v[168:171], v[60:63]
	v_mfma_f32_16x16x32_bf16 v[64:67], v[228:231], v[168:171], v[64:67]
	s_setprio 0
	s_barrier
	ds_read_b128 v[132:135], v210 offset:16384
	ds_read_b128 v[136:139], v211 offset:16384
	ds_read_b128 v[140:143], v210 offset:18432
	ds_read_b128 v[144:147], v211 offset:18432
	ds_read_b128 v[148:151], v210 offset:20480
	ds_read_b128 v[158:161], v211 offset:20480
	ds_read_b128 v[162:165], v210 offset:22528
	ds_read_b128 v[168:171], v211 offset:22528
	s_add_i32 m0, s40, 0x0
	s_nop 0
	global_load_lds_dwordx4 v208, s[68:69]
	global_load_lds_dwordx4 v209, s[70:71] offset:1024
	s_barrier
	s_waitcnt lgkmcnt(0)
	s_setprio 1
	v_mfma_f32_16x16x32_bf16 v[68:71], v[172:175], v[132:135], v[68:71]
	v_mfma_f32_16x16x32_bf16 v[72:75], v[180:183], v[132:135], v[72:75]
	v_mfma_f32_16x16x32_bf16 v[76:79], v[172:175], v[140:143], v[76:79]
	v_mfma_f32_16x16x32_bf16 v[80:83], v[180:183], v[140:143], v[80:83]
	v_mfma_f32_16x16x32_bf16 v[84:87], v[172:175], v[148:151], v[84:87]
	v_mfma_f32_16x16x32_bf16 v[88:91], v[180:183], v[148:151], v[88:91]
	v_mfma_f32_16x16x32_bf16 v[92:95], v[172:175], v[162:165], v[92:95]
	v_mfma_f32_16x16x32_bf16 v[96:99], v[180:183], v[162:165], v[96:99]
	v_mfma_f32_16x16x32_bf16 v[68:71], v[176:179], v[136:139], v[68:71]
	v_mfma_f32_16x16x32_bf16 v[72:75], v[184:187], v[136:139], v[72:75]
	v_mfma_f32_16x16x32_bf16 v[76:79], v[176:179], v[144:147], v[76:79]
	v_mfma_f32_16x16x32_bf16 v[80:83], v[184:187], v[144:147], v[80:83]
	v_mfma_f32_16x16x32_bf16 v[84:87], v[176:179], v[158:161], v[84:87]
	v_mfma_f32_16x16x32_bf16 v[88:91], v[184:187], v[158:161], v[88:91]
	v_mfma_f32_16x16x32_bf16 v[92:95], v[176:179], v[168:171], v[92:95]
	v_mfma_f32_16x16x32_bf16 v[96:99], v[184:187], v[168:171], v[96:99]
	s_setprio 0
	s_barrier
	s_add_i32 m0, s40, 0x14000
	s_nop 0
	global_load_lds_dwordx4 v208, s[80:81]
	global_load_lds_dwordx4 v209, s[82:83] offset:1024
	s_waitcnt vmcnt(6)
	s_barrier
	s_setprio 1
	v_mfma_f32_16x16x32_bf16 v[100:103], v[216:219], v[132:135], v[100:103]
	v_mfma_f32_16x16x32_bf16 v[104:107], v[224:227], v[132:135], v[104:107]
	v_mfma_f32_16x16x32_bf16 v[108:111], v[216:219], v[140:143], v[108:111]
	v_mfma_f32_16x16x32_bf16 v[112:115], v[224:227], v[140:143], v[112:115]
	v_mfma_f32_16x16x32_bf16 v[116:119], v[216:219], v[148:151], v[116:119]
	v_mfma_f32_16x16x32_bf16 v[120:123], v[224:227], v[148:151], v[120:123]
	v_mfma_f32_16x16x32_bf16 v[124:127], v[216:219], v[162:165], v[124:127]
	v_mfma_f32_16x16x32_bf16 v[128:131], v[224:227], v[162:165], v[128:131]
	v_mfma_f32_16x16x32_bf16 v[100:103], v[220:223], v[136:139], v[100:103]
	v_mfma_f32_16x16x32_bf16 v[104:107], v[228:231], v[136:139], v[104:107]
	v_mfma_f32_16x16x32_bf16 v[108:111], v[220:223], v[144:147], v[108:111]
	v_mfma_f32_16x16x32_bf16 v[112:115], v[228:231], v[144:147], v[112:115]
	v_mfma_f32_16x16x32_bf16 v[116:119], v[220:223], v[158:161], v[116:119]
	v_mfma_f32_16x16x32_bf16 v[120:123], v[228:231], v[158:161], v[120:123]
	v_mfma_f32_16x16x32_bf16 v[124:127], v[220:223], v[168:171], v[124:127]
	v_mfma_f32_16x16x32_bf16 v[128:131], v[228:231], v[168:171], v[128:131]
	s_setprio 0
	s_barrier
	ds_read_b128 v[172:175], v212 offset:32768
	ds_read_b128 v[176:179], v213 offset:32768
	ds_read_b128 v[180:183], v212 offset:34816
	ds_read_b128 v[184:187], v213 offset:34816
	ds_read_b128 v[132:135], v210 offset:32768
	ds_read_b128 v[136:139], v211 offset:32768
	ds_read_b128 v[140:143], v210 offset:34816
	ds_read_b128 v[144:147], v211 offset:34816
	ds_read_b128 v[148:151], v210 offset:36864
	ds_read_b128 v[158:161], v211 offset:36864
	ds_read_b128 v[162:165], v210 offset:38912
	ds_read_b128 v[168:171], v211 offset:38912
	s_add_i32 m0, s40, 0x4000
	s_nop 0
	global_load_lds_dwordx4 v208, s[72:73]
	global_load_lds_dwordx4 v209, s[74:75] offset:1024
	s_waitcnt lgkmcnt(8)
	s_barrier
; #define MFMA32(a, b, c) __builtin_amdgcn_mfma_f32_32x32x16_bf16((a), (b), (c), 0, 0, 0)
; template <bool SWAP, class Epi>
; DI void gemm_tile(const u16* __restrict__ A, int lda, const u16* __restrict__ Bw, int ldb, int K, char* lds, Epi epi) {
;     ...
;   auto compute = [&](int st) {
;     const char* as = lds + st * GEMM_STAGE;
;     const char* bs = as + 36864;
; #pragma unroll
;     for (int ks = 0; ks < 4; ++ks) {
;       bf16x8 af[2], bfr[2];
; #pragma unroll
;       for (int mi = 0; mi < 2; ++mi) af[mi] = *(const bf16x8*)(as + ((wm * 64 + mi * 32 + r) * 72 + ks * 16 + 8 * h) * 2);
; #pragma unroll
;       for (int ni = 0; ni < 2; ++ni) bfr[ni] = *(const bf16x8*)(bs + ((wn * 64 + ni * 32 + r) * 72 + ks * 16 + 8 * h) * 2);
; #pragma unroll
;       for (int mi = 0; mi < 2; ++mi)
; #pragma unroll
;         for (int ni = 0; ni < 2; ++ni) {
;           if (SWAP) acc[mi][ni] = MFMA32(bfr[ni], af[mi], acc[mi][ni]);
;           else acc[mi][ni] = MFMA32(af[mi], bfr[ni], acc[mi][ni]);
;         }
;     }
;   };
;   gload(0, ra0, rb0);
;   lstore(0, ra0, rb0);
;   gload(1, ra1, rb1);
;   __syncthreads();
;   for (int kt = 0; kt < nk; kt += 2) {
;     if (kt + 2 < nk) gload(kt + 2, ra0, rb0);
;     compute(0);
;     lstore(1, ra1, rb1);
;     __syncthreads();
;     if (kt + 3 < nk) gload(kt + 3, ra1, rb1);
;     compute(1);
;     if (kt + 2 < nk) lstore(0, ra0, rb0);
;     __syncthreads();
	s_waitcnt lgkmcnt(0)
	s_setprio 1
	v_mfma_f32_16x16x32_bf16 v[4:7], v[172:175], v[132:135], v[4:7]
	v_mfma_f32_16x16x32_bf16 v[8:11], v[180:183], v[132:135], v[8:11]
	v_mfma_f32_16x16x32_bf16 v[12:15], v[172:175], v[140:143], v[12:15]
	v_mfma_f32_16x16x32_bf16 v[16:19], v[180:183], v[140:143], v[16:19]
	v_mfma_f32_16x16x32_bf16 v[20:23], v[172:175], v[148:151], v[20:23]
	v_mfma_f32_16x16x32_bf16 v[24:27], v[180:183], v[148:151], v[24:27]
	v_mfma_f32_16x16x32_bf16 v[28:31], v[172:175], v[162:165], v[28:31]
	v_mfma_f32_16x16x32_bf16 v[32:35], v[180:183], v[162:165], v[32:35]
	v_mfma_f32_16x16x32_bf16 v[4:7], v[176:179], v[136:139], v[4:7]
	v_mfma_f32_16x16x32_bf16 v[8:11], v[184:187], v[136:139], v[8:11]
	v_mfma_f32_16x16x32_bf16 v[12:15], v[176:179], v[144:147], v[12:15]
	v_mfma_f32_16x16x32_bf16 v[16:19], v[184:187], v[144:147], v[16:19]
	v_mfma_f32_16x16x32_bf16 v[20:23], v[176:179], v[158:161], v[20:23]
	v_mfma_f32_16x16x32_bf16 v[24:27], v[184:187], v[158:161], v[24:27]
	v_mfma_f32_16x16x32_bf16 v[28:31], v[176:179], v[168:171], v[28:31]
	v_mfma_f32_16x16x32_bf16 v[32:35], v[184:187], v[168:171], v[32:35]
	s_setprio 0
	s_barrier
	ds_read_b128 v[216:219], v212 offset:49152
	ds_read_b128 v[220:223], v213 offset:49152
	ds_read_b128 v[224:227], v212 offset:51200
	ds_read_b128 v[228:231], v213 offset:51200
	v_add_u32_e32 v208, 0x80, v208
	v_add_u32_e32 v209, 0x80, v209
	s_add_i32 m0, s40, 0x18000
	s_nop 0
	global_load_lds_dwordx4 v208, s[76:77]
	global_load_lds_dwordx4 v209, s[78:79] offset:1024
	s_barrier
	s_waitcnt lgkmcnt(0)
	s_setprio 1
	v_mfma_f32_16x16x32_bf16 v[36:39], v[216:219], v[132:135], v[36:39]
	v_mfma_f32_16x16x32_bf16 v[40:43], v[224:227], v[132:135], v[40:43]
	v_mfma_f32_16x16x32_bf16 v[44:47], v[216:219], v[140:143], v[44:47]
	v_mfma_f32_16x16x32_bf16 v[48:51], v[224:227], v[140:143], v[48:51]
	v_mfma_f32_16x16x32_bf16 v[52:55], v[216:219], v[148:151], v[52:55]
	v_mfma_f32_16x16x32_bf16 v[56:59], v[224:227], v[148:151], v[56:59]
	v_mfma_f32_16x16x32_bf16 v[60:63], v[216:219], v[162:165], v[60:63]
	v_mfma_f32_16x16x32_bf16 v[64:67], v[224:227], v[162:165], v[64:67]
	v_mfma_f32_16x16x32_bf16 v[36:39], v[220:223], v[136:139], v[36:39]
	v_mfma_f32_16x16x32_bf16 v[40:43], v[228:231], v[136:139], v[40:43]
	v_mfma_f32_16x16x32_bf16 v[44:47], v[220:223], v[144:147], v[44:47]
	v_mfma_f32_16x16x32_bf16 v[48:51], v[228:231], v[144:147], v[48:51]
	v_mfma_f32_16x16x32_bf16 v[52:55], v[220:223], v[158:161], v[52:55]
	v_mfma_f32_16x16x32_bf16 v[56:59], v[228:231], v[158:161], v[56:59]
	v_mfma_f32_16x16x32_bf16 v[60:63], v[220:223], v[168:171], v[60:63]
	v_mfma_f32_16x16x32_bf16 v[64:67], v[228:231], v[168:171], v[64:67]
	s_setprio 0
	s_barrier
	ds_read_b128 v[132:135], v210 offset:49152
	ds_read_b128 v[136:139], v211 offset:49152
	ds_read_b128 v[140:143], v210 offset:51200
	ds_read_b128 v[144:147], v211 offset:51200
	ds_read_b128 v[148:151], v210 offset:53248
	ds_read_b128 v[158:161], v211 offset:53248
	ds_read_b128 v[162:165], v210 offset:55296
	ds_read_b128 v[168:171], v211 offset:55296
	s_add_i32 m0, s40, 0x8000
	s_nop 0
	global_load_lds_dwordx4 v208, s[68:69]
	global_load_lds_dwordx4 v209, s[70:71] offset:1024
	s_barrier
	s_waitcnt lgkmcnt(0)
	s_setprio 1
	v_mfma_f32_16x16x32_bf16 v[68:71], v[172:175], v[132:135], v[68:71]
	v_mfma_f32_16x16x32_bf16 v[72:75], v[180:183], v[132:135], v[72:75]
	v_mfma_f32_16x16x32_bf16 v[76:79], v[172:175], v[140:143], v[76:79]
	v_mfma_f32_16x16x32_bf16 v[80:83], v[180:183], v[140:143], v[80:83]
	v_mfma_f32_16x16x32_bf16 v[84:87], v[172:175], v[148:151], v[84:87]
	v_mfma_f32_16x16x32_bf16 v[88:91], v[180:183], v[148:151], v[88:91]
	v_mfma_f32_16x16x32_bf16 v[92:95], v[172:175], v[162:165], v[92:95]
	v_mfma_f32_16x16x32_bf16 v[96:99], v[180:183], v[162:165], v[96:99]
	v_mfma_f32_16x16x32_bf16 v[68:71], v[176:179], v[136:139], v[68:71]
	v_mfma_f32_16x16x32_bf16 v[72:75], v[184:187], v[136:139], v[72:75]
	v_mfma_f32_16x16x32_bf16 v[76:79], v[176:179], v[144:147], v[76:79]
	v_mfma_f32_16x16x32_bf16 v[80:83], v[184:187], v[144:147], v[80:83]
	v_mfma_f32_16x16x32_bf16 v[84:87], v[176:179], v[158:161], v[84:87]
	v_mfma_f32_16x16x32_bf16 v[88:91], v[184:187], v[158:161], v[88:91]
	v_mfma_f32_16x16x32_bf16 v[92:95], v[176:179], v[168:171], v[92:95]
	v_mfma_f32_16x16x32_bf16 v[96:99], v[184:187], v[168:171], v[96:99]
	s_setprio 0
	s_barrier
	s_add_i32 m0, s40, 0x1c000
	s_nop 0
	global_load_lds_dwordx4 v208, s[80:81]
	global_load_lds_dwordx4 v209, s[82:83] offset:1024
	s_waitcnt vmcnt(6)
	s_barrier
	s_setprio 1
	v_mfma_f32_16x16x32_bf16 v[100:103], v[216:219], v[132:135], v[100:103]
	v_mfma_f32_16x16x32_bf16 v[104:107], v[224:227], v[132:135], v[104:107]
	v_mfma_f32_16x16x32_bf16 v[108:111], v[216:219], v[140:143], v[108:111]
	v_mfma_f32_16x16x32_bf16 v[112:115], v[224:227], v[140:143], v[112:115]
	v_mfma_f32_16x16x32_bf16 v[116:119], v[216:219], v[148:151], v[116:119]
	v_mfma_f32_16x16x32_bf16 v[120:123], v[224:227], v[148:151], v[120:123]
	v_mfma_f32_16x16x32_bf16 v[124:127], v[216:219], v[162:165], v[124:127]
	v_mfma_f32_16x16x32_bf16 v[128:131], v[224:227], v[162:165], v[128:131]
	v_mfma_f32_16x16x32_bf16 v[100:103], v[220:223], v[136:139], v[100:103]
	v_mfma_f32_16x16x32_bf16 v[104:107], v[228:231], v[136:139], v[104:107]
	v_mfma_f32_16x16x32_bf16 v[108:111], v[220:223], v[144:147], v[108:111]
	v_mfma_f32_16x16x32_bf16 v[112:115], v[228:231], v[144:147], v[112:115]
	v_mfma_f32_16x16x32_bf16 v[116:119], v[220:223], v[158:161], v[116:119]
	v_mfma_f32_16x16x32_bf16 v[120:123], v[228:231], v[158:161], v[120:123]
	v_mfma_f32_16x16x32_bf16 v[124:127], v[220:223], v[168:171], v[124:127]
	v_mfma_f32_16x16x32_bf16 v[128:131], v[228:231], v[168:171], v[128:131]
	s_setprio 0
	s_barrier
; #define MFMA32(a, b, c) __builtin_amdgcn_mfma_f32_32x32x16_bf16((a), (b), (c), 0, 0, 0)
; template <bool SWAP, class Epi>
; DI void gemm_tile(const u16* __restrict__ A, int lda, const u16* __restrict__ Bw, int ldb, int K, char* lds, Epi epi) {
;     ...
;   auto compute = [&](int st) {
;     const char* as = lds + st * GEMM_STAGE;
;     const char* bs = as + 36864;
; #pragma unroll
;     for (int ks = 0; ks < 4; ++ks) {
;       bf16x8 af[2], bfr[2];
; #pragma unroll
;       for (int mi = 0; mi < 2; ++mi) af[mi] = *(const bf16x8*)(as + ((wm * 64 + mi * 32 + r) * 72 + ks * 16 + 8 * h) * 2);
; #pragma unroll
;       for (int ni = 0; ni < 2; ++ni) bfr[ni] = *(const bf16x8*)(bs + ((wn * 64 + ni * 32 + r) * 72 + ks * 16 + 8 * h) * 2);
; #pragma unroll
;       for (int mi = 0; mi < 2; ++mi)
; #pragma unroll
;         for (int ni = 0; ni < 2; ++ni) {
;           if (SWAP) acc[mi][ni] = MFMA32(bfr[ni], af[mi], acc[mi][ni]);
;           else acc[mi][ni] = MFMA32(af[mi], bfr[ni], acc[mi][ni]);
;         }
;     }
;   };
;   gload(0, ra0, rb0);
;   lstore(0, ra0, rb0);
;   gload(1, ra1, rb1);
;   __syncthreads();
;   for (int kt = 0; kt < nk; kt += 2) {
;     if (kt + 2 < nk) gload(kt + 2, ra0, rb0);
;     compute(0);
;     lstore(1, ra1, rb1);
;     __syncthreads();
;     if (kt + 3 < nk) gload(kt + 3, ra1, rb1);
;     compute(1);
;     if (kt + 2 < nk) lstore(0, ra0, rb0);
;     __syncthreads();
	ds_read_b128 v[172:175], v212 offset:0
	ds_read_b128 v[176:179], v213 offset:0
	ds_read_b128 v[180:183], v212 offset:2048
	ds_read_b128 v[184:187], v213 offset:2048
	ds_read_b128 v[132:135], v210 offset:0
	ds_read_b128 v[136:139], v211 offset:0
	ds_read_b128 v[140:143], v210 offset:2048
	ds_read_b128 v[144:147], v211 offset:2048
	ds_read_b128 v[148:151], v210 offset:4096
	ds_read_b128 v[158:161], v211 offset:4096
	ds_read_b128 v[162:165], v210 offset:6144
	ds_read_b128 v[168:171], v211 offset:6144
	s_add_i32 m0, s40, 0xc000
	s_nop 0
	global_load_lds_dwordx4 v208, s[72:73]
	global_load_lds_dwordx4 v209, s[74:75] offset:1024
	s_waitcnt lgkmcnt(8)
	s_barrier
	s_waitcnt lgkmcnt(0)
	s_setprio 1
	v_mfma_f32_16x16x32_bf16 v[4:7], v[172:175], v[132:135], v[4:7]
	v_mfma_f32_16x16x32_bf16 v[8:11], v[180:183], v[132:135], v[8:11]
	v_mfma_f32_16x16x32_bf16 v[12:15], v[172:175], v[140:143], v[12:15]
	v_mfma_f32_16x16x32_bf16 v[16:19], v[180:183], v[140:143], v[16:19]
	v_mfma_f32_16x16x32_bf16 v[20:23], v[172:175], v[148:151], v[20:23]
	v_mfma_f32_16x16x32_bf16 v[24:27], v[180:183], v[148:151], v[24:27]
	v_mfma_f32_16x16x32_bf16 v[28:31], v[172:175], v[162:165], v[28:31]
	v_mfma_f32_16x16x32_bf16 v[32:35], v[180:183], v[162:165], v[32:35]
	v_mfma_f32_16x16x32_bf16 v[4:7], v[176:179], v[136:139], v[4:7]
	v_mfma_f32_16x16x32_bf16 v[8:11], v[184:187], v[136:139], v[8:11]
	v_mfma_f32_16x16x32_bf16 v[12:15], v[176:179], v[144:147], v[12:15]
	v_mfma_f32_16x16x32_bf16 v[16:19], v[184:187], v[144:147], v[16:19]
	v_mfma_f32_16x16x32_bf16 v[20:23], v[176:179], v[158:161], v[20:23]
	v_mfma_f32_16x16x32_bf16 v[24:27], v[184:187], v[158:161], v[24:27]
	v_mfma_f32_16x16x32_bf16 v[28:31], v[176:179], v[168:171], v[28:31]
	v_mfma_f32_16x16x32_bf16 v[32:35], v[184:187], v[168:171], v[32:35]
	s_setprio 0
	s_barrier
	ds_read_b128 v[216:219], v212 offset:16384
	ds_read_b128 v[220:223], v213 offset:16384
	ds_read_b128 v[224:227], v212 offset:18432
	ds_read_b128 v[228:231], v213 offset:18432
	v_add_u32_e32 v208, 0x80, v208
	v_add_u32_e32 v209, 0x80, v209
	s_add_i32 m0, s40, 0x10000
	s_nop 0
	global_load_lds_dwordx4 v208, s[76:77]
	global_load_lds_dwordx4 v209, s[78:79] offset:1024
	s_barrier
	s_waitcnt lgkmcnt(0)
	s_setprio 1
	v_mfma_f32_16x16x32_bf16 v[36:39], v[216:219], v[132:135], v[36:39]
	v_mfma_f32_16x16x32_bf16 v[40:43], v[224:227], v[132:135], v[40:43]
	v_mfma_f32_16x16x32_bf16 v[44:47], v[216:219], v[140:143], v[44:47]
	v_mfma_f32_16x16x32_bf16 v[48:51], v[224:227], v[140:143], v[48:51]
	v_mfma_f32_16x16x32_bf16 v[52:55], v[216:219], v[148:151], v[52:55]
	v_mfma_f32_16x16x32_bf16 v[56:59], v[224:227], v[148:151], v[56:59]
	v_mfma_f32_16x16x32_bf16 v[60:63], v[216:219], v[162:165], v[60:63]
	v_mfma_f32_16x16x32_bf16 v[64:67], v[224:227], v[162:165], v[64:67]
	v_mfma_f32_16x16x32_bf16 v[36:39], v[220:223], v[136:139], v[36:39]
	v_mfma_f32_16x16x32_bf16 v[40:43], v[228:231], v[136:139], v[40:43]
	v_mfma_f32_16x16x32_bf16 v[44:47], v[220:223], v[144:147], v[44:47]
	v_mfma_f32_16x16x32_bf16 v[48:51], v[228:231], v[144:147], v[48:51]
	v_mfma_f32_16x16x32_bf16 v[52:55], v[220:223], v[158:161], v[52:55]
	v_mfma_f32_16x16x32_bf16 v[56:59], v[228:231], v[158:161], v[56:59]
	v_mfma_f32_16x16x32_bf16 v[60:63], v[220:223], v[168:171], v[60:63]
	v_mfma_f32_16x16x32_bf16 v[64:67], v[228:231], v[168:171], v[64:67]
	s_setprio 0
	s_barrier
	ds_read_b128 v[132:135], v210 offset:16384
	ds_read_b128 v[136:139], v211 offset:16384
	ds_read_b128 v[140:143], v210 offset:18432
	ds_read_b128 v[144:147], v211 offset:18432
	ds_read_b128 v[148:151], v210 offset:20480
	ds_read_b128 v[158:161], v211 offset:20480
	ds_read_b128 v[162:165], v210 offset:22528
	ds_read_b128 v[168:171], v211 offset:22528
	s_add_i32 m0, s40, 0x0
	s_nop 0
	global_load_lds_dwordx4 v208, s[68:69]
	global_load_lds_dwordx4 v209, s[70:71] offset:1024
	s_barrier
	s_waitcnt lgkmcnt(0)
	s_setprio 1
	v_mfma_f32_16x16x32_bf16 v[68:71], v[172:175], v[132:135], v[68:71]
	v_mfma_f32_16x16x32_bf16 v[72:75], v[180:183], v[132:135], v[72:75]
	v_mfma_f32_16x16x32_bf16 v[76:79], v[172:175], v[140:143], v[76:79]
	v_mfma_f32_16x16x32_bf16 v[80:83], v[180:183], v[140:143], v[80:83]
	v_mfma_f32_16x16x32_bf16 v[84:87], v[172:175], v[148:151], v[84:87]
	v_mfma_f32_16x16x32_bf16 v[88:91], v[180:183], v[148:151], v[88:91]
	v_mfma_f32_16x16x32_bf16 v[92:95], v[172:175], v[162:165], v[92:95]
	v_mfma_f32_16x16x32_bf16 v[96:99], v[180:183], v[162:165], v[96:99]
	v_mfma_f32_16x16x32_bf16 v[68:71], v[176:179], v[136:139], v[68:71]
	v_mfma_f32_16x16x32_bf16 v[72:75], v[184:187], v[136:139], v[72:75]
	v_mfma_f32_16x16x32_bf16 v[76:79], v[176:179], v[144:147], v[76:79]
	v_mfma_f32_16x16x32_bf16 v[80:83], v[184:187], v[144:147], v[80:83]
	v_mfma_f32_16x16x32_bf16 v[84:87], v[176:179], v[158:161], v[84:87]
	v_mfma_f32_16x16x32_bf16 v[88:91], v[184:187], v[158:161], v[88:91]
	v_mfma_f32_16x16x32_bf16 v[92:95], v[176:179], v[168:171], v[92:95]
	v_mfma_f32_16x16x32_bf16 v[96:99], v[184:187], v[168:171], v[96:99]
	s_setprio 0
	s_barrier
	s_add_i32 m0, s40, 0x14000
	s_nop 0
	global_load_lds_dwordx4 v208, s[80:81]
	global_load_lds_dwordx4 v209, s[82:83] offset:1024
	s_waitcnt vmcnt(6)
	s_barrier
; #define MFMA32(a, b, c) __builtin_amdgcn_mfma_f32_32x32x16_bf16((a), (b), (c), 0, 0, 0)
; template <bool SWAP, class Epi>
; DI void gemm_tile(const u16* __restrict__ A, int lda, const u16* __restrict__ Bw, int ldb, int K, char* lds, Epi epi) {
;     ...
;   auto compute = [&](int st) {
;     const char* as = lds + st * GEMM_STAGE;
;     const char* bs = as + 36864;
; #pragma unroll
;     for (int ks = 0; ks < 4; ++ks) {
;       bf16x8 af[2], bfr[2];
; #pragma unroll
;       for (int mi = 0; mi < 2; ++mi) af[mi] = *(const bf16x8*)(as + ((wm * 64 + mi * 32 + r) * 72 + ks * 16 + 8 * h) * 2);
; #pragma unroll
;       for (int ni = 0; ni < 2; ++ni) bfr[ni] = *(const bf16x8*)(bs + ((wn * 64 + ni * 32 + r) * 72 + ks * 16 + 8 * h) * 2);
; #pragma unroll
;       for (int mi = 0; mi < 2; ++mi)
; #pragma unroll
;         for (int ni = 0; ni < 2; ++ni) {
;           if (SWAP) acc[mi][ni] = MFMA32(bfr[ni], af[mi], acc[mi][ni]);
;           else acc[mi][ni] = MFMA32(af[mi], bfr[ni], acc[mi][ni]);
;         }
;     }
;   };
;   gload(0, ra0, rb0);
;   lstore(0, ra0, rb0);
;   gload(1, ra1, rb1);
;   __syncthreads();
;   for (int kt = 0; kt < nk; kt += 2) {
;     if (kt + 2 < nk) gload(kt + 2, ra0, rb0);
;     compute(0);
;     lstore(1, ra1, rb1);
;     __syncthreads();
;     if (kt + 3 < nk) gload(kt + 3, ra1, rb1);
;     compute(1);
;     if (kt + 2 < nk) lstore(0, ra0, rb0);
;     __syncthreads();
	s_setprio 1
	v_mfma_f32_16x16x32_bf16 v[100:103], v[216:219], v[132:135], v[100:103]
	v_mfma_f32_16x16x32_bf16 v[104:107], v[224:227], v[132:135], v[104:107]
	v_mfma_f32_16x16x32_bf16 v[108:111], v[216:219], v[140:143], v[108:111]
	v_mfma_f32_16x16x32_bf16 v[112:115], v[224:227], v[140:143], v[112:115]
	v_mfma_f32_16x16x32_bf16 v[116:119], v[216:219], v[148:151], v[116:119]
	v_mfma_f32_16x16x32_bf16 v[120:123], v[224:227], v[148:151], v[120:123]
	v_mfma_f32_16x16x32_bf16 v[124:127], v[216:219], v[162:165], v[124:127]
	v_mfma_f32_16x16x32_bf16 v[128:131], v[224:227], v[162:165], v[128:131]
	v_mfma_f32_16x16x32_bf16 v[100:103], v[220:223], v[136:139], v[100:103]
	v_mfma_f32_16x16x32_bf16 v[104:107], v[228:231], v[136:139], v[104:107]
	v_mfma_f32_16x16x32_bf16 v[108:111], v[220:223], v[144:147], v[108:111]
	v_mfma_f32_16x16x32_bf16 v[112:115], v[228:231], v[144:147], v[112:115]
	v_mfma_f32_16x16x32_bf16 v[116:119], v[220:223], v[158:161], v[116:119]
	v_mfma_f32_16x16x32_bf16 v[120:123], v[228:231], v[158:161], v[120:123]
	v_mfma_f32_16x16x32_bf16 v[124:127], v[220:223], v[168:171], v[124:127]
	v_mfma_f32_16x16x32_bf16 v[128:131], v[228:231], v[168:171], v[128:131]
	s_setprio 0
	s_barrier
	ds_read_b128 v[172:175], v212 offset:32768
	ds_read_b128 v[176:179], v213 offset:32768
	ds_read_b128 v[180:183], v212 offset:34816
	ds_read_b128 v[184:187], v213 offset:34816
	ds_read_b128 v[132:135], v210 offset:32768
	ds_read_b128 v[136:139], v211 offset:32768
	ds_read_b128 v[140:143], v210 offset:34816
	ds_read_b128 v[144:147], v211 offset:34816
	ds_read_b128 v[148:151], v210 offset:36864
	ds_read_b128 v[158:161], v211 offset:36864
	ds_read_b128 v[162:165], v210 offset:38912
	ds_read_b128 v[168:171], v211 offset:38912
	s_add_i32 m0, s40, 0x4000
	s_nop 0
	global_load_lds_dwordx4 v208, s[72:73]
	global_load_lds_dwordx4 v209, s[74:75] offset:1024
	s_waitcnt lgkmcnt(8)
	s_barrier
	s_waitcnt lgkmcnt(0)
	s_setprio 1
	v_mfma_f32_16x16x32_bf16 v[4:7], v[172:175], v[132:135], v[4:7]
	v_mfma_f32_16x16x32_bf16 v[8:11], v[180:183], v[132:135], v[8:11]
	v_mfma_f32_16x16x32_bf16 v[12:15], v[172:175], v[140:143], v[12:15]
	v_mfma_f32_16x16x32_bf16 v[16:19], v[180:183], v[140:143], v[16:19]
	v_mfma_f32_16x16x32_bf16 v[20:23], v[172:175], v[148:151], v[20:23]
	v_mfma_f32_16x16x32_bf16 v[24:27], v[180:183], v[148:151], v[24:27]
	v_mfma_f32_16x16x32_bf16 v[28:31], v[172:175], v[162:165], v[28:31]
	v_mfma_f32_16x16x32_bf16 v[32:35], v[180:183], v[162:165], v[32:35]
	v_mfma_f32_16x16x32_bf16 v[4:7], v[176:179], v[136:139], v[4:7]
	v_mfma_f32_16x16x32_bf16 v[8:11], v[184:187], v[136:139], v[8:11]
	v_mfma_f32_16x16x32_bf16 v[12:15], v[176:179], v[144:147], v[12:15]
	v_mfma_f32_16x16x32_bf16 v[16:19], v[184:187], v[144:147], v[16:19]
	v_mfma_f32_16x16x32_bf16 v[20:23], v[176:179], v[158:161], v[20:23]
	v_mfma_f32_16x16x32_bf16 v[24:27], v[184:187], v[158:161], v[24:27]
	v_mfma_f32_16x16x32_bf16 v[28:31], v[176:179], v[168:171], v[28:31]
	v_mfma_f32_16x16x32_bf16 v[32:35], v[184:187], v[168:171], v[32:35]
	s_setprio 0
	s_barrier
	ds_read_b128 v[216:219], v212 offset:49152
	ds_read_b128 v[220:223], v213 offset:49152
	ds_read_b128 v[224:227], v212 offset:51200
	ds_read_b128 v[228:231], v213 offset:51200
	v_add_u32_e32 v208, 0x80, v208
	v_add_u32_e32 v209, 0x80, v209
	s_add_i32 m0, s40, 0x18000
	s_nop 0
	global_load_lds_dwordx4 v208, s[76:77]
	global_load_lds_dwordx4 v209, s[78:79] offset:1024
	s_barrier
	s_waitcnt lgkmcnt(0)
	s_setprio 1
	v_mfma_f32_16x16x32_bf16 v[36:39], v[216:219], v[132:135], v[36:39]
	v_mfma_f32_16x16x32_bf16 v[40:43], v[224:227], v[132:135], v[40:43]
	v_mfma_f32_16x16x32_bf16 v[44:47], v[216:219], v[140:143], v[44:47]
	v_mfma_f32_16x16x32_bf16 v[48:51], v[224:227], v[140:143], v[48:51]
	v_mfma_f32_16x16x32_bf16 v[52:55], v[216:219], v[148:151], v[52:55]
	v_mfma_f32_16x16x32_bf16 v[56:59], v[224:227], v[148:151], v[56:59]
	v_mfma_f32_16x16x32_bf16 v[60:63], v[216:219], v[162:165], v[60:63]
	v_mfma_f32_16x16x32_bf16 v[64:67], v[224:227], v[162:165], v[64:67]
	v_mfma_f32_16x16x32_bf16 v[36:39], v[220:223], v[136:139], v[36:39]
	v_mfma_f32_16x16x32_bf16 v[40:43], v[228:231], v[136:139], v[40:43]
	v_mfma_f32_16x16x32_bf16 v[44:47], v[220:223], v[144:147], v[44:47]
	v_mfma_f32_16x16x32_bf16 v[48:51], v[228:231], v[144:147], v[48:51]
	v_mfma_f32_16x16x32_bf16 v[52:55], v[220:223], v[158:161], v[52:55]
	v_mfma_f32_16x16x32_bf16 v[56:59], v[228:231], v[158:161], v[56:59]
	v_mfma_f32_16x16x32_bf16 v[60:63], v[220:223], v[168:171], v[60:63]
	v_mfma_f32_16x16x32_bf16 v[64:67], v[228:231], v[168:171], v[64:67]
	s_setprio 0
	s_barrier
	ds_read_b128 v[132:135], v210 offset:49152
	ds_read_b128 v[136:139], v211 offset:49152
	ds_read_b128 v[140:143], v210 offset:51200
	ds_read_b128 v[144:147], v211 offset:51200
	ds_read_b128 v[148:151], v210 offset:53248
	ds_read_b128 v[158:161], v211 offset:53248
	ds_read_b128 v[162:165], v210 offset:55296
	ds_read_b128 v[168:171], v211 offset:55296
	s_add_i32 m0, s40, 0x8000
	s_nop 0
	global_load_lds_dwordx4 v208, s[68:69]
	global_load_lds_dwordx4 v209, s[70:71] offset:1024
	s_barrier
; #define MFMA32(a, b, c) __builtin_amdgcn_mfma_f32_32x32x16_bf16((a), (b), (c), 0, 0, 0)
; template <bool SWAP, class Epi>
; DI void gemm_tile(const u16* __restrict__ A, int lda, const u16* __restrict__ Bw, int ldb, int K, char* lds, Epi epi) {
;     ...
;   auto compute = [&](int st) {
;     const char* as = lds + st * GEMM_STAGE;
;     const char* bs = as + 36864;
; #pragma unroll
;     for (int ks = 0; ks < 4; ++ks) {
;       bf16x8 af[2], bfr[2];
; #pragma unroll
;       for (int mi = 0; mi < 2; ++mi) af[mi] = *(const bf16x8*)(as + ((wm * 64 + mi * 32 + r) * 72 + ks * 16 + 8 * h) * 2);
; #pragma unroll
;       for (int ni = 0; ni < 2; ++ni) bfr[ni] = *(const bf16x8*)(bs + ((wn * 64 + ni * 32 + r) * 72 + ks * 16 + 8 * h) * 2);
; #pragma unroll
;       for (int mi = 0; mi < 2; ++mi)
; #pragma unroll
;         for (int ni = 0; ni < 2; ++ni) {
;           if (SWAP) acc[mi][ni] = MFMA32(bfr[ni], af[mi], acc[mi][ni]);
;           else acc[mi][ni] = MFMA32(af[mi], bfr[ni], acc[mi][ni]);
;         }
;     }
;   };
;   gload(0, ra0, rb0);
;   lstore(0, ra0, rb0);
;   gload(1, ra1, rb1);
;   __syncthreads();
;   for (int kt = 0; kt < nk; kt += 2) {
;     if (kt + 2 < nk) gload(kt + 2, ra0, rb0);
;     compute(0);
;     lstore(1, ra1, rb1);
;     __syncthreads();
;     if (kt + 3 < nk) gload(kt + 3, ra1, rb1);
;     compute(1);
;     if (kt + 2 < nk) lstore(0, ra0, rb0);
;     __syncthreads();
	s_waitcnt lgkmcnt(0)
	s_setprio 1
	v_mfma_f32_16x16x32_bf16 v[68:71], v[172:175], v[132:135], v[68:71]
	v_mfma_f32_16x16x32_bf16 v[72:75], v[180:183], v[132:135], v[72:75]
	v_mfma_f32_16x16x32_bf16 v[76:79], v[172:175], v[140:143], v[76:79]
	v_mfma_f32_16x16x32_bf16 v[80:83], v[180:183], v[140:143], v[80:83]
	v_mfma_f32_16x16x32_bf16 v[84:87], v[172:175], v[148:151], v[84:87]
	v_mfma_f32_16x16x32_bf16 v[88:91], v[180:183], v[148:151], v[88:91]
	v_mfma_f32_16x16x32_bf16 v[92:95], v[172:175], v[162:165], v[92:95]
	v_mfma_f32_16x16x32_bf16 v[96:99], v[180:183], v[162:165], v[96:99]
	v_mfma_f32_16x16x32_bf16 v[68:71], v[176:179], v[136:139], v[68:71]
	v_mfma_f32_16x16x32_bf16 v[72:75], v[184:187], v[136:139], v[72:75]
	v_mfma_f32_16x16x32_bf16 v[76:79], v[176:179], v[144:147], v[76:79]
	v_mfma_f32_16x16x32_bf16 v[80:83], v[184:187], v[144:147], v[80:83]
	v_mfma_f32_16x16x32_bf16 v[84:87], v[176:179], v[158:161], v[84:87]
	v_mfma_f32_16x16x32_bf16 v[88:91], v[184:187], v[158:161], v[88:91]
	v_mfma_f32_16x16x32_bf16 v[92:95], v[176:179], v[168:171], v[92:95]
	v_mfma_f32_16x16x32_bf16 v[96:99], v[184:187], v[168:171], v[96:99]
	s_setprio 0
	s_barrier
	s_add_i32 m0, s40, 0x1c000
	s_nop 0
	global_load_lds_dwordx4 v208, s[80:81]
	global_load_lds_dwordx4 v209, s[82:83] offset:1024
	s_waitcnt vmcnt(6)
	s_barrier
	s_setprio 1
	v_mfma_f32_16x16x32_bf16 v[100:103], v[216:219], v[132:135], v[100:103]
	v_mfma_f32_16x16x32_bf16 v[104:107], v[224:227], v[132:135], v[104:107]
	v_mfma_f32_16x16x32_bf16 v[108:111], v[216:219], v[140:143], v[108:111]
	v_mfma_f32_16x16x32_bf16 v[112:115], v[224:227], v[140:143], v[112:115]
	v_mfma_f32_16x16x32_bf16 v[116:119], v[216:219], v[148:151], v[116:119]
	v_mfma_f32_16x16x32_bf16 v[120:123], v[224:227], v[148:151], v[120:123]
	v_mfma_f32_16x16x32_bf16 v[124:127], v[216:219], v[162:165], v[124:127]
	v_mfma_f32_16x16x32_bf16 v[128:131], v[224:227], v[162:165], v[128:131]
	v_mfma_f32_16x16x32_bf16 v[100:103], v[220:223], v[136:139], v[100:103]
	v_mfma_f32_16x16x32_bf16 v[104:107], v[228:231], v[136:139], v[104:107]
	v_mfma_f32_16x16x32_bf16 v[108:111], v[220:223], v[144:147], v[108:111]
	v_mfma_f32_16x16x32_bf16 v[112:115], v[228:231], v[144:147], v[112:115]
	v_mfma_f32_16x16x32_bf16 v[116:119], v[220:223], v[158:161], v[116:119]
	v_mfma_f32_16x16x32_bf16 v[120:123], v[228:231], v[158:161], v[120:123]
	v_mfma_f32_16x16x32_bf16 v[124:127], v[220:223], v[168:171], v[124:127]
	v_mfma_f32_16x16x32_bf16 v[128:131], v[228:231], v[168:171], v[128:131]
	s_setprio 0
	s_barrier
	ds_read_b128 v[172:175], v212 offset:0
	ds_read_b128 v[176:179], v213 offset:0
	ds_read_b128 v[180:183], v212 offset:2048
	ds_read_b128 v[184:187], v213 offset:2048
	ds_read_b128 v[132:135], v210 offset:0
	ds_read_b128 v[136:139], v211 offset:0
	ds_read_b128 v[140:143], v210 offset:2048
	ds_read_b128 v[144:147], v211 offset:2048
	ds_read_b128 v[148:151], v210 offset:4096
	ds_read_b128 v[158:161], v211 offset:4096
	ds_read_b128 v[162:165], v210 offset:6144
	ds_read_b128 v[168:171], v211 offset:6144
	s_add_i32 m0, s40, 0xc000
	s_nop 0
	global_load_lds_dwordx4 v208, s[72:73]
	global_load_lds_dwordx4 v209, s[74:75] offset:1024
	s_waitcnt lgkmcnt(8)
	s_barrier
	s_waitcnt lgkmcnt(0)
	s_setprio 1
	v_mfma_f32_16x16x32_bf16 v[4:7], v[172:175], v[132:135], v[4:7]
	v_mfma_f32_16x16x32_bf16 v[8:11], v[180:183], v[132:135], v[8:11]
	v_mfma_f32_16x16x32_bf16 v[12:15], v[172:175], v[140:143], v[12:15]
	v_mfma_f32_16x16x32_bf16 v[16:19], v[180:183], v[140:143], v[16:19]
	v_mfma_f32_16x16x32_bf16 v[20:23], v[172:175], v[148:151], v[20:23]
	v_mfma_f32_16x16x32_bf16 v[24:27], v[180:183], v[148:151], v[24:27]
	v_mfma_f32_16x16x32_bf16 v[28:31], v[172:175], v[162:165], v[28:31]
	v_mfma_f32_16x16x32_bf16 v[32:35], v[180:183], v[162:165], v[32:35]
	v_mfma_f32_16x16x32_bf16 v[4:7], v[176:179], v[136:139], v[4:7]
	v_mfma_f32_16x16x32_bf16 v[8:11], v[184:187], v[136:139], v[8:11]
	v_mfma_f32_16x16x32_bf16 v[12:15], v[176:179], v[144:147], v[12:15]
	v_mfma_f32_16x16x32_bf16 v[16:19], v[184:187], v[144:147], v[16:19]
	v_mfma_f32_16x16x32_bf16 v[20:23], v[176:179], v[158:161], v[20:23]
	v_mfma_f32_16x16x32_bf16 v[24:27], v[184:187], v[158:161], v[24:27]
	v_mfma_f32_16x16x32_bf16 v[28:31], v[176:179], v[168:171], v[28:31]
	v_mfma_f32_16x16x32_bf16 v[32:35], v[184:187], v[168:171], v[32:35]
	s_setprio 0
	s_barrier
	ds_read_b128 v[216:219], v212 offset:16384
	ds_read_b128 v[220:223], v213 offset:16384
	ds_read_b128 v[224:227], v212 offset:18432
	ds_read_b128 v[228:231], v213 offset:18432
	v_add_u32_e32 v208, 0x80, v208
	v_add_u32_e32 v209, 0x80, v209
	s_add_i32 m0, s40, 0x10000
	s_nop 0
	global_load_lds_dwordx4 v208, s[76:77]
	global_load_lds_dwordx4 v209, s[78:79] offset:1024
	s_barrier
	s_waitcnt lgkmcnt(0)
	s_setprio 1
	v_mfma_f32_16x16x32_bf16 v[36:39], v[216:219], v[132:135], v[36:39]
	v_mfma_f32_16x16x32_bf16 v[40:43], v[224:227], v[132:135], v[40:43]
	v_mfma_f32_16x16x32_bf16 v[44:47], v[216:219], v[140:143], v[44:47]
	v_mfma_f32_16x16x32_bf16 v[48:51], v[224:227], v[140:143], v[48:51]
	v_mfma_f32_16x16x32_bf16 v[52:55], v[216:219], v[148:151], v[52:55]
	v_mfma_f32_16x16x32_bf16 v[56:59], v[224:227], v[148:151], v[56:59]
	v_mfma_f32_16x16x32_bf16 v[60:63], v[216:219], v[162:165], v[60:63]
	v_mfma_f32_16x16x32_bf16 v[64:67], v[224:227], v[162:165], v[64:67]
	v_mfma_f32_16x16x32_bf16 v[36:39], v[220:223], v[136:139], v[36:39]
	v_mfma_f32_16x16x32_bf16 v[40:43], v[228:231], v[136:139], v[40:43]
	v_mfma_f32_16x16x32_bf16 v[44:47], v[220:223], v[144:147], v[44:47]
	v_mfma_f32_16x16x32_bf16 v[48:51], v[228:231], v[144:147], v[48:51]
	v_mfma_f32_16x16x32_bf16 v[52:55], v[220:223], v[158:161], v[52:55]
	v_mfma_f32_16x16x32_bf16 v[56:59], v[228:231], v[158:161], v[56:59]
	v_mfma_f32_16x16x32_bf16 v[60:63], v[220:223], v[168:171], v[60:63]
	v_mfma_f32_16x16x32_bf16 v[64:67], v[228:231], v[168:171], v[64:67]
	s_setprio 0
	s_barrier
; #define MFMA32(a, b, c) __builtin_amdgcn_mfma_f32_32x32x16_bf16((a), (b), (c), 0, 0, 0)
; template <bool SWAP, class Epi>
; DI void gemm_tile(const u16* __restrict__ A, int lda, const u16* __restrict__ Bw, int ldb, int K, char* lds, Epi epi) {
;     ...
;   auto compute = [&](int st) {
;     const char* as = lds + st * GEMM_STAGE;
;     const char* bs = as + 36864;
; #pragma unroll
;     for (int ks = 0; ks < 4; ++ks) {
;       bf16x8 af[2], bfr[2];
; #pragma unroll
;       for (int mi = 0; mi < 2; ++mi) af[mi] = *(const bf16x8*)(as + ((wm * 64 + mi * 32 + r) * 72 + ks * 16 + 8 * h) * 2);
; #pragma unroll
;       for (int ni = 0; ni < 2; ++ni) bfr[ni] = *(const bf16x8*)(bs + ((wn * 64 + ni * 32 + r) * 72 + ks * 16 + 8 * h) * 2);
; #pragma unroll
;       for (int mi = 0; mi < 2; ++mi)
; #pragma unroll
;         for (int ni = 0; ni < 2; ++ni) {
;           if (SWAP) acc[mi][ni] = MFMA32(bfr[ni], af[mi], acc[mi][ni]);
;           else acc[mi][ni] = MFMA32(af[mi], bfr[ni], acc[mi][ni]);
;         }
;     }
;   };
;   gload(0, ra0, rb0);
;   lstore(0, ra0, rb0);
;   gload(1, ra1, rb1);
;   __syncthreads();
;   for (int kt = 0; kt < nk; kt += 2) {
;     if (kt + 2 < nk) gload(kt + 2, ra0, rb0);
;     compute(0);
;     lstore(1, ra1, rb1);
;     __syncthreads();
;     if (kt + 3 < nk) gload(kt + 3, ra1, rb1);
;     compute(1);
;     if (kt + 2 < nk) lstore(0, ra0, rb0);
;     __syncthreads();
	ds_read_b128 v[132:135], v210 offset:16384
	ds_read_b128 v[136:139], v211 offset:16384
	ds_read_b128 v[140:143], v210 offset:18432
	ds_read_b128 v[144:147], v211 offset:18432
	ds_read_b128 v[148:151], v210 offset:20480
	ds_read_b128 v[158:161], v211 offset:20480
	ds_read_b128 v[162:165], v210 offset:22528
	ds_read_b128 v[168:171], v211 offset:22528
	s_add_i32 m0, s40, 0x0
	s_nop 0
	global_load_lds_dwordx4 v208, s[68:69]
	global_load_lds_dwordx4 v209, s[70:71] offset:1024
	s_barrier
	s_waitcnt lgkmcnt(0)
	s_setprio 1
	v_mfma_f32_16x16x32_bf16 v[68:71], v[172:175], v[132:135], v[68:71]
	v_mfma_f32_16x16x32_bf16 v[72:75], v[180:183], v[132:135], v[72:75]
	v_mfma_f32_16x16x32_bf16 v[76:79], v[172:175], v[140:143], v[76:79]
	v_mfma_f32_16x16x32_bf16 v[80:83], v[180:183], v[140:143], v[80:83]
	v_mfma_f32_16x16x32_bf16 v[84:87], v[172:175], v[148:151], v[84:87]
	v_mfma_f32_16x16x32_bf16 v[88:91], v[180:183], v[148:151], v[88:91]
	v_mfma_f32_16x16x32_bf16 v[92:95], v[172:175], v[162:165], v[92:95]
	v_mfma_f32_16x16x32_bf16 v[96:99], v[180:183], v[162:165], v[96:99]
	v_mfma_f32_16x16x32_bf16 v[68:71], v[176:179], v[136:139], v[68:71]
	v_mfma_f32_16x16x32_bf16 v[72:75], v[184:187], v[136:139], v[72:75]
	v_mfma_f32_16x16x32_bf16 v[76:79], v[176:179], v[144:147], v[76:79]
	v_mfma_f32_16x16x32_bf16 v[80:83], v[184:187], v[144:147], v[80:83]
	v_mfma_f32_16x16x32_bf16 v[84:87], v[176:179], v[158:161], v[84:87]
	v_mfma_f32_16x16x32_bf16 v[88:91], v[184:187], v[158:161], v[88:91]
	v_mfma_f32_16x16x32_bf16 v[92:95], v[176:179], v[168:171], v[92:95]
	v_mfma_f32_16x16x32_bf16 v[96:99], v[184:187], v[168:171], v[96:99]
	s_setprio 0
	s_barrier
	s_add_i32 m0, s40, 0x14000
	s_nop 0
	global_load_lds_dwordx4 v208, s[80:81]
	global_load_lds_dwordx4 v209, s[82:83] offset:1024
	s_waitcnt vmcnt(6)
	s_barrier
	s_setprio 1
	v_mfma_f32_16x16x32_bf16 v[100:103], v[216:219], v[132:135], v[100:103]
	v_mfma_f32_16x16x32_bf16 v[104:107], v[224:227], v[132:135], v[104:107]
	v_mfma_f32_16x16x32_bf16 v[108:111], v[216:219], v[140:143], v[108:111]
	v_mfma_f32_16x16x32_bf16 v[112:115], v[224:227], v[140:143], v[112:115]
	v_mfma_f32_16x16x32_bf16 v[116:119], v[216:219], v[148:151], v[116:119]
	v_mfma_f32_16x16x32_bf16 v[120:123], v[224:227], v[148:151], v[120:123]
	v_mfma_f32_16x16x32_bf16 v[124:127], v[216:219], v[162:165], v[124:127]
	v_mfma_f32_16x16x32_bf16 v[128:131], v[224:227], v[162:165], v[128:131]
	v_mfma_f32_16x16x32_bf16 v[100:103], v[220:223], v[136:139], v[100:103]
	v_mfma_f32_16x16x32_bf16 v[104:107], v[228:231], v[136:139], v[104:107]
	v_mfma_f32_16x16x32_bf16 v[108:111], v[220:223], v[144:147], v[108:111]
	v_mfma_f32_16x16x32_bf16 v[112:115], v[228:231], v[144:147], v[112:115]
	v_mfma_f32_16x16x32_bf16 v[116:119], v[220:223], v[158:161], v[116:119]
	v_mfma_f32_16x16x32_bf16 v[120:123], v[228:231], v[158:161], v[120:123]
	v_mfma_f32_16x16x32_bf16 v[124:127], v[220:223], v[168:171], v[124:127]
	v_mfma_f32_16x16x32_bf16 v[128:131], v[228:231], v[168:171], v[128:131]
	s_setprio 0
	s_barrier
	ds_read_b128 v[172:175], v212 offset:32768
	ds_read_b128 v[176:179], v213 offset:32768
	ds_read_b128 v[180:183], v212 offset:34816
	ds_read_b128 v[184:187], v213 offset:34816
	ds_read_b128 v[132:135], v210 offset:32768
	ds_read_b128 v[136:139], v211 offset:32768
	ds_read_b128 v[140:143], v210 offset:34816
	ds_read_b128 v[144:147], v211 offset:34816
	ds_read_b128 v[148:151], v210 offset:36864
	ds_read_b128 v[158:161], v211 offset:36864
	ds_read_b128 v[162:165], v210 offset:38912
	ds_read_b128 v[168:171], v211 offset:38912
	s_add_i32 m0, s40, 0x4000
	s_nop 0
	global_load_lds_dwordx4 v208, s[72:73]
	global_load_lds_dwordx4 v209, s[74:75] offset:1024
	s_waitcnt lgkmcnt(8)
	s_barrier
	s_waitcnt lgkmcnt(0)
	s_setprio 1
	v_mfma_f32_16x16x32_bf16 v[4:7], v[172:175], v[132:135], v[4:7]
	v_mfma_f32_16x16x32_bf16 v[8:11], v[180:183], v[132:135], v[8:11]
	v_mfma_f32_16x16x32_bf16 v[12:15], v[172:175], v[140:143], v[12:15]
	v_mfma_f32_16x16x32_bf16 v[16:19], v[180:183], v[140:143], v[16:19]
	v_mfma_f32_16x16x32_bf16 v[20:23], v[172:175], v[148:151], v[20:23]
	v_mfma_f32_16x16x32_bf16 v[24:27], v[180:183], v[148:151], v[24:27]
	v_mfma_f32_16x16x32_bf16 v[28:31], v[172:175], v[162:165], v[28:31]
	v_mfma_f32_16x16x32_bf16 v[32:35], v[180:183], v[162:165], v[32:35]
	v_mfma_f32_16x16x32_bf16 v[4:7], v[176:179], v[136:139], v[4:7]
	v_mfma_f32_16x16x32_bf16 v[8:11], v[184:187], v[136:139], v[8:11]
	v_mfma_f32_16x16x32_bf16 v[12:15], v[176:179], v[144:147], v[12:15]
	v_mfma_f32_16x16x32_bf16 v[16:19], v[184:187], v[144:147], v[16:19]
	v_mfma_f32_16x16x32_bf16 v[20:23], v[176:179], v[158:161], v[20:23]
	v_mfma_f32_16x16x32_bf16 v[24:27], v[184:187], v[158:161], v[24:27]
	v_mfma_f32_16x16x32_bf16 v[28:31], v[176:179], v[168:171], v[28:31]
	v_mfma_f32_16x16x32_bf16 v[32:35], v[184:187], v[168:171], v[32:35]
	s_setprio 0
	s_barrier
	ds_read_b128 v[216:219], v212 offset:49152
	ds_read_b128 v[220:223], v213 offset:49152
	ds_read_b128 v[224:227], v212 offset:51200
	ds_read_b128 v[228:231], v213 offset:51200
	v_add_u32_e32 v208, 0x80, v208
	v_add_u32_e32 v209, 0x80, v209
	s_add_i32 m0, s40, 0x18000
	s_nop 0
	global_load_lds_dwordx4 v208, s[76:77]
	global_load_lds_dwordx4 v209, s[78:79] offset:1024
	s_barrier
; #define MFMA32(a, b, c) __builtin_amdgcn_mfma_f32_32x32x16_bf16((a), (b), (c), 0, 0, 0)
; template <bool SWAP, class Epi>
; DI void gemm_tile(const u16* __restrict__ A, int lda, const u16* __restrict__ Bw, int ldb, int K, char* lds, Epi epi) {
;     ...
;   auto compute = [&](int st) {
;     const char* as = lds + st * GEMM_STAGE;
;     const char* bs = as + 36864;
; #pragma unroll
;     for (int ks = 0; ks < 4; ++ks) {
;       bf16x8 af[2], bfr[2];
; #pragma unroll
;       for (int mi = 0; mi < 2; ++mi) af[mi] = *(const bf16x8*)(as + ((wm * 64 + mi * 32 + r) * 72 + ks * 16 + 8 * h) * 2);
; #pragma unroll
;       for (int ni = 0; ni < 2; ++ni) bfr[ni] = *(const bf16x8*)(bs + ((wn * 64 + ni * 32 + r) * 72 + ks * 16 + 8 * h) * 2);
; #pragma unroll
;       for (int mi = 0; mi < 2; ++mi)
; #pragma unroll
;         for (int ni = 0; ni < 2; ++ni) {
;           if (SWAP) acc[mi][ni] = MFMA32(bfr[ni], af[mi], acc[mi][ni]);
;           else acc[mi][ni] = MFMA32(af[mi], bfr[ni], acc[mi][ni]);
;         }
;     }
;   };
;   gload(0, ra0, rb0);
;   lstore(0, ra0, rb0);
;   gload(1, ra1, rb1);
;   __syncthreads();
;   for (int kt = 0; kt < nk; kt += 2) {
;     if (kt + 2 < nk) gload(kt + 2, ra0, rb0);
;     compute(0);
;     lstore(1, ra1, rb1);
;     __syncthreads();
;     if (kt + 3 < nk) gload(kt + 3, ra1, rb1);
;     compute(1);
;     if (kt + 2 < nk) lstore(0, ra0, rb0);
;     __syncthreads();
	s_waitcnt lgkmcnt(0)
	s_setprio 1
	v_mfma_f32_16x16x32_bf16 v[36:39], v[216:219], v[132:135], v[36:39]
	v_mfma_f32_16x16x32_bf16 v[40:43], v[224:227], v[132:135], v[40:43]
	v_mfma_f32_16x16x32_bf16 v[44:47], v[216:219], v[140:143], v[44:47]
	v_mfma_f32_16x16x32_bf16 v[48:51], v[224:227], v[140:143], v[48:51]
	v_mfma_f32_16x16x32_bf16 v[52:55], v[216:219], v[148:151], v[52:55]
	v_mfma_f32_16x16x32_bf16 v[56:59], v[224:227], v[148:151], v[56:59]
	v_mfma_f32_16x16x32_bf16 v[60:63], v[216:219], v[162:165], v[60:63]
	v_mfma_f32_16x16x32_bf16 v[64:67], v[224:227], v[162:165], v[64:67]
	v_mfma_f32_16x16x32_bf16 v[36:39], v[220:223], v[136:139], v[36:39]
	v_mfma_f32_16x16x32_bf16 v[40:43], v[228:231], v[136:139], v[40:43]
	v_mfma_f32_16x16x32_bf16 v[44:47], v[220:223], v[144:147], v[44:47]
	v_mfma_f32_16x16x32_bf16 v[48:51], v[228:231], v[144:147], v[48:51]
	v_mfma_f32_16x16x32_bf16 v[52:55], v[220:223], v[158:161], v[52:55]
	v_mfma_f32_16x16x32_bf16 v[56:59], v[228:231], v[158:161], v[56:59]
	v_mfma_f32_16x16x32_bf16 v[60:63], v[220:223], v[168:171], v[60:63]
	v_mfma_f32_16x16x32_bf16 v[64:67], v[228:231], v[168:171], v[64:67]
	s_setprio 0
	s_barrier
	ds_read_b128 v[132:135], v210 offset:49152
	ds_read_b128 v[136:139], v211 offset:49152
	ds_read_b128 v[140:143], v210 offset:51200
	ds_read_b128 v[144:147], v211 offset:51200
	ds_read_b128 v[148:151], v210 offset:53248
	ds_read_b128 v[158:161], v211 offset:53248
	ds_read_b128 v[162:165], v210 offset:55296
	ds_read_b128 v[168:171], v211 offset:55296
	s_add_i32 m0, s40, 0x8000
	s_nop 0
	global_load_lds_dwordx4 v208, s[68:69]
	global_load_lds_dwordx4 v209, s[70:71] offset:1024
	s_barrier
	s_waitcnt lgkmcnt(0)
	s_setprio 1
	v_mfma_f32_16x16x32_bf16 v[68:71], v[172:175], v[132:135], v[68:71]
	v_mfma_f32_16x16x32_bf16 v[72:75], v[180:183], v[132:135], v[72:75]
	v_mfma_f32_16x16x32_bf16 v[76:79], v[172:175], v[140:143], v[76:79]
	v_mfma_f32_16x16x32_bf16 v[80:83], v[180:183], v[140:143], v[80:83]
	v_mfma_f32_16x16x32_bf16 v[84:87], v[172:175], v[148:151], v[84:87]
	v_mfma_f32_16x16x32_bf16 v[88:91], v[180:183], v[148:151], v[88:91]
	v_mfma_f32_16x16x32_bf16 v[92:95], v[172:175], v[162:165], v[92:95]
	v_mfma_f32_16x16x32_bf16 v[96:99], v[180:183], v[162:165], v[96:99]
	v_mfma_f32_16x16x32_bf16 v[68:71], v[176:179], v[136:139], v[68:71]
	v_mfma_f32_16x16x32_bf16 v[72:75], v[184:187], v[136:139], v[72:75]
	v_mfma_f32_16x16x32_bf16 v[76:79], v[176:179], v[144:147], v[76:79]
	v_mfma_f32_16x16x32_bf16 v[80:83], v[184:187], v[144:147], v[80:83]
	v_mfma_f32_16x16x32_bf16 v[84:87], v[176:179], v[158:161], v[84:87]
	v_mfma_f32_16x16x32_bf16 v[88:91], v[184:187], v[158:161], v[88:91]
	v_mfma_f32_16x16x32_bf16 v[92:95], v[176:179], v[168:171], v[92:95]
	v_mfma_f32_16x16x32_bf16 v[96:99], v[184:187], v[168:171], v[96:99]
	s_setprio 0
	s_barrier
	s_add_i32 m0, s40, 0x1c000
	s_nop 0
	global_load_lds_dwordx4 v208, s[80:81]
	global_load_lds_dwordx4 v209, s[82:83] offset:1024
	s_waitcnt vmcnt(6)
	s_barrier
	s_setprio 1
	v_mfma_f32_16x16x32_bf16 v[100:103], v[216:219], v[132:135], v[100:103]
	v_mfma_f32_16x16x32_bf16 v[104:107], v[224:227], v[132:135], v[104:107]
	v_mfma_f32_16x16x32_bf16 v[108:111], v[216:219], v[140:143], v[108:111]
	v_mfma_f32_16x16x32_bf16 v[112:115], v[224:227], v[140:143], v[112:115]
	v_mfma_f32_16x16x32_bf16 v[116:119], v[216:219], v[148:151], v[116:119]
	v_mfma_f32_16x16x32_bf16 v[120:123], v[224:227], v[148:151], v[120:123]
	v_mfma_f32_16x16x32_bf16 v[124:127], v[216:219], v[162:165], v[124:127]
	v_mfma_f32_16x16x32_bf16 v[128:131], v[224:227], v[162:165], v[128:131]
	v_mfma_f32_16x16x32_bf16 v[100:103], v[220:223], v[136:139], v[100:103]
	v_mfma_f32_16x16x32_bf16 v[104:107], v[228:231], v[136:139], v[104:107]
	v_mfma_f32_16x16x32_bf16 v[108:111], v[220:223], v[144:147], v[108:111]
	v_mfma_f32_16x16x32_bf16 v[112:115], v[228:231], v[144:147], v[112:115]
	v_mfma_f32_16x16x32_bf16 v[116:119], v[220:223], v[158:161], v[116:119]
	v_mfma_f32_16x16x32_bf16 v[120:123], v[228:231], v[158:161], v[120:123]
	v_mfma_f32_16x16x32_bf16 v[124:127], v[220:223], v[168:171], v[124:127]
	v_mfma_f32_16x16x32_bf16 v[128:131], v[228:231], v[168:171], v[128:131]
	s_setprio 0
	s_barrier
	ds_read_b128 v[172:175], v212 offset:0
	ds_read_b128 v[176:179], v213 offset:0
	ds_read_b128 v[180:183], v212 offset:2048
	ds_read_b128 v[184:187], v213 offset:2048
	ds_read_b128 v[132:135], v210 offset:0
	ds_read_b128 v[136:139], v211 offset:0
	ds_read_b128 v[140:143], v210 offset:2048
	ds_read_b128 v[144:147], v211 offset:2048
	ds_read_b128 v[148:151], v210 offset:4096
	ds_read_b128 v[158:161], v211 offset:4096
	ds_read_b128 v[162:165], v210 offset:6144
	ds_read_b128 v[168:171], v211 offset:6144
	s_add_i32 m0, s40, 0xc000
	s_nop 0
	global_load_lds_dwordx4 v208, s[72:73]
	global_load_lds_dwordx4 v209, s[74:75] offset:1024
	s_barrier
	s_waitcnt lgkmcnt(0)
	s_setprio 1
	v_mfma_f32_16x16x32_bf16 v[4:7], v[172:175], v[132:135], v[4:7]
	v_mfma_f32_16x16x32_bf16 v[8:11], v[180:183], v[132:135], v[8:11]
	v_mfma_f32_16x16x32_bf16 v[12:15], v[172:175], v[140:143], v[12:15]
	v_mfma_f32_16x16x32_bf16 v[16:19], v[180:183], v[140:143], v[16:19]
	v_mfma_f32_16x16x32_bf16 v[20:23], v[172:175], v[148:151], v[20:23]
	v_mfma_f32_16x16x32_bf16 v[24:27], v[180:183], v[148:151], v[24:27]
	v_mfma_f32_16x16x32_bf16 v[28:31], v[172:175], v[162:165], v[28:31]
	v_mfma_f32_16x16x32_bf16 v[32:35], v[180:183], v[162:165], v[32:35]
	v_mfma_f32_16x16x32_bf16 v[4:7], v[176:179], v[136:139], v[4:7]
	v_mfma_f32_16x16x32_bf16 v[8:11], v[184:187], v[136:139], v[8:11]
	v_mfma_f32_16x16x32_bf16 v[12:15], v[176:179], v[144:147], v[12:15]
	v_mfma_f32_16x16x32_bf16 v[16:19], v[184:187], v[144:147], v[16:19]
	v_mfma_f32_16x16x32_bf16 v[20:23], v[176:179], v[158:161], v[20:23]
	v_mfma_f32_16x16x32_bf16 v[24:27], v[184:187], v[158:161], v[24:27]
	v_mfma_f32_16x16x32_bf16 v[28:31], v[176:179], v[168:171], v[28:31]
	v_mfma_f32_16x16x32_bf16 v[32:35], v[184:187], v[168:171], v[32:35]
	s_setprio 0
	s_barrier
; template <bool SWAP, class Epi>
; DI void gemm_tile(const u16* __restrict__ A, int lda, const u16* __restrict__ Bw, int ldb, int K, char* lds, Epi epi) {
;     ...
;   for (int kt = 0; kt < nk; kt += 2) {
;     if (kt + 2 < nk) gload(kt + 2, ra0, rb0);
;     compute(0);
;     lstore(1, ra1, rb1);
;     __syncthreads();
;     if (kt + 3 < nk) gload(kt + 3, ra1, rb1);
;     compute(1);
;     if (kt + 2 < nk) lstore(0, ra0, rb0);
;     __syncthreads();
	ds_read_b128 v[216:219], v212 offset:16384
	ds_read_b128 v[220:223], v213 offset:16384
	ds_read_b128 v[224:227], v212 offset:18432
	ds_read_b128 v[228:231], v213 offset:18432
	s_barrier
	s_waitcnt lgkmcnt(0)
	s_setprio 1
	v_mfma_f32_16x16x32_bf16 v[36:39], v[216:219], v[132:135], v[36:39]
	v_mfma_f32_16x16x32_bf16 v[40:43], v[224:227], v[132:135], v[40:43]
	v_mfma_f32_16x16x32_bf16 v[44:47], v[216:219], v[140:143], v[44:47]
	v_mfma_f32_16x16x32_bf16 v[48:51], v[224:227], v[140:143], v[48:51]
	v_mfma_f32_16x16x32_bf16 v[52:55], v[216:219], v[148:151], v[52:55]
	v_mfma_f32_16x16x32_bf16 v[56:59], v[224:227], v[148:151], v[56:59]
	v_mfma_f32_16x16x32_bf16 v[60:63], v[216:219], v[162:165], v[60:63]
	v_mfma_f32_16x16x32_bf16 v[64:67], v[224:227], v[162:165], v[64:67]
	v_mfma_f32_16x16x32_bf16 v[36:39], v[220:223], v[136:139], v[36:39]
	v_mfma_f32_16x16x32_bf16 v[40:43], v[228:231], v[136:139], v[40:43]
	v_mfma_f32_16x16x32_bf16 v[44:47], v[220:223], v[144:147], v[44:47]
	v_mfma_f32_16x16x32_bf16 v[48:51], v[228:231], v[144:147], v[48:51]
	v_mfma_f32_16x16x32_bf16 v[52:55], v[220:223], v[158:161], v[52:55]
	v_mfma_f32_16x16x32_bf16 v[56:59], v[228:231], v[158:161], v[56:59]
	v_mfma_f32_16x16x32_bf16 v[60:63], v[220:223], v[168:171], v[60:63]
	v_mfma_f32_16x16x32_bf16 v[64:67], v[228:231], v[168:171], v[64:67]
	s_setprio 0
	s_barrier
	ds_read_b128 v[132:135], v210 offset:16384
	ds_read_b128 v[136:139], v211 offset:16384
	ds_read_b128 v[140:143], v210 offset:18432
	ds_read_b128 v[144:147], v211 offset:18432
	ds_read_b128 v[148:151], v210 offset:20480
	ds_read_b128 v[158:161], v211 offset:20480
	ds_read_b128 v[162:165], v210 offset:22528
	ds_read_b128 v[168:171], v211 offset:22528
	s_waitcnt vmcnt(4)
	s_barrier
	s_waitcnt lgkmcnt(0)
	s_setprio 1
	v_mfma_f32_16x16x32_bf16 v[68:71], v[172:175], v[132:135], v[68:71]
	v_mfma_f32_16x16x32_bf16 v[72:75], v[180:183], v[132:135], v[72:75]
	v_mfma_f32_16x16x32_bf16 v[76:79], v[172:175], v[140:143], v[76:79]
	v_mfma_f32_16x16x32_bf16 v[80:83], v[180:183], v[140:143], v[80:83]
	v_mfma_f32_16x16x32_bf16 v[84:87], v[172:175], v[148:151], v[84:87]
	v_mfma_f32_16x16x32_bf16 v[88:91], v[180:183], v[148:151], v[88:91]
	v_mfma_f32_16x16x32_bf16 v[92:95], v[172:175], v[162:165], v[92:95]
	v_mfma_f32_16x16x32_bf16 v[96:99], v[180:183], v[162:165], v[96:99]
	v_mfma_f32_16x16x32_bf16 v[68:71], v[176:179], v[136:139], v[68:71]
	v_mfma_f32_16x16x32_bf16 v[72:75], v[184:187], v[136:139], v[72:75]
	v_mfma_f32_16x16x32_bf16 v[76:79], v[176:179], v[144:147], v[76:79]
	v_mfma_f32_16x16x32_bf16 v[80:83], v[184:187], v[144:147], v[80:83]
	v_mfma_f32_16x16x32_bf16 v[84:87], v[176:179], v[158:161], v[84:87]
	v_mfma_f32_16x16x32_bf16 v[88:91], v[184:187], v[158:161], v[88:91]
	v_mfma_f32_16x16x32_bf16 v[92:95], v[176:179], v[168:171], v[92:95]
	v_mfma_f32_16x16x32_bf16 v[96:99], v[184:187], v[168:171], v[96:99]
	s_setprio 0
	s_setprio 1
	v_mfma_f32_16x16x32_bf16 v[100:103], v[216:219], v[132:135], v[100:103]
	v_mfma_f32_16x16x32_bf16 v[104:107], v[224:227], v[132:135], v[104:107]
	v_mfma_f32_16x16x32_bf16 v[108:111], v[216:219], v[140:143], v[108:111]
	v_mfma_f32_16x16x32_bf16 v[112:115], v[224:227], v[140:143], v[112:115]
	v_mfma_f32_16x16x32_bf16 v[116:119], v[216:219], v[148:151], v[116:119]
	v_mfma_f32_16x16x32_bf16 v[120:123], v[224:227], v[148:151], v[120:123]
	v_mfma_f32_16x16x32_bf16 v[124:127], v[216:219], v[162:165], v[124:127]
	v_mfma_f32_16x16x32_bf16 v[128:131], v[224:227], v[162:165], v[128:131]
	v_mfma_f32_16x16x32_bf16 v[100:103], v[220:223], v[136:139], v[100:103]
	v_mfma_f32_16x16x32_bf16 v[104:107], v[228:231], v[136:139], v[104:107]
	v_mfma_f32_16x16x32_bf16 v[108:111], v[220:223], v[144:147], v[108:111]
	v_mfma_f32_16x16x32_bf16 v[112:115], v[228:231], v[144:147], v[112:115]
	v_mfma_f32_16x16x32_bf16 v[116:119], v[220:223], v[158:161], v[116:119]
	v_mfma_f32_16x16x32_bf16 v[120:123], v[228:231], v[158:161], v[120:123]
	v_mfma_f32_16x16x32_bf16 v[124:127], v[220:223], v[168:171], v[124:127]
	v_mfma_f32_16x16x32_bf16 v[128:131], v[228:231], v[168:171], v[128:131]
	s_setprio 0
	s_barrier
	ds_read_b128 v[172:175], v212 offset:32768
	ds_read_b128 v[176:179], v213 offset:32768
	ds_read_b128 v[180:183], v212 offset:34816
	ds_read_b128 v[184:187], v213 offset:34816
	ds_read_b128 v[132:135], v210 offset:32768
	ds_read_b128 v[136:139], v211 offset:32768
	ds_read_b128 v[140:143], v210 offset:34816
	ds_read_b128 v[144:147], v211 offset:34816
	ds_read_b128 v[148:151], v210 offset:36864
	ds_read_b128 v[158:161], v211 offset:36864
	ds_read_b128 v[162:165], v210 offset:38912
	ds_read_b128 v[168:171], v211 offset:38912
	s_waitcnt vmcnt(2)
	s_barrier
	s_waitcnt lgkmcnt(0)
	s_setprio 1
	v_mfma_f32_16x16x32_bf16 v[4:7], v[172:175], v[132:135], v[4:7]
	v_mfma_f32_16x16x32_bf16 v[8:11], v[180:183], v[132:135], v[8:11]
	v_mfma_f32_16x16x32_bf16 v[12:15], v[172:175], v[140:143], v[12:15]
	v_mfma_f32_16x16x32_bf16 v[16:19], v[180:183], v[140:143], v[16:19]
	v_mfma_f32_16x16x32_bf16 v[20:23], v[172:175], v[148:151], v[20:23]
	v_mfma_f32_16x16x32_bf16 v[24:27], v[180:183], v[148:151], v[24:27]
	v_mfma_f32_16x16x32_bf16 v[28:31], v[172:175], v[162:165], v[28:31]
	v_mfma_f32_16x16x32_bf16 v[32:35], v[180:183], v[162:165], v[32:35]
	v_mfma_f32_16x16x32_bf16 v[4:7], v[176:179], v[136:139], v[4:7]
	v_mfma_f32_16x16x32_bf16 v[8:11], v[184:187], v[136:139], v[8:11]
	v_mfma_f32_16x16x32_bf16 v[12:15], v[176:179], v[144:147], v[12:15]
	v_mfma_f32_16x16x32_bf16 v[16:19], v[184:187], v[144:147], v[16:19]
	v_mfma_f32_16x16x32_bf16 v[20:23], v[176:179], v[158:161], v[20:23]
	v_mfma_f32_16x16x32_bf16 v[24:27], v[184:187], v[158:161], v[24:27]
	v_mfma_f32_16x16x32_bf16 v[28:31], v[176:179], v[168:171], v[28:31]
	v_mfma_f32_16x16x32_bf16 v[32:35], v[184:187], v[168:171], v[32:35]
	s_setprio 0
	s_barrier
; template <bool SWAP, class Epi>
; DI void gemm_tile(const u16* __restrict__ A, int lda, const u16* __restrict__ Bw, int ldb, int K, char* lds, Epi epi) {
;     ...
;   for (int kt = 0; kt < nk; kt += 2) {
;     if (kt + 2 < nk) gload(kt + 2, ra0, rb0);
;     compute(0);
;     lstore(1, ra1, rb1);
;     __syncthreads();
;     if (kt + 3 < nk) gload(kt + 3, ra1, rb1);
;     compute(1);
;     if (kt + 2 < nk) lstore(0, ra0, rb0);
;     __syncthreads();
;   }
; #pragma unroll
;   for (int mi = 0; mi < 2; ++mi)
; #pragma unroll
;     for (int ni = 0; ni < 2; ++ni) epi(mi, ni, acc[mi][ni]);
; }
	ds_read_b128 v[216:219], v212 offset:49152
	ds_read_b128 v[220:223], v213 offset:49152
	ds_read_b128 v[224:227], v212 offset:51200
	ds_read_b128 v[228:231], v213 offset:51200
	s_waitcnt vmcnt(0)
	s_barrier
	s_waitcnt lgkmcnt(0)
	s_setprio 1
	v_mfma_f32_16x16x32_bf16 v[36:39], v[216:219], v[132:135], v[36:39]
	v_mfma_f32_16x16x32_bf16 v[40:43], v[224:227], v[132:135], v[40:43]
	v_mfma_f32_16x16x32_bf16 v[44:47], v[216:219], v[140:143], v[44:47]
	v_mfma_f32_16x16x32_bf16 v[48:51], v[224:227], v[140:143], v[48:51]
	v_mfma_f32_16x16x32_bf16 v[52:55], v[216:219], v[148:151], v[52:55]
	v_mfma_f32_16x16x32_bf16 v[56:59], v[224:227], v[148:151], v[56:59]
	v_mfma_f32_16x16x32_bf16 v[60:63], v[216:219], v[162:165], v[60:63]
	v_mfma_f32_16x16x32_bf16 v[64:67], v[224:227], v[162:165], v[64:67]
	v_mfma_f32_16x16x32_bf16 v[36:39], v[220:223], v[136:139], v[36:39]
	v_mfma_f32_16x16x32_bf16 v[40:43], v[228:231], v[136:139], v[40:43]
	v_mfma_f32_16x16x32_bf16 v[44:47], v[220:223], v[144:147], v[44:47]
	v_mfma_f32_16x16x32_bf16 v[48:51], v[228:231], v[144:147], v[48:51]
	v_mfma_f32_16x16x32_bf16 v[52:55], v[220:223], v[158:161], v[52:55]
	v_mfma_f32_16x16x32_bf16 v[56:59], v[228:231], v[158:161], v[56:59]
	v_mfma_f32_16x16x32_bf16 v[60:63], v[220:223], v[168:171], v[60:63]
	v_mfma_f32_16x16x32_bf16 v[64:67], v[228:231], v[168:171], v[64:67]
	s_setprio 0
	s_barrier
	ds_read_b128 v[132:135], v210 offset:49152
	ds_read_b128 v[136:139], v211 offset:49152
	ds_read_b128 v[140:143], v210 offset:51200
	ds_read_b128 v[144:147], v211 offset:51200
	ds_read_b128 v[148:151], v210 offset:53248
	ds_read_b128 v[158:161], v211 offset:53248
	ds_read_b128 v[162:165], v210 offset:55296
	ds_read_b128 v[168:171], v211 offset:55296
	s_barrier
	s_waitcnt lgkmcnt(0)
	s_setprio 1
	v_mfma_f32_16x16x32_bf16 v[68:71], v[172:175], v[132:135], v[68:71]
	v_mfma_f32_16x16x32_bf16 v[72:75], v[180:183], v[132:135], v[72:75]
	v_mfma_f32_16x16x32_bf16 v[76:79], v[172:175], v[140:143], v[76:79]
	v_mfma_f32_16x16x32_bf16 v[80:83], v[180:183], v[140:143], v[80:83]
	v_mfma_f32_16x16x32_bf16 v[84:87], v[172:175], v[148:151], v[84:87]
	v_mfma_f32_16x16x32_bf16 v[88:91], v[180:183], v[148:151], v[88:91]
	v_mfma_f32_16x16x32_bf16 v[92:95], v[172:175], v[162:165], v[92:95]
	v_mfma_f32_16x16x32_bf16 v[96:99], v[180:183], v[162:165], v[96:99]
	v_mfma_f32_16x16x32_bf16 v[68:71], v[176:179], v[136:139], v[68:71]
	v_mfma_f32_16x16x32_bf16 v[72:75], v[184:187], v[136:139], v[72:75]
	v_mfma_f32_16x16x32_bf16 v[76:79], v[176:179], v[144:147], v[76:79]
	v_mfma_f32_16x16x32_bf16 v[80:83], v[184:187], v[144:147], v[80:83]
	v_mfma_f32_16x16x32_bf16 v[84:87], v[176:179], v[158:161], v[84:87]
	v_mfma_f32_16x16x32_bf16 v[88:91], v[184:187], v[158:161], v[88:91]
	v_mfma_f32_16x16x32_bf16 v[92:95], v[176:179], v[168:171], v[92:95]
	v_mfma_f32_16x16x32_bf16 v[96:99], v[184:187], v[168:171], v[96:99]
	s_setprio 0
	s_setprio 1
	v_mfma_f32_16x16x32_bf16 v[100:103], v[216:219], v[132:135], v[100:103]
	v_mfma_f32_16x16x32_bf16 v[104:107], v[224:227], v[132:135], v[104:107]
	v_mfma_f32_16x16x32_bf16 v[108:111], v[216:219], v[140:143], v[108:111]
	v_mfma_f32_16x16x32_bf16 v[112:115], v[224:227], v[140:143], v[112:115]
	v_mfma_f32_16x16x32_bf16 v[116:119], v[216:219], v[148:151], v[116:119]
	v_mfma_f32_16x16x32_bf16 v[120:123], v[224:227], v[148:151], v[120:123]
	v_mfma_f32_16x16x32_bf16 v[124:127], v[216:219], v[162:165], v[124:127]
	v_mfma_f32_16x16x32_bf16 v[128:131], v[224:227], v[162:165], v[128:131]
	v_mfma_f32_16x16x32_bf16 v[100:103], v[220:223], v[136:139], v[100:103]
	v_mfma_f32_16x16x32_bf16 v[104:107], v[228:231], v[136:139], v[104:107]
	v_mfma_f32_16x16x32_bf16 v[108:111], v[220:223], v[144:147], v[108:111]
	v_mfma_f32_16x16x32_bf16 v[112:115], v[228:231], v[144:147], v[112:115]
	v_mfma_f32_16x16x32_bf16 v[116:119], v[220:223], v[158:161], v[116:119]
	v_mfma_f32_16x16x32_bf16 v[120:123], v[228:231], v[158:161], v[120:123]
	v_mfma_f32_16x16x32_bf16 v[124:127], v[220:223], v[168:171], v[124:127]
	v_mfma_f32_16x16x32_bf16 v[128:131], v[228:231], v[168:171], v[128:131]
	s_setprio 0
	s_barrier
	s_cmp_lt_u32 s3, 4
	s_cbranch_scc0 .Lpp_g1b
	s_barrier
; DI unsigned pk2(float a, float b) { f32x2 v = {a, b}; return __builtin_bit_cast(unsigned, __builtin_convertvector(v, bf2_t)); }
; DI void store_rowmajor(u16* dst, const f32x16& a, int h, float sc) {
; #pragma unroll
;   for (int kp = 0; kp < 2; ++kp) {
;     const int g = 2 * kp;
;     unsigned ax = pk2(a[4 * g] * sc, a[4 * g + 1] * sc), ay = pk2(a[4 * g + 2] * sc, a[4 * g + 3] * sc);
;     unsigned bx = pk2(a[4 * g + 4] * sc, a[4 * g + 5] * sc), by = pk2(a[4 * g + 6] * sc, a[4 * g + 7] * sc);
;     const u32x2 rx = __builtin_amdgcn_permlane32_swap(ax, bx, false, false);
;     const u32x2 ry = __builtin_amdgcn_permlane32_swap(ay, by, false, false);
;     const u32x4 v = {rx[0], ry[0], rx[1], ry[1]};
;     *(u32x4*)(dst + 8 * (g + h)) = v;
;   }
; }
; DI void inproj_tile(const Params& p, int l, int mt, int nt, char* lds) {
;     ...
;     gemm_tile<true>(A, DM, Bw, DM, DM, lds, [&](int mi, int ni, const f32x16& a) {
;       const int tok = m0 + wm * 64 + mi * 32 + r;
;       store_rowmajor(p.H + (size_t)tok * LDH + nt * 128 + wn * 64 + ni * 32, a, h, 1.f);
.Lpp_g1b:
	s_nop 7
	s_nop 7
	v_cvt_pk_bf16_f32 v132, v4, v5
	v_cvt_pk_bf16_f32 v133, v6, v7
	s_nop 0
	global_store_dwordx2 v214, v[132:133], s[8:9]
	v_cvt_pk_bf16_f32 v134, v8, v9
	v_cvt_pk_bf16_f32 v135, v10, v11
	s_nop 0
	global_store_dwordx2 v214, v[134:135], s[8:9] offset:32
	v_cvt_pk_bf16_f32 v136, v36, v37
	v_cvt_pk_bf16_f32 v137, v38, v39
	s_nop 0
	global_store_dwordx2 v214, v[136:137], s[8:9] offset:256
	v_cvt_pk_bf16_f32 v138, v40, v41
	v_cvt_pk_bf16_f32 v139, v42, v43
	s_nop 0
	global_store_dwordx2 v214, v[138:139], s[8:9] offset:288
	v_add_u32_e32 v215, 0x2a000, v214
	v_cvt_pk_bf16_f32 v132, v12, v13
	v_cvt_pk_bf16_f32 v133, v14, v15
	s_nop 0
	global_store_dwordx2 v215, v[132:133], s[8:9]
	v_cvt_pk_bf16_f32 v134, v16, v17
	v_cvt_pk_bf16_f32 v135, v18, v19
	s_nop 0
	global_store_dwordx2 v215, v[134:135], s[8:9] offset:32
	v_cvt_pk_bf16_f32 v136, v44, v45
	v_cvt_pk_bf16_f32 v137, v46, v47
	s_nop 0
	global_store_dwordx2 v215, v[136:137], s[8:9] offset:256
	v_cvt_pk_bf16_f32 v138, v48, v49
	v_cvt_pk_bf16_f32 v139, v50, v51
	s_nop 0
	global_store_dwordx2 v215, v[138:139], s[8:9] offset:288
	v_add_u32_e32 v215, 0x54000, v214
	v_cvt_pk_bf16_f32 v132, v20, v21
	v_cvt_pk_bf16_f32 v133, v22, v23
	s_nop 0
	global_store_dwordx2 v215, v[132:133], s[8:9]
	v_cvt_pk_bf16_f32 v134, v24, v25
	v_cvt_pk_bf16_f32 v135, v26, v27
	s_nop 0
	global_store_dwordx2 v215, v[134:135], s[8:9] offset:32
	v_cvt_pk_bf16_f32 v136, v52, v53
	v_cvt_pk_bf16_f32 v137, v54, v55
	s_nop 0
	global_store_dwordx2 v215, v[136:137], s[8:9] offset:256
	v_cvt_pk_bf16_f32 v138, v56, v57
	v_cvt_pk_bf16_f32 v139, v58, v59
	s_nop 0
	global_store_dwordx2 v215, v[138:139], s[8:9] offset:288
	v_add_u32_e32 v215, 0x7e000, v214
	v_cvt_pk_bf16_f32 v132, v28, v29
	v_cvt_pk_bf16_f32 v133, v30, v31
	s_nop 0
	global_store_dwordx2 v215, v[132:133], s[8:9]
	v_cvt_pk_bf16_f32 v134, v32, v33
	v_cvt_pk_bf16_f32 v135, v34, v35
	s_nop 0
	global_store_dwordx2 v215, v[134:135], s[8:9] offset:32
	v_cvt_pk_bf16_f32 v136, v60, v61
	v_cvt_pk_bf16_f32 v137, v62, v63
	s_nop 0
	global_store_dwordx2 v215, v[136:137], s[8:9] offset:256
	v_cvt_pk_bf16_f32 v138, v64, v65
	v_cvt_pk_bf16_f32 v139, v66, v67
	s_nop 0
	global_store_dwordx2 v215, v[138:139], s[8:9] offset:288
	v_add_u32_e32 v215, 0x150000, v214
	v_cvt_pk_bf16_f32 v132, v68, v69
	v_cvt_pk_bf16_f32 v133, v70, v71
	s_nop 0
	global_store_dwordx2 v215, v[132:133], s[8:9]
	v_cvt_pk_bf16_f32 v134, v72, v73
	v_cvt_pk_bf16_f32 v135, v74, v75
	s_nop 0
	global_store_dwordx2 v215, v[134:135], s[8:9] offset:32
	v_cvt_pk_bf16_f32 v136, v100, v101
	v_cvt_pk_bf16_f32 v137, v102, v103
	s_nop 0
	global_store_dwordx2 v215, v[136:137], s[8:9] offset:256
	v_cvt_pk_bf16_f32 v138, v104, v105
	v_cvt_pk_bf16_f32 v139, v106, v107
	s_nop 0
	global_store_dwordx2 v215, v[138:139], s[8:9] offset:288
	v_add_u32_e32 v215, 0x17a000, v214
	v_cvt_pk_bf16_f32 v132, v76, v77
	v_cvt_pk_bf16_f32 v133, v78, v79
	s_nop 0
	global_store_dwordx2 v215, v[132:133], s[8:9]
	v_cvt_pk_bf16_f32 v134, v80, v81
	v_cvt_pk_bf16_f32 v135, v82, v83
	s_nop 0
	global_store_dwordx2 v215, v[134:135], s[8:9] offset:32
	v_cvt_pk_bf16_f32 v136, v108, v109
	v_cvt_pk_bf16_f32 v137, v110, v111
	s_nop 0
	global_store_dwordx2 v215, v[136:137], s[8:9] offset:256
	v_cvt_pk_bf16_f32 v138, v112, v113
	v_cvt_pk_bf16_f32 v139, v114, v115
	s_nop 0
	global_store_dwordx2 v215, v[138:139], s[8:9] offset:288
	v_add_u32_e32 v215, 0x1a4000, v214
	v_cvt_pk_bf16_f32 v132, v84, v85
	v_cvt_pk_bf16_f32 v133, v86, v87
	s_nop 0
	global_store_dwordx2 v215, v[132:133], s[8:9]
	v_cvt_pk_bf16_f32 v134, v88, v89
	v_cvt_pk_bf16_f32 v135, v90, v91
	s_nop 0
	global_store_dwordx2 v215, v[134:135], s[8:9] offset:32
	v_cvt_pk_bf16_f32 v136, v116, v117
	v_cvt_pk_bf16_f32 v137, v118, v119
	s_nop 0
	global_store_dwordx2 v215, v[136:137], s[8:9] offset:256
	v_cvt_pk_bf16_f32 v138, v120, v121
	v_cvt_pk_bf16_f32 v139, v122, v123
	s_nop 0
	global_store_dwordx2 v215, v[138:139], s[8:9] offset:288
	v_add_u32_e32 v215, 0x1ce000, v214
	v_cvt_pk_bf16_f32 v132, v92, v93
	v_cvt_pk_bf16_f32 v133, v94, v95
	s_nop 0
	global_store_dwordx2 v215, v[132:133], s[8:9]
	v_cvt_pk_bf16_f32 v134, v96, v97
	v_cvt_pk_bf16_f32 v135, v98, v99
	s_nop 0
	global_store_dwordx2 v215, v[134:135], s[8:9] offset:32
	v_cvt_pk_bf16_f32 v136, v124, v125
	v_cvt_pk_bf16_f32 v137, v126, v127
	s_nop 0
	global_store_dwordx2 v215, v[136:137], s[8:9] offset:256
	v_cvt_pk_bf16_f32 v138, v128, v129
	v_cvt_pk_bf16_f32 v139, v130, v131
	s_nop 0
	global_store_dwordx2 v215, v[138:139], s[8:9] offset:288
	s_branch .LBB0_323
